# GEMM loops: priority flips reversed (load/ds_read segments at prio 1, MFMA segments at prio 0), on top of header-drain removal
# speedup vs baseline: 1.0055x; 1.0035x over previous
; #define PG8_STAGE(bufoff, gbase, voff) do { _Pragma("unroll") for (int _i = 0; _i < 2; ++_i) \
;         __builtin_amdgcn_global_load_lds((const unsigned*)((const char*)(gbase) + (voff)[_i]), (PG8_LAS unsigned*)(lds + (bufoff) + ldsw + _i * 8192), 16, 0, 0); } while (0)
; #define PG8_LDA(dst, b, h) do { _Pragma("unroll") for (int m = 0; m < 4; ++m) _Pragma("unroll") for (int k = 0; k < 2; ++k) dst[m][k] = *(const PG8_LAS bf16x8*)(lds + PG8_SA(b, h) + aoff + m * 2048 + k * 1024); } while (0)
; #define PG8_LDB(dst, b, h) do { _Pragma("unroll") for (int n = 0; n < 2; ++n) _Pragma("unroll") for (int k = 0; k < 2; ++k) dst[n][k] = *(const PG8_LAS bf16x8*)(lds + PG8_SB(b, h) + boff + n * 2048 + k * 1024); } while (0)
; #define PG8_MMA(ai, bj, At, Bt) do { __builtin_amdgcn_s_setprio(1); _Pragma("unroll") for (int m = 0; m < 4; ++m) _Pragma("unroll") for (int n = 0; n < 2; ++n) _Pragma("unroll") for (int k = 0; k < 2; ++k) \
;         acc[ai][bj][m][n] = __builtin_amdgcn_mfma_f32_16x16x32_bf16(Bt[n][k], At[m][k], acc[ai][bj][m][n], 0, 0, 0); __builtin_amdgcn_s_setprio(0); } while (0)
; #define PG8_WAIT_V(n) asm volatile("s_waitcnt vmcnt(" #n ")" ::: "memory")
; template <class Epi, class Sched, bool ALIGN_EPI = false, bool SP2 = false>
; __device__ __forceinline__ void gemm_phase(PG8_LAS unsigned char* lds, const Gemm g, const Sched& S, const Epi& E) {
;     ...
;             PG8_LDB(B0, 0, 0); PG8_LDB(B1, 0, 1); PG8_SCHED; PG8_LDA(At, 0, 0); PG8_STAGE(PG8_SA(1, 1), a1 + hstep, voffA);
;             PG8_WAIT_V(8); PG8_WAIT_L(0); PG8_BAR; PG8_MMA(0, 0, At, B0); PG8_MMA(0, 1, At, B1); PG8_BAR; PG8_SCHED;
;             PG8_LDA(At, 0, 1); PG8_STAGE(PG8_SB(0, 0), b2, voffB); PG8_STAGE(PG8_SB(0, 1), b2 + hstep, voffB); PG8_STAGE(PG8_SA(0, 0), a2, voffA);
;             PG8_WAIT_V(8); PG8_WAIT_L(0); PG8_BAR; PG8_MMA(1, 0, At, B0); PG8_MMA(1, 1, At, B1); PG8_BAR; PG8_SCHED;
;             PG8_LDB(B0, 1, 0); PG8_LDB(B1, 1, 1); PG8_SCHED; PG8_LDA(At, 1, 0); PG8_STAGE(PG8_SA(0, 1), a2 + hstep, voffA);
;             PG8_WAIT_V(8); PG8_WAIT_L(0); PG8_BAR; PG8_MMA(0, 0, At, B0); PG8_MMA(0, 1, At, B1); PG8_BAR; PG8_SCHED;
;             PG8_LDA(At, 1, 1); PG8_STAGE(PG8_SB(1, 0), b3, voffB); PG8_STAGE(PG8_SB(1, 1), b3 + hstep, voffB); PG8_STAGE(PG8_SA(1, 0), a3, voffA);
;             PG8_WAIT_V(8); PG8_WAIT_L(0); PG8_BAR; PG8_MMA(1, 0, At, B0); PG8_MMA(1, 1, At, B1); PG8_BAR; PG8_SCHED;
.LBB0_427:
	ds_read_b128 v[152:155], v162
	ds_read_b128 v[156:159], v162 offset:1024
	ds_read_b128 v[166:169], v162 offset:2048
	ds_read_b128 v[170:173], v162 offset:3072
	ds_read_b128 v[174:177], v163
	ds_read_b128 v[178:181], v163 offset:1024
	ds_read_b128 v[182:185], v163 offset:2048
	ds_read_b128 v[186:189], v163 offset:3072
	s_add_u32 s28, s8, 0xfffc0080
	s_addc_u32 s29, s9, -1
	s_cmp_eq_u32 s39, 12
	s_cselect_b32 s37, s5, s29
	s_cselect_b32 s36, s7, s28
	s_cselect_b32 s29, s12, s38
	s_cselect_b32 s28, s21, s23
	v_lshl_add_u64 v[160:161], s[8:9], 0, v[140:141]
	s_add_i32 m0, s63, 0xc000
	ds_read_b128 v[190:193], v164
	ds_read_b128 v[194:197], v164 offset:1024
	ds_read_b128 v[198:201], v164 offset:2048
	ds_read_b128 v[202:205], v164 offset:3072
	ds_read_b128 v[206:209], v164 offset:4096
	ds_read_b128 v[210:213], v164 offset:5120
	ds_read_b128 v[214:217], v164 offset:6144
	ds_read_b128 v[218:221], v164 offset:7168
	global_load_lds_dwordx4 v[160:161], off
	v_lshl_add_u64 v[160:161], s[8:9], 0, v[142:143]
	s_add_i32 m0, s63, 0xe000
	s_nop 0
	global_load_lds_dwordx4 v[160:161], off
	s_waitcnt vmcnt(8)
	s_waitcnt lgkmcnt(0)
	s_barrier
	s_setprio 0
	s_waitcnt lgkmcnt(0)
	v_mfma_f32_16x16x32_bf16 v[124:127], v[152:155], v[190:193], v[124:127]
	v_mfma_f32_16x16x32_bf16 v[120:123], v[166:169], v[190:193], v[120:123]
	v_mfma_f32_16x16x32_bf16 v[108:111], v[152:155], v[198:201], v[108:111]
	v_mfma_f32_16x16x32_bf16 v[104:107], v[166:169], v[198:201], v[104:107]
	v_mfma_f32_16x16x32_bf16 v[92:95], v[152:155], v[206:209], v[92:95]
	v_mfma_f32_16x16x32_bf16 v[88:91], v[166:169], v[206:209], v[88:91]
	v_mfma_f32_16x16x32_bf16 v[76:79], v[152:155], v[214:217], v[76:79]
	v_mfma_f32_16x16x32_bf16 v[72:75], v[166:169], v[214:217], v[72:75]
	v_mfma_f32_16x16x32_bf16 v[124:127], v[156:159], v[194:197], v[124:127]
	v_mfma_f32_16x16x32_bf16 v[120:123], v[170:173], v[194:197], v[120:123]
	v_mfma_f32_16x16x32_bf16 v[108:111], v[156:159], v[202:205], v[108:111]
	v_mfma_f32_16x16x32_bf16 v[104:107], v[170:173], v[202:205], v[104:107]
	v_mfma_f32_16x16x32_bf16 v[92:95], v[156:159], v[210:213], v[92:95]
	v_mfma_f32_16x16x32_bf16 v[88:91], v[170:173], v[210:213], v[88:91]
	v_mfma_f32_16x16x32_bf16 v[76:79], v[156:159], v[218:221], v[76:79]
	v_mfma_f32_16x16x32_bf16 v[72:75], v[170:173], v[218:221], v[72:75]
	s_setprio 1
	s_setprio 0
	v_mfma_f32_16x16x32_bf16 v[116:119], v[174:177], v[190:193], v[116:119]
	v_mfma_f32_16x16x32_bf16 v[112:115], v[182:185], v[190:193], v[112:115]
	v_mfma_f32_16x16x32_bf16 v[100:103], v[174:177], v[198:201], v[100:103]
	v_mfma_f32_16x16x32_bf16 v[96:99], v[182:185], v[198:201], v[96:99]
	v_mfma_f32_16x16x32_bf16 v[84:87], v[174:177], v[206:209], v[84:87]
	v_mfma_f32_16x16x32_bf16 v[80:83], v[182:185], v[206:209], v[80:83]
	v_mfma_f32_16x16x32_bf16 v[68:71], v[174:177], v[214:217], v[68:71]
	v_mfma_f32_16x16x32_bf16 v[64:67], v[182:185], v[214:217], v[64:67]
	v_mfma_f32_16x16x32_bf16 v[116:119], v[178:181], v[194:197], v[116:119]
	v_mfma_f32_16x16x32_bf16 v[112:115], v[186:189], v[194:197], v[112:115]
	v_mfma_f32_16x16x32_bf16 v[100:103], v[178:181], v[202:205], v[100:103]
	v_mfma_f32_16x16x32_bf16 v[96:99], v[186:189], v[202:205], v[96:99]
	v_mfma_f32_16x16x32_bf16 v[84:87], v[178:181], v[210:213], v[84:87]
	v_mfma_f32_16x16x32_bf16 v[80:83], v[186:189], v[210:213], v[80:83]
	v_mfma_f32_16x16x32_bf16 v[68:71], v[178:181], v[218:221], v[68:71]
	v_mfma_f32_16x16x32_bf16 v[64:67], v[186:189], v[218:221], v[64:67]
	s_setprio 1
	s_barrier
	s_add_i32 s42, s79, s62
	v_lshl_add_u64 v[160:161], s[28:29], 0, v[130:131]
	s_mov_b32 m0, s42
	ds_read_b128 v[190:193], v164 offset:16384
	ds_read_b128 v[194:197], v164 offset:17408
	ds_read_b128 v[198:201], v164 offset:18432
	ds_read_b128 v[202:205], v164 offset:19456
	ds_read_b128 v[206:209], v164 offset:20480
	ds_read_b128 v[210:213], v164 offset:21504
	ds_read_b128 v[214:217], v164 offset:22528
	ds_read_b128 v[218:221], v164 offset:23552
	global_load_lds_dwordx4 v[160:161], off
	s_add_i32 m0, s42, 0x2000
	s_add_u32 s42, s28, 0x40000
	v_lshl_add_u64 v[222:223], s[28:29], 0, v[134:135]
	s_addc_u32 s43, s29, 0
	s_add_i32 s44, s84, s62
	global_load_lds_dwordx4 v[222:223], off
	v_lshl_add_u64 v[224:225], s[42:43], 0, v[130:131]
	s_mov_b32 m0, s44
	v_lshl_add_u64 v[226:227], s[36:37], 0, v[132:133]
	global_load_lds_dwordx4 v[224:225], off
	v_lshl_add_u64 v[224:225], s[42:43], 0, v[134:135]
	s_add_i32 m0, s44, 0x2000
	s_nop 0
	global_load_lds_dwordx4 v[224:225], off
	v_lshl_add_u64 v[224:225], s[36:37], 0, v[128:129]
	s_mov_b32 m0, s63
	s_nop 0
	global_load_lds_dwordx4 v[224:225], off
	s_mov_b32 m0, s68
	s_nop 0
	global_load_lds_dwordx4 v[226:227], off
	s_waitcnt vmcnt(8)
	s_waitcnt lgkmcnt(0)
	s_barrier
; #define PG8_STAGE(bufoff, gbase, voff) do { _Pragma("unroll") for (int _i = 0; _i < 2; ++_i) \
;         __builtin_amdgcn_global_load_lds((const unsigned*)((const char*)(gbase) + (voff)[_i]), (PG8_LAS unsigned*)(lds + (bufoff) + ldsw + _i * 8192), 16, 0, 0); } while (0)
; #define PG8_LDA(dst, b, h) do { _Pragma("unroll") for (int m = 0; m < 4; ++m) _Pragma("unroll") for (int k = 0; k < 2; ++k) dst[m][k] = *(const PG8_LAS bf16x8*)(lds + PG8_SA(b, h) + aoff + m * 2048 + k * 1024); } while (0)
; #define PG8_LDB(dst, b, h) do { _Pragma("unroll") for (int n = 0; n < 2; ++n) _Pragma("unroll") for (int k = 0; k < 2; ++k) dst[n][k] = *(const PG8_LAS bf16x8*)(lds + PG8_SB(b, h) + boff + n * 2048 + k * 1024); } while (0)
; #define PG8_MMA(ai, bj, At, Bt) do { __builtin_amdgcn_s_setprio(1); _Pragma("unroll") for (int m = 0; m < 4; ++m) _Pragma("unroll") for (int n = 0; n < 2; ++n) _Pragma("unroll") for (int k = 0; k < 2; ++k) \
;         acc[ai][bj][m][n] = __builtin_amdgcn_mfma_f32_16x16x32_bf16(Bt[n][k], At[m][k], acc[ai][bj][m][n], 0, 0, 0); __builtin_amdgcn_s_setprio(0); } while (0)
; #define PG8_WAIT_V(n) asm volatile("s_waitcnt vmcnt(" #n ")" ::: "memory")
; template <class Epi, class Sched, bool ALIGN_EPI = false, bool SP2 = false>
; __device__ __forceinline__ void gemm_phase(PG8_LAS unsigned char* lds, const Gemm g, const Sched& S, const Epi& E) {
;     ...
;             PG8_LDB(B0, 0, 0); PG8_LDB(B1, 0, 1); PG8_SCHED; PG8_LDA(At, 0, 0); PG8_STAGE(PG8_SA(1, 1), a1 + hstep, voffA);
;             PG8_WAIT_V(8); PG8_WAIT_L(0); PG8_BAR; PG8_MMA(0, 0, At, B0); PG8_MMA(0, 1, At, B1); PG8_BAR; PG8_SCHED;
;             PG8_LDA(At, 0, 1); PG8_STAGE(PG8_SB(0, 0), b2, voffB); PG8_STAGE(PG8_SB(0, 1), b2 + hstep, voffB); PG8_STAGE(PG8_SA(0, 0), a2, voffA);
;             PG8_WAIT_V(8); PG8_WAIT_L(0); PG8_BAR; PG8_MMA(1, 0, At, B0); PG8_MMA(1, 1, At, B1); PG8_BAR; PG8_SCHED;
;             PG8_LDB(B0, 1, 0); PG8_LDB(B1, 1, 1); PG8_SCHED; PG8_LDA(At, 1, 0); PG8_STAGE(PG8_SA(0, 1), a2 + hstep, voffA);
;             PG8_WAIT_V(8); PG8_WAIT_L(0); PG8_BAR; PG8_MMA(0, 0, At, B0); PG8_MMA(0, 1, At, B1); PG8_BAR; PG8_SCHED;
;             PG8_LDA(At, 1, 1); PG8_STAGE(PG8_SB(1, 0), b3, voffB); PG8_STAGE(PG8_SB(1, 1), b3 + hstep, voffB); PG8_STAGE(PG8_SA(1, 0), a3, voffA);
;             PG8_WAIT_V(8); PG8_WAIT_L(0); PG8_BAR; PG8_MMA(1, 0, At, B0); PG8_MMA(1, 1, At, B1); PG8_BAR; PG8_SCHED;
	s_setprio 0
	s_waitcnt lgkmcnt(0)
	v_mfma_f32_16x16x32_bf16 v[60:63], v[152:155], v[190:193], v[60:63]
	v_mfma_f32_16x16x32_bf16 v[56:59], v[166:169], v[190:193], v[56:59]
	v_mfma_f32_16x16x32_bf16 v[44:47], v[152:155], v[198:201], v[44:47]
	v_mfma_f32_16x16x32_bf16 v[40:43], v[166:169], v[198:201], v[40:43]
	v_mfma_f32_16x16x32_bf16 v[28:31], v[152:155], v[206:209], v[28:31]
	v_mfma_f32_16x16x32_bf16 v[24:27], v[166:169], v[206:209], v[24:27]
	v_mfma_f32_16x16x32_bf16 v[12:15], v[152:155], v[214:217], v[12:15]
	v_mfma_f32_16x16x32_bf16 v[8:11], v[166:169], v[214:217], v[8:11]
	v_mfma_f32_16x16x32_bf16 v[60:63], v[156:159], v[194:197], v[60:63]
	v_mfma_f32_16x16x32_bf16 v[56:59], v[170:173], v[194:197], v[56:59]
	v_mfma_f32_16x16x32_bf16 v[44:47], v[156:159], v[202:205], v[44:47]
	v_mfma_f32_16x16x32_bf16 v[40:43], v[170:173], v[202:205], v[40:43]
	v_mfma_f32_16x16x32_bf16 v[28:31], v[156:159], v[210:213], v[28:31]
	v_mfma_f32_16x16x32_bf16 v[24:27], v[170:173], v[210:213], v[24:27]
	v_mfma_f32_16x16x32_bf16 v[12:15], v[156:159], v[218:221], v[12:15]
	v_mfma_f32_16x16x32_bf16 v[8:11], v[170:173], v[218:221], v[8:11]
	s_setprio 1
	s_setprio 0
	v_mfma_f32_16x16x32_bf16 v[52:55], v[174:177], v[190:193], v[52:55]
	v_mfma_f32_16x16x32_bf16 v[48:51], v[182:185], v[190:193], v[48:51]
	v_mfma_f32_16x16x32_bf16 v[36:39], v[174:177], v[198:201], v[36:39]
	v_mfma_f32_16x16x32_bf16 v[32:35], v[182:185], v[198:201], v[32:35]
	v_mfma_f32_16x16x32_bf16 v[20:23], v[174:177], v[206:209], v[20:23]
	v_mfma_f32_16x16x32_bf16 v[16:19], v[182:185], v[206:209], v[16:19]
	v_mfma_f32_16x16x32_bf16 v[4:7], v[174:177], v[214:217], v[4:7]
	v_mfma_f32_16x16x32_bf16 v[0:3], v[182:185], v[214:217], v[0:3]
	v_mfma_f32_16x16x32_bf16 v[52:55], v[178:181], v[194:197], v[52:55]
	v_mfma_f32_16x16x32_bf16 v[48:51], v[186:189], v[194:197], v[48:51]
	v_mfma_f32_16x16x32_bf16 v[36:39], v[178:181], v[202:205], v[36:39]
	v_mfma_f32_16x16x32_bf16 v[32:35], v[186:189], v[202:205], v[32:35]
	v_mfma_f32_16x16x32_bf16 v[20:23], v[178:181], v[210:213], v[20:23]
	v_mfma_f32_16x16x32_bf16 v[16:19], v[186:189], v[210:213], v[16:19]
	v_mfma_f32_16x16x32_bf16 v[4:7], v[178:181], v[218:221], v[4:7]
	v_mfma_f32_16x16x32_bf16 v[0:3], v[186:189], v[218:221], v[0:3]
	s_setprio 1
	s_barrier
	s_add_i32 s42, 0, 0x18000
	v_add_u32_e32 v136, s42, v149
	s_add_i32 s43, 0, 0x1c000
	ds_read_b128 v[152:155], v136
	ds_read_b128 v[156:159], v136 offset:1024
	ds_read_b128 v[166:169], v136 offset:2048
	ds_read_b128 v[170:173], v136 offset:3072
	v_add_u32_e32 v136, s43, v149
	ds_read_b128 v[174:177], v136
	ds_read_b128 v[178:181], v136 offset:1024
	ds_read_b128 v[182:185], v136 offset:2048
	ds_read_b128 v[186:189], v136 offset:3072
	s_add_u32 s36, s36, 0x40000
	s_addc_u32 s37, s37, 0
	s_mov_b32 m0, s50
	v_lshl_add_u64 v[228:229], s[36:37], 0, v[128:129]
	ds_read_b128 v[190:193], v164 offset:32768
	ds_read_b128 v[194:197], v164 offset:33792
	ds_read_b128 v[198:201], v164 offset:34816
	ds_read_b128 v[202:205], v164 offset:35840
	ds_read_b128 v[206:209], v164 offset:36864
	ds_read_b128 v[210:213], v164 offset:37888
	ds_read_b128 v[214:217], v164 offset:38912
	ds_read_b128 v[218:221], v164 offset:39936
	global_load_lds_dwordx4 v[228:229], off
	v_lshl_add_u64 v[228:229], s[36:37], 0, v[132:133]
	s_mov_b32 m0, s51
	s_nop 0
	global_load_lds_dwordx4 v[228:229], off
	s_waitcnt vmcnt(8)
	s_waitcnt lgkmcnt(0)
	s_barrier
	s_setprio 0
	s_waitcnt lgkmcnt(0)
	v_mfma_f32_16x16x32_bf16 v[124:127], v[152:155], v[190:193], v[124:127]
	v_mfma_f32_16x16x32_bf16 v[120:123], v[166:169], v[190:193], v[120:123]
	v_mfma_f32_16x16x32_bf16 v[108:111], v[152:155], v[198:201], v[108:111]
	v_mfma_f32_16x16x32_bf16 v[104:107], v[166:169], v[198:201], v[104:107]
	v_mfma_f32_16x16x32_bf16 v[92:95], v[152:155], v[206:209], v[92:95]
	v_mfma_f32_16x16x32_bf16 v[88:91], v[166:169], v[206:209], v[88:91]
	v_mfma_f32_16x16x32_bf16 v[76:79], v[152:155], v[214:217], v[76:79]
	v_mfma_f32_16x16x32_bf16 v[72:75], v[166:169], v[214:217], v[72:75]
	v_mfma_f32_16x16x32_bf16 v[124:127], v[156:159], v[194:197], v[124:127]
	v_mfma_f32_16x16x32_bf16 v[120:123], v[170:173], v[194:197], v[120:123]
	v_mfma_f32_16x16x32_bf16 v[108:111], v[156:159], v[202:205], v[108:111]
	v_mfma_f32_16x16x32_bf16 v[104:107], v[170:173], v[202:205], v[104:107]
	v_mfma_f32_16x16x32_bf16 v[92:95], v[156:159], v[210:213], v[92:95]
	v_mfma_f32_16x16x32_bf16 v[88:91], v[170:173], v[210:213], v[88:91]
	v_mfma_f32_16x16x32_bf16 v[76:79], v[156:159], v[218:221], v[76:79]
	v_mfma_f32_16x16x32_bf16 v[72:75], v[170:173], v[218:221], v[72:75]
	s_setprio 1
	s_setprio 0
	v_mfma_f32_16x16x32_bf16 v[116:119], v[174:177], v[190:193], v[116:119]
	v_mfma_f32_16x16x32_bf16 v[112:115], v[182:185], v[190:193], v[112:115]
	v_mfma_f32_16x16x32_bf16 v[100:103], v[174:177], v[198:201], v[100:103]
	v_mfma_f32_16x16x32_bf16 v[96:99], v[182:185], v[198:201], v[96:99]
	v_mfma_f32_16x16x32_bf16 v[84:87], v[174:177], v[206:209], v[84:87]
	v_mfma_f32_16x16x32_bf16 v[80:83], v[182:185], v[206:209], v[80:83]
	v_mfma_f32_16x16x32_bf16 v[68:71], v[174:177], v[214:217], v[68:71]
	v_mfma_f32_16x16x32_bf16 v[64:67], v[182:185], v[214:217], v[64:67]
	v_mfma_f32_16x16x32_bf16 v[116:119], v[178:181], v[194:197], v[116:119]
	v_mfma_f32_16x16x32_bf16 v[112:115], v[186:189], v[194:197], v[112:115]
	v_mfma_f32_16x16x32_bf16 v[100:103], v[178:181], v[202:205], v[100:103]
	v_mfma_f32_16x16x32_bf16 v[96:99], v[186:189], v[202:205], v[96:99]
	v_mfma_f32_16x16x32_bf16 v[84:87], v[178:181], v[210:213], v[84:87]
	v_mfma_f32_16x16x32_bf16 v[80:83], v[186:189], v[210:213], v[80:83]
	v_mfma_f32_16x16x32_bf16 v[68:71], v[178:181], v[218:221], v[68:71]
	v_mfma_f32_16x16x32_bf16 v[64:67], v[186:189], v[218:221], v[64:67]
	s_setprio 1
	s_barrier
; #define PG8_STAGE(bufoff, gbase, voff) do { _Pragma("unroll") for (int _i = 0; _i < 2; ++_i) \
;         __builtin_amdgcn_global_load_lds((const unsigned*)((const char*)(gbase) + (voff)[_i]), (PG8_LAS unsigned*)(lds + (bufoff) + ldsw + _i * 8192), 16, 0, 0); } while (0)
; #define PG8_LDA(dst, b, h) do { _Pragma("unroll") for (int m = 0; m < 4; ++m) _Pragma("unroll") for (int k = 0; k < 2; ++k) dst[m][k] = *(const PG8_LAS bf16x8*)(lds + PG8_SA(b, h) + aoff + m * 2048 + k * 1024); } while (0)
; #define PG8_LDB(dst, b, h) do { _Pragma("unroll") for (int n = 0; n < 2; ++n) _Pragma("unroll") for (int k = 0; k < 2; ++k) dst[n][k] = *(const PG8_LAS bf16x8*)(lds + PG8_SB(b, h) + boff + n * 2048 + k * 1024); } while (0)
; #define PG8_MMA(ai, bj, At, Bt) do { __builtin_amdgcn_s_setprio(1); _Pragma("unroll") for (int m = 0; m < 4; ++m) _Pragma("unroll") for (int n = 0; n < 2; ++n) _Pragma("unroll") for (int k = 0; k < 2; ++k) \
;         acc[ai][bj][m][n] = __builtin_amdgcn_mfma_f32_16x16x32_bf16(Bt[n][k], At[m][k], acc[ai][bj][m][n], 0, 0, 0); __builtin_amdgcn_s_setprio(0); } while (0)
; #define PG8_WAIT_V(n) asm volatile("s_waitcnt vmcnt(" #n ")" ::: "memory")
; template <class Epi, class Sched, bool ALIGN_EPI = false, bool SP2 = false>
; __device__ __forceinline__ void gemm_phase(PG8_LAS unsigned char* lds, const Gemm g, const Sched& S, const Epi& E) {
;     ...
;             PG8_LDB(B0, 0, 0); PG8_LDB(B1, 0, 1); PG8_SCHED; PG8_LDA(At, 0, 0); PG8_STAGE(PG8_SA(1, 1), a1 + hstep, voffA);
;             PG8_WAIT_V(8); PG8_WAIT_L(0); PG8_BAR; PG8_MMA(0, 0, At, B0); PG8_MMA(0, 1, At, B1); PG8_BAR; PG8_SCHED;
;             PG8_LDA(At, 0, 1); PG8_STAGE(PG8_SB(0, 0), b2, voffB); PG8_STAGE(PG8_SB(0, 1), b2 + hstep, voffB); PG8_STAGE(PG8_SA(0, 0), a2, voffA);
;             PG8_WAIT_V(8); PG8_WAIT_L(0); PG8_BAR; PG8_MMA(1, 0, At, B0); PG8_MMA(1, 1, At, B1); PG8_BAR; PG8_SCHED;
;             PG8_LDB(B0, 1, 0); PG8_LDB(B1, 1, 1); PG8_SCHED; PG8_LDA(At, 1, 0); PG8_STAGE(PG8_SA(0, 1), a2 + hstep, voffA);
;             PG8_WAIT_V(8); PG8_WAIT_L(0); PG8_BAR; PG8_MMA(0, 0, At, B0); PG8_MMA(0, 1, At, B1); PG8_BAR; PG8_SCHED;
;             PG8_LDA(At, 1, 1); PG8_STAGE(PG8_SB(1, 0), b3, voffB); PG8_STAGE(PG8_SB(1, 1), b3 + hstep, voffB); PG8_STAGE(PG8_SA(1, 0), a3, voffA);
;             PG8_WAIT_V(8); PG8_WAIT_L(0); PG8_BAR; PG8_MMA(1, 0, At, B0); PG8_MMA(1, 1, At, B1); PG8_BAR; PG8_SCHED;
	s_add_i32 s36, s42, s62
	v_lshl_add_u64 v[160:161], v[160:161], 0, s[16:17]
	s_mov_b32 m0, s36
	ds_read_b128 v[190:193], v164 offset:49152
	ds_read_b128 v[194:197], v164 offset:50176
	ds_read_b128 v[198:201], v164 offset:51200
	ds_read_b128 v[202:205], v164 offset:52224
	ds_read_b128 v[206:209], v164 offset:53248
	ds_read_b128 v[210:213], v164 offset:54272
	ds_read_b128 v[214:217], v164 offset:55296
	ds_read_b128 v[218:221], v164 offset:56320
	global_load_lds_dwordx4 v[160:161], off
	s_add_i32 m0, s36, 0x2000
	s_add_u32 s28, s28, 0x40080
	v_lshl_add_u64 v[160:161], v[222:223], 0, s[16:17]
	s_addc_u32 s29, s29, 0
	s_add_i32 s36, s43, s62
	global_load_lds_dwordx4 v[160:161], off
	v_lshl_add_u64 v[160:161], s[28:29], 0, v[130:131]
	s_mov_b32 m0, s36
	s_nop 0
	global_load_lds_dwordx4 v[160:161], off
	v_lshl_add_u64 v[160:161], s[28:29], 0, v[134:135]
	s_add_i32 m0, s36, 0x2000
	s_nop 0
	global_load_lds_dwordx4 v[160:161], off
	v_lshl_add_u64 v[160:161], v[224:225], 0, s[16:17]
	s_mov_b32 m0, s69
	s_nop 0
	global_load_lds_dwordx4 v[160:161], off
	v_lshl_add_u64 v[160:161], v[226:227], 0, s[16:17]
	s_mov_b32 m0, s70
	s_nop 0
	global_load_lds_dwordx4 v[160:161], off
	s_waitcnt vmcnt(8)
	s_waitcnt lgkmcnt(0)
	s_barrier
	s_setprio 0
	s_waitcnt lgkmcnt(0)
	v_mfma_f32_16x16x32_bf16 v[60:63], v[152:155], v[190:193], v[60:63]
	v_mfma_f32_16x16x32_bf16 v[56:59], v[166:169], v[190:193], v[56:59]
	v_mfma_f32_16x16x32_bf16 v[44:47], v[152:155], v[198:201], v[44:47]
	v_mfma_f32_16x16x32_bf16 v[40:43], v[166:169], v[198:201], v[40:43]
	v_mfma_f32_16x16x32_bf16 v[28:31], v[152:155], v[206:209], v[28:31]
	v_mfma_f32_16x16x32_bf16 v[24:27], v[166:169], v[206:209], v[24:27]
	v_mfma_f32_16x16x32_bf16 v[12:15], v[152:155], v[214:217], v[12:15]
	v_mfma_f32_16x16x32_bf16 v[8:11], v[166:169], v[214:217], v[8:11]
	v_mfma_f32_16x16x32_bf16 v[60:63], v[156:159], v[194:197], v[60:63]
	v_mfma_f32_16x16x32_bf16 v[56:59], v[170:173], v[194:197], v[56:59]
	v_mfma_f32_16x16x32_bf16 v[44:47], v[156:159], v[202:205], v[44:47]
	v_mfma_f32_16x16x32_bf16 v[40:43], v[170:173], v[202:205], v[40:43]
	v_mfma_f32_16x16x32_bf16 v[28:31], v[156:159], v[210:213], v[28:31]
	v_mfma_f32_16x16x32_bf16 v[24:27], v[170:173], v[210:213], v[24:27]
	v_mfma_f32_16x16x32_bf16 v[12:15], v[156:159], v[218:221], v[12:15]
	v_mfma_f32_16x16x32_bf16 v[8:11], v[170:173], v[218:221], v[8:11]
	s_setprio 1
	s_setprio 0
	v_mfma_f32_16x16x32_bf16 v[52:55], v[174:177], v[190:193], v[52:55]
	v_mfma_f32_16x16x32_bf16 v[48:51], v[182:185], v[190:193], v[48:51]
	v_mfma_f32_16x16x32_bf16 v[36:39], v[174:177], v[198:201], v[36:39]
	v_mfma_f32_16x16x32_bf16 v[32:35], v[182:185], v[198:201], v[32:35]
	v_mfma_f32_16x16x32_bf16 v[20:23], v[174:177], v[206:209], v[20:23]
	v_mfma_f32_16x16x32_bf16 v[16:19], v[182:185], v[206:209], v[16:19]
	v_mfma_f32_16x16x32_bf16 v[4:7], v[174:177], v[214:217], v[4:7]
	v_mfma_f32_16x16x32_bf16 v[0:3], v[182:185], v[214:217], v[0:3]
	v_mfma_f32_16x16x32_bf16 v[52:55], v[178:181], v[194:197], v[52:55]
	v_mfma_f32_16x16x32_bf16 v[48:51], v[186:189], v[194:197], v[48:51]
	v_mfma_f32_16x16x32_bf16 v[36:39], v[178:181], v[202:205], v[36:39]
	v_mfma_f32_16x16x32_bf16 v[32:35], v[186:189], v[202:205], v[32:35]
	v_mfma_f32_16x16x32_bf16 v[20:23], v[178:181], v[210:213], v[20:23]
	v_mfma_f32_16x16x32_bf16 v[16:19], v[186:189], v[210:213], v[16:19]
	v_mfma_f32_16x16x32_bf16 v[4:7], v[178:181], v[218:221], v[4:7]
	v_mfma_f32_16x16x32_bf16 v[0:3], v[186:189], v[218:221], v[0:3]
	s_setprio 1
	s_barrier
	s_add_i32 s39, s39, 2
	s_add_u32 s8, s8, 0x100
	s_addc_u32 s9, s9, 0
	s_add_u32 s23, s23, 0x100
	s_addc_u32 s38, s38, 0
	s_cmp_gt_u32 s39, 13
	s_cbranch_scc0 .LBB0_427
	s_and_b64 vcc, exec, s[18:19]
	s_cbranch_vccz .LBB0_430
	s_barrier

; #define PG8_STAGE(bufoff, gbase, voff) do { _Pragma("unroll") for (int _i = 0; _i < 2; ++_i) \
;         __builtin_amdgcn_global_load_lds((const unsigned*)((const char*)(gbase) + (voff)[_i]), (PG8_LAS unsigned*)(lds + (bufoff) + ldsw + _i * 8192), 16, 0, 0); } while (0)
; #define PG8_LDA(dst, b, h) do { _Pragma("unroll") for (int m = 0; m < 4; ++m) _Pragma("unroll") for (int k = 0; k < 2; ++k) dst[m][k] = *(const PG8_LAS bf16x8*)(lds + PG8_SA(b, h) + aoff + m * 2048 + k * 1024); } while (0)
; #define PG8_LDB(dst, b, h) do { _Pragma("unroll") for (int n = 0; n < 2; ++n) _Pragma("unroll") for (int k = 0; k < 2; ++k) dst[n][k] = *(const PG8_LAS bf16x8*)(lds + PG8_SB(b, h) + boff + n * 2048 + k * 1024); } while (0)
; #define PG8_MMA(ai, bj, At, Bt) do { __builtin_amdgcn_s_setprio(1); _Pragma("unroll") for (int m = 0; m < 4; ++m) _Pragma("unroll") for (int n = 0; n < 2; ++n) _Pragma("unroll") for (int k = 0; k < 2; ++k) \
;         acc[ai][bj][m][n] = __builtin_amdgcn_mfma_f32_16x16x32_bf16(Bt[n][k], At[m][k], acc[ai][bj][m][n], 0, 0, 0); __builtin_amdgcn_s_setprio(0); } while (0)
; #define PG8_WAIT_V(n) asm volatile("s_waitcnt vmcnt(" #n ")" ::: "memory")
; template <class Epi, class Sched, bool ALIGN_EPI = false, bool SP2 = false>
; __device__ __forceinline__ void gemm_phase(PG8_LAS unsigned char* lds, const Gemm g, const Sched& S, const Epi& E) {
;     ...
;             PG8_LDB(B0, 0, 0); PG8_LDB(B1, 0, 1); PG8_SCHED; PG8_LDA(At, 0, 0); PG8_STAGE(PG8_SA(1, 1), a1 + hstep, voffA);
;             PG8_WAIT_V(8); PG8_WAIT_L(0); PG8_BAR; PG8_MMA(0, 0, At, B0); PG8_MMA(0, 1, At, B1); PG8_BAR; PG8_SCHED;
;             PG8_LDA(At, 0, 1); PG8_STAGE(PG8_SB(0, 0), b2, voffB); PG8_STAGE(PG8_SB(0, 1), b2 + hstep, voffB); PG8_STAGE(PG8_SA(0, 0), a2, voffA);
;             PG8_WAIT_V(8); PG8_WAIT_L(0); PG8_BAR; PG8_MMA(1, 0, At, B0); PG8_MMA(1, 1, At, B1); PG8_BAR; PG8_SCHED;
;             PG8_LDB(B0, 1, 0); PG8_LDB(B1, 1, 1); PG8_SCHED; PG8_LDA(At, 1, 0); PG8_STAGE(PG8_SA(0, 1), a2 + hstep, voffA);
;             PG8_WAIT_V(8); PG8_WAIT_L(0); PG8_BAR; PG8_MMA(0, 0, At, B0); PG8_MMA(0, 1, At, B1); PG8_BAR; PG8_SCHED;
;             PG8_LDA(At, 1, 1); PG8_STAGE(PG8_SB(1, 0), b3, voffB); PG8_STAGE(PG8_SB(1, 1), b3 + hstep, voffB); PG8_STAGE(PG8_SA(1, 0), a3, voffA);
;             PG8_WAIT_V(8); PG8_WAIT_L(0); PG8_BAR; PG8_MMA(1, 0, At, B0); PG8_MMA(1, 1, At, B1); PG8_BAR; PG8_SCHED;
.LBB0_1247:
	ds_read_b128 v[144:147], v163
	ds_read_b128 v[174:177], v163 offset:1024
	ds_read_b128 v[178:181], v163 offset:2048
	ds_read_b128 v[182:185], v163 offset:3072
	ds_read_b128 v[186:189], v170
	ds_read_b128 v[190:193], v170 offset:1024
	ds_read_b128 v[194:197], v170 offset:2048
	ds_read_b128 v[198:201], v170 offset:3072
	s_add_u32 s6, s4, 0xfffc0080
	s_addc_u32 s7, s5, -1
	s_cmp_eq_u32 s56, 12
	s_cselect_b32 s9, s10, s7
	s_cselect_b32 s8, s11, s6
	s_cselect_b32 s7, s27, s53
	s_cselect_b32 s6, s29, s52
	v_lshl_add_u64 v[154:155], s[4:5], 0, v[136:137]
	s_add_i32 m0, s40, 0xc000
	ds_read_b128 v[202:205], v171
	ds_read_b128 v[206:209], v171 offset:1024
	ds_read_b128 v[210:213], v171 offset:2048
	ds_read_b128 v[214:217], v171 offset:3072
	ds_read_b128 v[218:221], v171 offset:4096
	ds_read_b128 v[222:225], v171 offset:5120
	ds_read_b128 v[226:229], v171 offset:6144
	ds_read_b128 v[230:233], v171 offset:7168
	global_load_lds_dwordx4 v[154:155], off
	v_lshl_add_u64 v[154:155], s[4:5], 0, v[138:139]
	s_add_i32 m0, s40, 0xe000
	s_nop 0
	global_load_lds_dwordx4 v[154:155], off
	s_waitcnt vmcnt(8)
	s_waitcnt lgkmcnt(0)
	s_barrier
	s_setprio 0
	s_waitcnt lgkmcnt(0)
	v_mfma_f32_16x16x32_bf16 v[124:127], v[144:147], v[202:205], v[124:127]
	v_mfma_f32_16x16x32_bf16 v[120:123], v[178:181], v[202:205], v[120:123]
	v_mfma_f32_16x16x32_bf16 v[108:111], v[144:147], v[210:213], v[108:111]
	v_mfma_f32_16x16x32_bf16 v[104:107], v[178:181], v[210:213], v[104:107]
	v_mfma_f32_16x16x32_bf16 v[92:95], v[144:147], v[218:221], v[92:95]
	v_mfma_f32_16x16x32_bf16 v[88:91], v[178:181], v[218:221], v[88:91]
	v_mfma_f32_16x16x32_bf16 v[76:79], v[144:147], v[226:229], v[76:79]
	v_mfma_f32_16x16x32_bf16 v[72:75], v[178:181], v[226:229], v[72:75]
	v_mfma_f32_16x16x32_bf16 v[124:127], v[174:177], v[206:209], v[124:127]
	v_mfma_f32_16x16x32_bf16 v[120:123], v[182:185], v[206:209], v[120:123]
	v_mfma_f32_16x16x32_bf16 v[108:111], v[174:177], v[214:217], v[108:111]
	v_mfma_f32_16x16x32_bf16 v[104:107], v[182:185], v[214:217], v[104:107]
	v_mfma_f32_16x16x32_bf16 v[92:95], v[174:177], v[222:225], v[92:95]
	v_mfma_f32_16x16x32_bf16 v[88:91], v[182:185], v[222:225], v[88:91]
	v_mfma_f32_16x16x32_bf16 v[76:79], v[174:177], v[230:233], v[76:79]
	v_mfma_f32_16x16x32_bf16 v[72:75], v[182:185], v[230:233], v[72:75]
	s_setprio 1
	s_setprio 0
	v_mfma_f32_16x16x32_bf16 v[116:119], v[186:189], v[202:205], v[116:119]
	v_mfma_f32_16x16x32_bf16 v[112:115], v[194:197], v[202:205], v[112:115]
	v_mfma_f32_16x16x32_bf16 v[100:103], v[186:189], v[210:213], v[100:103]
	v_mfma_f32_16x16x32_bf16 v[96:99], v[194:197], v[210:213], v[96:99]
	v_mfma_f32_16x16x32_bf16 v[84:87], v[186:189], v[218:221], v[84:87]
	v_mfma_f32_16x16x32_bf16 v[80:83], v[194:197], v[218:221], v[80:83]
	v_mfma_f32_16x16x32_bf16 v[68:71], v[186:189], v[226:229], v[68:71]
	v_mfma_f32_16x16x32_bf16 v[64:67], v[194:197], v[226:229], v[64:67]
	v_mfma_f32_16x16x32_bf16 v[116:119], v[190:193], v[206:209], v[116:119]
	v_mfma_f32_16x16x32_bf16 v[112:115], v[198:201], v[206:209], v[112:115]
	v_mfma_f32_16x16x32_bf16 v[100:103], v[190:193], v[214:217], v[100:103]
	v_mfma_f32_16x16x32_bf16 v[96:99], v[198:201], v[214:217], v[96:99]
	v_mfma_f32_16x16x32_bf16 v[84:87], v[190:193], v[222:225], v[84:87]
	v_mfma_f32_16x16x32_bf16 v[80:83], v[198:201], v[222:225], v[80:83]
	v_mfma_f32_16x16x32_bf16 v[68:71], v[190:193], v[230:233], v[68:71]
	v_mfma_f32_16x16x32_bf16 v[64:67], v[198:201], v[230:233], v[64:67]
	s_setprio 1
	s_barrier
	s_add_i32 s57, s60, s39
	v_lshl_add_u64 v[154:155], s[6:7], 0, v[130:131]
	s_mov_b32 m0, s57
	ds_read_b128 v[202:205], v171 offset:16384
	ds_read_b128 v[206:209], v171 offset:17408
	ds_read_b128 v[210:213], v171 offset:18432
	ds_read_b128 v[214:217], v171 offset:19456
	ds_read_b128 v[218:221], v171 offset:20480
	ds_read_b128 v[222:225], v171 offset:21504
	ds_read_b128 v[226:229], v171 offset:22528
	ds_read_b128 v[230:233], v171 offset:23552
	global_load_lds_dwordx4 v[154:155], off
	s_add_i32 m0, s57, 0x2000
	s_add_u32 s70, s6, 0x40000
	v_lshl_add_u64 v[234:235], s[6:7], 0, v[134:135]
	s_addc_u32 s71, s7, 0
	s_add_i32 s57, s61, s39
	global_load_lds_dwordx4 v[234:235], off
	v_lshl_add_u64 v[236:237], s[70:71], 0, v[130:131]
	s_mov_b32 m0, s57
	v_lshl_add_u64 v[238:239], s[8:9], 0, v[132:133]
	global_load_lds_dwordx4 v[236:237], off
	v_lshl_add_u64 v[236:237], s[70:71], 0, v[134:135]
	s_add_i32 m0, s57, 0x2000
	s_nop 0
	global_load_lds_dwordx4 v[236:237], off
	v_lshl_add_u64 v[236:237], s[8:9], 0, v[128:129]
	s_mov_b32 m0, s40
	s_nop 0
	global_load_lds_dwordx4 v[236:237], off
	s_mov_b32 m0, s41
	s_nop 0
	global_load_lds_dwordx4 v[238:239], off
	s_waitcnt vmcnt(8)
	s_waitcnt lgkmcnt(0)
	s_barrier
; #define PG8_STAGE(bufoff, gbase, voff) do { _Pragma("unroll") for (int _i = 0; _i < 2; ++_i) \
;         __builtin_amdgcn_global_load_lds((const unsigned*)((const char*)(gbase) + (voff)[_i]), (PG8_LAS unsigned*)(lds + (bufoff) + ldsw + _i * 8192), 16, 0, 0); } while (0)
; #define PG8_LDA(dst, b, h) do { _Pragma("unroll") for (int m = 0; m < 4; ++m) _Pragma("unroll") for (int k = 0; k < 2; ++k) dst[m][k] = *(const PG8_LAS bf16x8*)(lds + PG8_SA(b, h) + aoff + m * 2048 + k * 1024); } while (0)
; #define PG8_LDB(dst, b, h) do { _Pragma("unroll") for (int n = 0; n < 2; ++n) _Pragma("unroll") for (int k = 0; k < 2; ++k) dst[n][k] = *(const PG8_LAS bf16x8*)(lds + PG8_SB(b, h) + boff + n * 2048 + k * 1024); } while (0)
; #define PG8_MMA(ai, bj, At, Bt) do { __builtin_amdgcn_s_setprio(1); _Pragma("unroll") for (int m = 0; m < 4; ++m) _Pragma("unroll") for (int n = 0; n < 2; ++n) _Pragma("unroll") for (int k = 0; k < 2; ++k) \
;         acc[ai][bj][m][n] = __builtin_amdgcn_mfma_f32_16x16x32_bf16(Bt[n][k], At[m][k], acc[ai][bj][m][n], 0, 0, 0); __builtin_amdgcn_s_setprio(0); } while (0)
; #define PG8_WAIT_V(n) asm volatile("s_waitcnt vmcnt(" #n ")" ::: "memory")
; template <class Epi, class Sched, bool ALIGN_EPI = false, bool SP2 = false>
; __device__ __forceinline__ void gemm_phase(PG8_LAS unsigned char* lds, const Gemm g, const Sched& S, const Epi& E) {
;     ...
;             PG8_LDB(B0, 0, 0); PG8_LDB(B1, 0, 1); PG8_SCHED; PG8_LDA(At, 0, 0); PG8_STAGE(PG8_SA(1, 1), a1 + hstep, voffA);
;             PG8_WAIT_V(8); PG8_WAIT_L(0); PG8_BAR; PG8_MMA(0, 0, At, B0); PG8_MMA(0, 1, At, B1); PG8_BAR; PG8_SCHED;
;             PG8_LDA(At, 0, 1); PG8_STAGE(PG8_SB(0, 0), b2, voffB); PG8_STAGE(PG8_SB(0, 1), b2 + hstep, voffB); PG8_STAGE(PG8_SA(0, 0), a2, voffA);
;             PG8_WAIT_V(8); PG8_WAIT_L(0); PG8_BAR; PG8_MMA(1, 0, At, B0); PG8_MMA(1, 1, At, B1); PG8_BAR; PG8_SCHED;
;             PG8_LDB(B0, 1, 0); PG8_LDB(B1, 1, 1); PG8_SCHED; PG8_LDA(At, 1, 0); PG8_STAGE(PG8_SA(0, 1), a2 + hstep, voffA);
;             PG8_WAIT_V(8); PG8_WAIT_L(0); PG8_BAR; PG8_MMA(0, 0, At, B0); PG8_MMA(0, 1, At, B1); PG8_BAR; PG8_SCHED;
;             PG8_LDA(At, 1, 1); PG8_STAGE(PG8_SB(1, 0), b3, voffB); PG8_STAGE(PG8_SB(1, 1), b3 + hstep, voffB); PG8_STAGE(PG8_SA(1, 0), a3, voffA);
;             PG8_WAIT_V(8); PG8_WAIT_L(0); PG8_BAR; PG8_MMA(1, 0, At, B0); PG8_MMA(1, 1, At, B1); PG8_BAR; PG8_SCHED;
	s_setprio 0
	s_waitcnt lgkmcnt(0)
	v_mfma_f32_16x16x32_bf16 v[60:63], v[144:147], v[202:205], v[60:63]
	v_mfma_f32_16x16x32_bf16 v[56:59], v[178:181], v[202:205], v[56:59]
	v_mfma_f32_16x16x32_bf16 v[44:47], v[144:147], v[210:213], v[44:47]
	v_mfma_f32_16x16x32_bf16 v[40:43], v[178:181], v[210:213], v[40:43]
	v_mfma_f32_16x16x32_bf16 v[28:31], v[144:147], v[218:221], v[28:31]
	v_mfma_f32_16x16x32_bf16 v[24:27], v[178:181], v[218:221], v[24:27]
	v_mfma_f32_16x16x32_bf16 v[12:15], v[144:147], v[226:229], v[12:15]
	v_mfma_f32_16x16x32_bf16 v[8:11], v[178:181], v[226:229], v[8:11]
	v_mfma_f32_16x16x32_bf16 v[60:63], v[174:177], v[206:209], v[60:63]
	v_mfma_f32_16x16x32_bf16 v[56:59], v[182:185], v[206:209], v[56:59]
	v_mfma_f32_16x16x32_bf16 v[44:47], v[174:177], v[214:217], v[44:47]
	v_mfma_f32_16x16x32_bf16 v[40:43], v[182:185], v[214:217], v[40:43]
	v_mfma_f32_16x16x32_bf16 v[28:31], v[174:177], v[222:225], v[28:31]
	v_mfma_f32_16x16x32_bf16 v[24:27], v[182:185], v[222:225], v[24:27]
	v_mfma_f32_16x16x32_bf16 v[12:15], v[174:177], v[230:233], v[12:15]
	v_mfma_f32_16x16x32_bf16 v[8:11], v[182:185], v[230:233], v[8:11]
	s_setprio 1
	s_setprio 0
	v_mfma_f32_16x16x32_bf16 v[52:55], v[186:189], v[202:205], v[52:55]
	v_mfma_f32_16x16x32_bf16 v[48:51], v[194:197], v[202:205], v[48:51]
	v_mfma_f32_16x16x32_bf16 v[36:39], v[186:189], v[210:213], v[36:39]
	v_mfma_f32_16x16x32_bf16 v[32:35], v[194:197], v[210:213], v[32:35]
	v_mfma_f32_16x16x32_bf16 v[20:23], v[186:189], v[218:221], v[20:23]
	v_mfma_f32_16x16x32_bf16 v[16:19], v[194:197], v[218:221], v[16:19]
	v_mfma_f32_16x16x32_bf16 v[4:7], v[186:189], v[226:229], v[4:7]
	v_mfma_f32_16x16x32_bf16 v[0:3], v[194:197], v[226:229], v[0:3]
	v_mfma_f32_16x16x32_bf16 v[52:55], v[190:193], v[206:209], v[52:55]
	v_mfma_f32_16x16x32_bf16 v[48:51], v[198:201], v[206:209], v[48:51]
	v_mfma_f32_16x16x32_bf16 v[36:39], v[190:193], v[214:217], v[36:39]
	v_mfma_f32_16x16x32_bf16 v[32:35], v[198:201], v[214:217], v[32:35]
	v_mfma_f32_16x16x32_bf16 v[20:23], v[190:193], v[222:225], v[20:23]
	v_mfma_f32_16x16x32_bf16 v[16:19], v[198:201], v[222:225], v[16:19]
	v_mfma_f32_16x16x32_bf16 v[4:7], v[190:193], v[230:233], v[4:7]
	v_mfma_f32_16x16x32_bf16 v[0:3], v[198:201], v[230:233], v[0:3]
	s_setprio 1
	s_barrier
	s_add_i32 s57, 0, 0x18000
	v_add_u32_e32 v152, s57, v161
	s_add_i32 s69, 0, 0x1c000
	ds_read_b128 v[144:147], v152
	ds_read_b128 v[174:177], v152 offset:1024
	ds_read_b128 v[178:181], v152 offset:2048
	ds_read_b128 v[182:185], v152 offset:3072
	v_add_u32_e32 v152, s69, v161
	ds_read_b128 v[186:189], v152
	ds_read_b128 v[190:193], v152 offset:1024
	ds_read_b128 v[194:197], v152 offset:2048
	ds_read_b128 v[198:201], v152 offset:3072
	s_add_u32 s8, s8, 0x40000
	s_addc_u32 s9, s9, 0
	s_mov_b32 m0, s42
	v_lshl_add_u64 v[240:241], s[8:9], 0, v[128:129]
	ds_read_b128 v[202:205], v171 offset:32768
	ds_read_b128 v[206:209], v171 offset:33792
	ds_read_b128 v[210:213], v171 offset:34816
	ds_read_b128 v[214:217], v171 offset:35840
	ds_read_b128 v[218:221], v171 offset:36864
	ds_read_b128 v[222:225], v171 offset:37888
	ds_read_b128 v[226:229], v171 offset:38912
	ds_read_b128 v[230:233], v171 offset:39936
	global_load_lds_dwordx4 v[240:241], off
	v_lshl_add_u64 v[240:241], s[8:9], 0, v[132:133]
	s_mov_b32 m0, s43
	s_nop 0
	global_load_lds_dwordx4 v[240:241], off
	s_waitcnt vmcnt(8)
	s_waitcnt lgkmcnt(0)
	s_barrier
	s_setprio 0
	s_waitcnt lgkmcnt(0)
	v_mfma_f32_16x16x32_bf16 v[124:127], v[144:147], v[202:205], v[124:127]
	v_mfma_f32_16x16x32_bf16 v[120:123], v[178:181], v[202:205], v[120:123]
	v_mfma_f32_16x16x32_bf16 v[108:111], v[144:147], v[210:213], v[108:111]
	v_mfma_f32_16x16x32_bf16 v[104:107], v[178:181], v[210:213], v[104:107]
	v_mfma_f32_16x16x32_bf16 v[92:95], v[144:147], v[218:221], v[92:95]
	v_mfma_f32_16x16x32_bf16 v[88:91], v[178:181], v[218:221], v[88:91]
	v_mfma_f32_16x16x32_bf16 v[76:79], v[144:147], v[226:229], v[76:79]
	v_mfma_f32_16x16x32_bf16 v[72:75], v[178:181], v[226:229], v[72:75]
	v_mfma_f32_16x16x32_bf16 v[124:127], v[174:177], v[206:209], v[124:127]
	v_mfma_f32_16x16x32_bf16 v[120:123], v[182:185], v[206:209], v[120:123]
	v_mfma_f32_16x16x32_bf16 v[108:111], v[174:177], v[214:217], v[108:111]
	v_mfma_f32_16x16x32_bf16 v[104:107], v[182:185], v[214:217], v[104:107]
	v_mfma_f32_16x16x32_bf16 v[92:95], v[174:177], v[222:225], v[92:95]
	v_mfma_f32_16x16x32_bf16 v[88:91], v[182:185], v[222:225], v[88:91]
	v_mfma_f32_16x16x32_bf16 v[76:79], v[174:177], v[230:233], v[76:79]
	v_mfma_f32_16x16x32_bf16 v[72:75], v[182:185], v[230:233], v[72:75]
	s_setprio 1
	s_setprio 0
	v_mfma_f32_16x16x32_bf16 v[116:119], v[186:189], v[202:205], v[116:119]
	v_mfma_f32_16x16x32_bf16 v[112:115], v[194:197], v[202:205], v[112:115]
	v_mfma_f32_16x16x32_bf16 v[100:103], v[186:189], v[210:213], v[100:103]
	v_mfma_f32_16x16x32_bf16 v[96:99], v[194:197], v[210:213], v[96:99]
	v_mfma_f32_16x16x32_bf16 v[84:87], v[186:189], v[218:221], v[84:87]
	v_mfma_f32_16x16x32_bf16 v[80:83], v[194:197], v[218:221], v[80:83]
	v_mfma_f32_16x16x32_bf16 v[68:71], v[186:189], v[226:229], v[68:71]
	v_mfma_f32_16x16x32_bf16 v[64:67], v[194:197], v[226:229], v[64:67]
	v_mfma_f32_16x16x32_bf16 v[116:119], v[190:193], v[206:209], v[116:119]
	v_mfma_f32_16x16x32_bf16 v[112:115], v[198:201], v[206:209], v[112:115]
	v_mfma_f32_16x16x32_bf16 v[100:103], v[190:193], v[214:217], v[100:103]
	v_mfma_f32_16x16x32_bf16 v[96:99], v[198:201], v[214:217], v[96:99]
	v_mfma_f32_16x16x32_bf16 v[84:87], v[190:193], v[222:225], v[84:87]
	v_mfma_f32_16x16x32_bf16 v[80:83], v[198:201], v[222:225], v[80:83]
	v_mfma_f32_16x16x32_bf16 v[68:71], v[190:193], v[230:233], v[68:71]
	v_mfma_f32_16x16x32_bf16 v[64:67], v[198:201], v[230:233], v[64:67]
	s_setprio 1
	s_barrier
; #define PG8_STAGE(bufoff, gbase, voff) do { _Pragma("unroll") for (int _i = 0; _i < 2; ++_i) \
;         __builtin_amdgcn_global_load_lds((const unsigned*)((const char*)(gbase) + (voff)[_i]), (PG8_LAS unsigned*)(lds + (bufoff) + ldsw + _i * 8192), 16, 0, 0); } while (0)
; #define PG8_LDA(dst, b, h) do { _Pragma("unroll") for (int m = 0; m < 4; ++m) _Pragma("unroll") for (int k = 0; k < 2; ++k) dst[m][k] = *(const PG8_LAS bf16x8*)(lds + PG8_SA(b, h) + aoff + m * 2048 + k * 1024); } while (0)
; #define PG8_LDB(dst, b, h) do { _Pragma("unroll") for (int n = 0; n < 2; ++n) _Pragma("unroll") for (int k = 0; k < 2; ++k) dst[n][k] = *(const PG8_LAS bf16x8*)(lds + PG8_SB(b, h) + boff + n * 2048 + k * 1024); } while (0)
; #define PG8_MMA(ai, bj, At, Bt) do { __builtin_amdgcn_s_setprio(1); _Pragma("unroll") for (int m = 0; m < 4; ++m) _Pragma("unroll") for (int n = 0; n < 2; ++n) _Pragma("unroll") for (int k = 0; k < 2; ++k) \
;         acc[ai][bj][m][n] = __builtin_amdgcn_mfma_f32_16x16x32_bf16(Bt[n][k], At[m][k], acc[ai][bj][m][n], 0, 0, 0); __builtin_amdgcn_s_setprio(0); } while (0)
; #define PG8_WAIT_V(n) asm volatile("s_waitcnt vmcnt(" #n ")" ::: "memory")
; template <class Epi, class Sched, bool ALIGN_EPI = false, bool SP2 = false>
; __device__ __forceinline__ void gemm_phase(PG8_LAS unsigned char* lds, const Gemm g, const Sched& S, const Epi& E) {
;     ...
;             PG8_LDB(B0, 0, 0); PG8_LDB(B1, 0, 1); PG8_SCHED; PG8_LDA(At, 0, 0); PG8_STAGE(PG8_SA(1, 1), a1 + hstep, voffA);
;             PG8_WAIT_V(8); PG8_WAIT_L(0); PG8_BAR; PG8_MMA(0, 0, At, B0); PG8_MMA(0, 1, At, B1); PG8_BAR; PG8_SCHED;
;             PG8_LDA(At, 0, 1); PG8_STAGE(PG8_SB(0, 0), b2, voffB); PG8_STAGE(PG8_SB(0, 1), b2 + hstep, voffB); PG8_STAGE(PG8_SA(0, 0), a2, voffA);
;             PG8_WAIT_V(8); PG8_WAIT_L(0); PG8_BAR; PG8_MMA(1, 0, At, B0); PG8_MMA(1, 1, At, B1); PG8_BAR; PG8_SCHED;
;             PG8_LDB(B0, 1, 0); PG8_LDB(B1, 1, 1); PG8_SCHED; PG8_LDA(At, 1, 0); PG8_STAGE(PG8_SA(0, 1), a2 + hstep, voffA);
;             PG8_WAIT_V(8); PG8_WAIT_L(0); PG8_BAR; PG8_MMA(0, 0, At, B0); PG8_MMA(0, 1, At, B1); PG8_BAR; PG8_SCHED;
;             PG8_LDA(At, 1, 1); PG8_STAGE(PG8_SB(1, 0), b3, voffB); PG8_STAGE(PG8_SB(1, 1), b3 + hstep, voffB); PG8_STAGE(PG8_SA(1, 0), a3, voffA);
;             PG8_WAIT_V(8); PG8_WAIT_L(0); PG8_BAR; PG8_MMA(1, 0, At, B0); PG8_MMA(1, 1, At, B1); PG8_BAR; PG8_SCHED;
	s_add_i32 s8, s57, s39
	v_lshl_add_u64 v[154:155], v[154:155], 0, s[18:19]
	s_mov_b32 m0, s8
	ds_read_b128 v[202:205], v171 offset:49152
	ds_read_b128 v[206:209], v171 offset:50176
	ds_read_b128 v[210:213], v171 offset:51200
	ds_read_b128 v[214:217], v171 offset:52224
	ds_read_b128 v[218:221], v171 offset:53248
	ds_read_b128 v[222:225], v171 offset:54272
	ds_read_b128 v[226:229], v171 offset:55296
	ds_read_b128 v[230:233], v171 offset:56320
	global_load_lds_dwordx4 v[154:155], off
	s_add_i32 m0, s8, 0x2000
	s_add_u32 s6, s6, 0x40080
	v_lshl_add_u64 v[154:155], v[234:235], 0, s[18:19]
	s_addc_u32 s7, s7, 0
	s_add_i32 s8, s69, s39
	global_load_lds_dwordx4 v[154:155], off
	v_lshl_add_u64 v[154:155], s[6:7], 0, v[130:131]
	s_mov_b32 m0, s8
	s_nop 0
	global_load_lds_dwordx4 v[154:155], off
	v_lshl_add_u64 v[154:155], s[6:7], 0, v[134:135]
	s_add_i32 m0, s8, 0x2000
	s_nop 0
	global_load_lds_dwordx4 v[154:155], off
	v_lshl_add_u64 v[154:155], v[236:237], 0, s[18:19]
	s_mov_b32 m0, s45
	s_nop 0
	global_load_lds_dwordx4 v[154:155], off
	v_lshl_add_u64 v[154:155], v[238:239], 0, s[18:19]
	s_mov_b32 m0, s50
	s_nop 0
	global_load_lds_dwordx4 v[154:155], off
	s_waitcnt vmcnt(8)
	s_waitcnt lgkmcnt(0)
	s_barrier
	s_setprio 0
	s_waitcnt lgkmcnt(0)
	v_mfma_f32_16x16x32_bf16 v[60:63], v[144:147], v[202:205], v[60:63]
	v_mfma_f32_16x16x32_bf16 v[56:59], v[178:181], v[202:205], v[56:59]
	v_mfma_f32_16x16x32_bf16 v[44:47], v[144:147], v[210:213], v[44:47]
	v_mfma_f32_16x16x32_bf16 v[40:43], v[178:181], v[210:213], v[40:43]
	v_mfma_f32_16x16x32_bf16 v[28:31], v[144:147], v[218:221], v[28:31]
	v_mfma_f32_16x16x32_bf16 v[24:27], v[178:181], v[218:221], v[24:27]
	v_mfma_f32_16x16x32_bf16 v[12:15], v[144:147], v[226:229], v[12:15]
	v_mfma_f32_16x16x32_bf16 v[8:11], v[178:181], v[226:229], v[8:11]
	v_mfma_f32_16x16x32_bf16 v[60:63], v[174:177], v[206:209], v[60:63]
	v_mfma_f32_16x16x32_bf16 v[56:59], v[182:185], v[206:209], v[56:59]
	v_mfma_f32_16x16x32_bf16 v[44:47], v[174:177], v[214:217], v[44:47]
	v_mfma_f32_16x16x32_bf16 v[40:43], v[182:185], v[214:217], v[40:43]
	v_mfma_f32_16x16x32_bf16 v[28:31], v[174:177], v[222:225], v[28:31]
	v_mfma_f32_16x16x32_bf16 v[24:27], v[182:185], v[222:225], v[24:27]
	v_mfma_f32_16x16x32_bf16 v[12:15], v[174:177], v[230:233], v[12:15]
	v_mfma_f32_16x16x32_bf16 v[8:11], v[182:185], v[230:233], v[8:11]
	s_setprio 1
	s_setprio 0
	v_mfma_f32_16x16x32_bf16 v[52:55], v[186:189], v[202:205], v[52:55]
	v_mfma_f32_16x16x32_bf16 v[48:51], v[194:197], v[202:205], v[48:51]
	v_mfma_f32_16x16x32_bf16 v[36:39], v[186:189], v[210:213], v[36:39]
	v_mfma_f32_16x16x32_bf16 v[32:35], v[194:197], v[210:213], v[32:35]
	v_mfma_f32_16x16x32_bf16 v[20:23], v[186:189], v[218:221], v[20:23]
	v_mfma_f32_16x16x32_bf16 v[16:19], v[194:197], v[218:221], v[16:19]
	v_mfma_f32_16x16x32_bf16 v[4:7], v[186:189], v[226:229], v[4:7]
	v_mfma_f32_16x16x32_bf16 v[0:3], v[194:197], v[226:229], v[0:3]
	v_mfma_f32_16x16x32_bf16 v[52:55], v[190:193], v[206:209], v[52:55]
	v_mfma_f32_16x16x32_bf16 v[48:51], v[198:201], v[206:209], v[48:51]
	v_mfma_f32_16x16x32_bf16 v[36:39], v[190:193], v[214:217], v[36:39]
	v_mfma_f32_16x16x32_bf16 v[32:35], v[198:201], v[214:217], v[32:35]
	v_mfma_f32_16x16x32_bf16 v[20:23], v[190:193], v[222:225], v[20:23]
	v_mfma_f32_16x16x32_bf16 v[16:19], v[198:201], v[222:225], v[16:19]
	v_mfma_f32_16x16x32_bf16 v[4:7], v[190:193], v[230:233], v[4:7]
	v_mfma_f32_16x16x32_bf16 v[0:3], v[198:201], v[230:233], v[0:3]
	s_setprio 1
	s_barrier
	s_add_i32 s56, s56, 2
	s_add_u32 s4, s4, 0x100
	s_addc_u32 s5, s5, 0
	s_add_u32 s52, s52, 0x100
	s_addc_u32 s53, s53, 0
	s_cmp_gt_u32 s56, 13
	s_cbranch_scc0 .LBB0_1247
	s_and_b64 vcc, exec, s[20:21]
	s_cbranch_vccz .LBB0_1250
	s_barrier

; #define PG8_STAGE(bufoff, gbase, voff) do { _Pragma("unroll") for (int _i = 0; _i < 2; ++_i) \
;         __builtin_amdgcn_global_load_lds((const unsigned*)((const char*)(gbase) + (voff)[_i]), (PG8_LAS unsigned*)(lds + (bufoff) + ldsw + _i * 8192), 16, 0, 0); } while (0)
; #define PG8_LDA(dst, b, h) do { _Pragma("unroll") for (int m = 0; m < 4; ++m) _Pragma("unroll") for (int k = 0; k < 2; ++k) dst[m][k] = *(const PG8_LAS bf16x8*)(lds + PG8_SA(b, h) + aoff + m * 2048 + k * 1024); } while (0)
; #define PG8_LDB(dst, b, h) do { _Pragma("unroll") for (int n = 0; n < 2; ++n) _Pragma("unroll") for (int k = 0; k < 2; ++k) dst[n][k] = *(const PG8_LAS bf16x8*)(lds + PG8_SB(b, h) + boff + n * 2048 + k * 1024); } while (0)
; #define PG8_MMA(ai, bj, At, Bt) do { __builtin_amdgcn_s_setprio(1); _Pragma("unroll") for (int m = 0; m < 4; ++m) _Pragma("unroll") for (int n = 0; n < 2; ++n) _Pragma("unroll") for (int k = 0; k < 2; ++k) \
;         acc[ai][bj][m][n] = __builtin_amdgcn_mfma_f32_16x16x32_bf16(Bt[n][k], At[m][k], acc[ai][bj][m][n], 0, 0, 0); __builtin_amdgcn_s_setprio(0); } while (0)
; #define PG8_WAIT_V(n) asm volatile("s_waitcnt vmcnt(" #n ")" ::: "memory")
; template <class Epi, class Sched, bool ALIGN_EPI = false, bool SP2 = false>
; __device__ __forceinline__ void gemm_phase(PG8_LAS unsigned char* lds, const Gemm g, const Sched& S, const Epi& E) {
;     ...
;             PG8_LDB(B0, 0, 0); PG8_LDB(B1, 0, 1); PG8_SCHED; PG8_LDA(At, 0, 0); PG8_STAGE(PG8_SA(1, 1), a1 + hstep, voffA);
;             PG8_WAIT_V(8); PG8_WAIT_L(0); PG8_BAR; PG8_MMA(0, 0, At, B0); PG8_MMA(0, 1, At, B1); PG8_BAR; PG8_SCHED;
;             PG8_LDA(At, 0, 1); PG8_STAGE(PG8_SB(0, 0), b2, voffB); PG8_STAGE(PG8_SB(0, 1), b2 + hstep, voffB); PG8_STAGE(PG8_SA(0, 0), a2, voffA);
;             PG8_WAIT_V(8); PG8_WAIT_L(0); PG8_BAR; PG8_MMA(1, 0, At, B0); PG8_MMA(1, 1, At, B1); PG8_BAR; PG8_SCHED;
;             PG8_LDB(B0, 1, 0); PG8_LDB(B1, 1, 1); PG8_SCHED; PG8_LDA(At, 1, 0); PG8_STAGE(PG8_SA(0, 1), a2 + hstep, voffA);
;             PG8_WAIT_V(8); PG8_WAIT_L(0); PG8_BAR; PG8_MMA(0, 0, At, B0); PG8_MMA(0, 1, At, B1); PG8_BAR; PG8_SCHED;
;             PG8_LDA(At, 1, 1); PG8_STAGE(PG8_SB(1, 0), b3, voffB); PG8_STAGE(PG8_SB(1, 1), b3 + hstep, voffB); PG8_STAGE(PG8_SA(1, 0), a3, voffA);
;             PG8_WAIT_V(8); PG8_WAIT_L(0); PG8_BAR; PG8_MMA(1, 0, At, B0); PG8_MMA(1, 1, At, B1); PG8_BAR; PG8_SCHED;
.LBB0_1271:
	ds_read_b128 v[156:159], v135
	ds_read_b128 v[170:173], v135 offset:1024
	ds_read_b128 v[174:177], v135 offset:2048
	ds_read_b128 v[178:181], v135 offset:3072
	ds_read_b128 v[182:185], v162
	ds_read_b128 v[186:189], v162 offset:1024
	ds_read_b128 v[190:193], v162 offset:2048
	ds_read_b128 v[194:197], v162 offset:3072
	s_add_u32 s30, s28, 0xfffe0080
	s_addc_u32 s31, s29, -1
	s_cmp_eq_u32 s63, 4
	s_cselect_b32 s35, s21, s31
	s_cselect_b32 s34, s56, s30
	s_cselect_b32 s31, s19, s62
	s_cselect_b32 s30, s57, s61
	v_lshl_add_u64 v[160:161], s[28:29], 0, v[144:145]
	s_add_i32 m0, s27, 0xc000
	ds_read_b128 v[198:201], v163
	ds_read_b128 v[202:205], v163 offset:1024
	ds_read_b128 v[206:209], v163 offset:2048
	ds_read_b128 v[210:213], v163 offset:3072
	ds_read_b128 v[214:217], v163 offset:4096
	ds_read_b128 v[218:221], v163 offset:5120
	ds_read_b128 v[222:225], v163 offset:6144
	ds_read_b128 v[226:229], v163 offset:7168
	global_load_lds_dwordx4 v[160:161], off
	v_lshl_add_u64 v[160:161], s[28:29], 0, v[146:147]
	s_add_i32 m0, s27, 0xe000
	s_nop 0
	global_load_lds_dwordx4 v[160:161], off
	s_waitcnt vmcnt(8)
	s_waitcnt lgkmcnt(0)
	s_barrier
	s_setprio 0
	s_waitcnt lgkmcnt(0)
	v_mfma_f32_16x16x32_bf16 v[124:127], v[156:159], v[198:201], v[124:127]
	v_mfma_f32_16x16x32_bf16 v[120:123], v[174:177], v[198:201], v[120:123]
	v_mfma_f32_16x16x32_bf16 v[108:111], v[156:159], v[206:209], v[108:111]
	v_mfma_f32_16x16x32_bf16 v[104:107], v[174:177], v[206:209], v[104:107]
	v_mfma_f32_16x16x32_bf16 v[92:95], v[156:159], v[214:217], v[92:95]
	v_mfma_f32_16x16x32_bf16 v[88:91], v[174:177], v[214:217], v[88:91]
	v_mfma_f32_16x16x32_bf16 v[76:79], v[156:159], v[222:225], v[76:79]
	v_mfma_f32_16x16x32_bf16 v[72:75], v[174:177], v[222:225], v[72:75]
	v_mfma_f32_16x16x32_bf16 v[124:127], v[170:173], v[202:205], v[124:127]
	v_mfma_f32_16x16x32_bf16 v[120:123], v[178:181], v[202:205], v[120:123]
	v_mfma_f32_16x16x32_bf16 v[108:111], v[170:173], v[210:213], v[108:111]
	v_mfma_f32_16x16x32_bf16 v[104:107], v[178:181], v[210:213], v[104:107]
	v_mfma_f32_16x16x32_bf16 v[92:95], v[170:173], v[218:221], v[92:95]
	v_mfma_f32_16x16x32_bf16 v[88:91], v[178:181], v[218:221], v[88:91]
	v_mfma_f32_16x16x32_bf16 v[76:79], v[170:173], v[226:229], v[76:79]
	v_mfma_f32_16x16x32_bf16 v[72:75], v[178:181], v[226:229], v[72:75]
	s_setprio 1
	s_setprio 0
	v_mfma_f32_16x16x32_bf16 v[116:119], v[182:185], v[198:201], v[116:119]
	v_mfma_f32_16x16x32_bf16 v[112:115], v[190:193], v[198:201], v[112:115]
	v_mfma_f32_16x16x32_bf16 v[100:103], v[182:185], v[206:209], v[100:103]
	v_mfma_f32_16x16x32_bf16 v[96:99], v[190:193], v[206:209], v[96:99]
	v_mfma_f32_16x16x32_bf16 v[84:87], v[182:185], v[214:217], v[84:87]
	v_mfma_f32_16x16x32_bf16 v[80:83], v[190:193], v[214:217], v[80:83]
	v_mfma_f32_16x16x32_bf16 v[68:71], v[182:185], v[222:225], v[68:71]
	v_mfma_f32_16x16x32_bf16 v[64:67], v[190:193], v[222:225], v[64:67]
	v_mfma_f32_16x16x32_bf16 v[116:119], v[186:189], v[202:205], v[116:119]
	v_mfma_f32_16x16x32_bf16 v[112:115], v[194:197], v[202:205], v[112:115]
	v_mfma_f32_16x16x32_bf16 v[100:103], v[186:189], v[210:213], v[100:103]
	v_mfma_f32_16x16x32_bf16 v[96:99], v[194:197], v[210:213], v[96:99]
	v_mfma_f32_16x16x32_bf16 v[84:87], v[186:189], v[218:221], v[84:87]
	v_mfma_f32_16x16x32_bf16 v[80:83], v[194:197], v[218:221], v[80:83]
	v_mfma_f32_16x16x32_bf16 v[68:71], v[186:189], v[226:229], v[68:71]
	v_mfma_f32_16x16x32_bf16 v[64:67], v[194:197], v[226:229], v[64:67]
	s_setprio 1
	s_barrier
	s_add_i32 s68, s45, s37
	v_lshl_add_u64 v[160:161], s[30:31], 0, v[138:139]
	s_mov_b32 m0, s68
	ds_read_b128 v[198:201], v163 offset:16384
	ds_read_b128 v[202:205], v163 offset:17408
	ds_read_b128 v[206:209], v163 offset:18432
	ds_read_b128 v[210:213], v163 offset:19456
	ds_read_b128 v[214:217], v163 offset:20480
	ds_read_b128 v[218:221], v163 offset:21504
	ds_read_b128 v[222:225], v163 offset:22528
	ds_read_b128 v[226:229], v163 offset:23552
	global_load_lds_dwordx4 v[160:161], off
	s_add_i32 m0, s68, 0x2000
	s_add_u32 s68, s30, 0x20000
	v_lshl_add_u64 v[230:231], s[30:31], 0, v[142:143]
	s_addc_u32 s69, s31, 0
	s_add_i32 s70, s50, s37
	global_load_lds_dwordx4 v[230:231], off
	v_lshl_add_u64 v[232:233], s[68:69], 0, v[138:139]
	s_mov_b32 m0, s70
	v_lshl_add_u64 v[234:235], s[34:35], 0, v[140:141]
	global_load_lds_dwordx4 v[232:233], off
	v_lshl_add_u64 v[232:233], s[68:69], 0, v[142:143]
	s_add_i32 m0, s70, 0x2000
	s_nop 0
	global_load_lds_dwordx4 v[232:233], off
	v_lshl_add_u64 v[232:233], s[34:35], 0, v[136:137]
	s_mov_b32 m0, s27
	s_nop 0
	global_load_lds_dwordx4 v[232:233], off
	s_mov_b32 m0, s38
	s_nop 0
	global_load_lds_dwordx4 v[234:235], off
	s_waitcnt vmcnt(8)
	s_waitcnt lgkmcnt(0)
	s_barrier
; #define PG8_STAGE(bufoff, gbase, voff) do { _Pragma("unroll") for (int _i = 0; _i < 2; ++_i) \
;         __builtin_amdgcn_global_load_lds((const unsigned*)((const char*)(gbase) + (voff)[_i]), (PG8_LAS unsigned*)(lds + (bufoff) + ldsw + _i * 8192), 16, 0, 0); } while (0)
; #define PG8_LDA(dst, b, h) do { _Pragma("unroll") for (int m = 0; m < 4; ++m) _Pragma("unroll") for (int k = 0; k < 2; ++k) dst[m][k] = *(const PG8_LAS bf16x8*)(lds + PG8_SA(b, h) + aoff + m * 2048 + k * 1024); } while (0)
; #define PG8_LDB(dst, b, h) do { _Pragma("unroll") for (int n = 0; n < 2; ++n) _Pragma("unroll") for (int k = 0; k < 2; ++k) dst[n][k] = *(const PG8_LAS bf16x8*)(lds + PG8_SB(b, h) + boff + n * 2048 + k * 1024); } while (0)
; #define PG8_MMA(ai, bj, At, Bt) do { __builtin_amdgcn_s_setprio(1); _Pragma("unroll") for (int m = 0; m < 4; ++m) _Pragma("unroll") for (int n = 0; n < 2; ++n) _Pragma("unroll") for (int k = 0; k < 2; ++k) \
;         acc[ai][bj][m][n] = __builtin_amdgcn_mfma_f32_16x16x32_bf16(Bt[n][k], At[m][k], acc[ai][bj][m][n], 0, 0, 0); __builtin_amdgcn_s_setprio(0); } while (0)
; #define PG8_WAIT_V(n) asm volatile("s_waitcnt vmcnt(" #n ")" ::: "memory")
; #define PG8_WAIT_L(n) asm volatile("s_waitcnt lgkmcnt(" #n ")" ::: "memory")
; #define PG8_BAR __builtin_amdgcn_s_barrier()
; #define PG8_SCHED __builtin_amdgcn_sched_barrier(0)
; template <class Epi, class Sched, bool ALIGN_EPI = false, bool SP2 = false>
; __device__ __forceinline__ void gemm_phase(PG8_LAS unsigned char* lds, const Gemm g, const Sched& S, const Epi& E) {
;     ...
;             PG8_WAIT_V(8); PG8_WAIT_L(0); PG8_BAR; PG8_MMA(1, 0, At, B0); PG8_MMA(1, 1, At, B1); PG8_BAR; PG8_SCHED;
;             PG8_LDB(B0, 1, 0); PG8_LDB(B1, 1, 1); PG8_SCHED; PG8_LDA(At, 1, 0); PG8_STAGE(PG8_SA(0, 1), a2 + hstep, voffA);
;             PG8_WAIT_V(8); PG8_WAIT_L(0); PG8_BAR; PG8_MMA(0, 0, At, B0); PG8_MMA(0, 1, At, B1); PG8_BAR; PG8_SCHED;
	s_setprio 0
	s_waitcnt lgkmcnt(0)
	v_mfma_f32_16x16x32_bf16 v[60:63], v[156:159], v[198:201], v[60:63]
	v_mfma_f32_16x16x32_bf16 v[56:59], v[174:177], v[198:201], v[56:59]
	v_mfma_f32_16x16x32_bf16 v[44:47], v[156:159], v[206:209], v[44:47]
	v_mfma_f32_16x16x32_bf16 v[40:43], v[174:177], v[206:209], v[40:43]
	v_mfma_f32_16x16x32_bf16 v[28:31], v[156:159], v[214:217], v[28:31]
	v_mfma_f32_16x16x32_bf16 v[24:27], v[174:177], v[214:217], v[24:27]
	v_mfma_f32_16x16x32_bf16 v[12:15], v[156:159], v[222:225], v[12:15]
	v_mfma_f32_16x16x32_bf16 v[8:11], v[174:177], v[222:225], v[8:11]
	v_mfma_f32_16x16x32_bf16 v[60:63], v[170:173], v[202:205], v[60:63]
	v_mfma_f32_16x16x32_bf16 v[56:59], v[178:181], v[202:205], v[56:59]
	v_mfma_f32_16x16x32_bf16 v[44:47], v[170:173], v[210:213], v[44:47]
	v_mfma_f32_16x16x32_bf16 v[40:43], v[178:181], v[210:213], v[40:43]
	v_mfma_f32_16x16x32_bf16 v[28:31], v[170:173], v[218:221], v[28:31]
	v_mfma_f32_16x16x32_bf16 v[24:27], v[178:181], v[218:221], v[24:27]
	v_mfma_f32_16x16x32_bf16 v[12:15], v[170:173], v[226:229], v[12:15]
	v_mfma_f32_16x16x32_bf16 v[8:11], v[178:181], v[226:229], v[8:11]
	s_setprio 1
	s_setprio 0
	v_mfma_f32_16x16x32_bf16 v[52:55], v[182:185], v[198:201], v[52:55]
	v_mfma_f32_16x16x32_bf16 v[48:51], v[190:193], v[198:201], v[48:51]
	v_mfma_f32_16x16x32_bf16 v[36:39], v[182:185], v[206:209], v[36:39]
	v_mfma_f32_16x16x32_bf16 v[32:35], v[190:193], v[206:209], v[32:35]
	v_mfma_f32_16x16x32_bf16 v[20:23], v[182:185], v[214:217], v[20:23]
	v_mfma_f32_16x16x32_bf16 v[16:19], v[190:193], v[214:217], v[16:19]
	v_mfma_f32_16x16x32_bf16 v[4:7], v[182:185], v[222:225], v[4:7]
	v_mfma_f32_16x16x32_bf16 v[0:3], v[190:193], v[222:225], v[0:3]
	v_mfma_f32_16x16x32_bf16 v[52:55], v[186:189], v[202:205], v[52:55]
	v_mfma_f32_16x16x32_bf16 v[48:51], v[194:197], v[202:205], v[48:51]
	v_mfma_f32_16x16x32_bf16 v[36:39], v[186:189], v[210:213], v[36:39]
	v_mfma_f32_16x16x32_bf16 v[32:35], v[194:197], v[210:213], v[32:35]
	v_mfma_f32_16x16x32_bf16 v[20:23], v[186:189], v[218:221], v[20:23]
	v_mfma_f32_16x16x32_bf16 v[16:19], v[194:197], v[218:221], v[16:19]
	v_mfma_f32_16x16x32_bf16 v[4:7], v[186:189], v[226:229], v[4:7]
	v_mfma_f32_16x16x32_bf16 v[0:3], v[194:197], v[226:229], v[0:3]
	s_setprio 1
	s_barrier
	s_add_i32 s68, 0, 0x18000
	s_add_i32 s69, 0, 0x1c000
	v_add_u32_e32 v178, s68, v131
	v_add_u32_e32 v194, s69, v131
	ds_read_b128 v[156:159], v178
	ds_read_b128 v[170:173], v178 offset:1024
	ds_read_b128 v[174:177], v178 offset:2048
	ds_read_b128 v[178:181], v178 offset:3072
	ds_read_b128 v[182:185], v194
	ds_read_b128 v[186:189], v194 offset:1024
	ds_read_b128 v[190:193], v194 offset:2048
	ds_read_b128 v[194:197], v194 offset:3072
	s_add_u32 s34, s34, 0x20000
	s_addc_u32 s35, s35, 0
	s_mov_b32 m0, s39
	v_lshl_add_u64 v[236:237], s[34:35], 0, v[136:137]
	ds_read_b128 v[198:201], v163 offset:32768
	ds_read_b128 v[202:205], v163 offset:33792
	ds_read_b128 v[206:209], v163 offset:34816
	ds_read_b128 v[210:213], v163 offset:35840
	ds_read_b128 v[214:217], v163 offset:36864
	ds_read_b128 v[218:221], v163 offset:37888
	ds_read_b128 v[222:225], v163 offset:38912
	ds_read_b128 v[226:229], v163 offset:39936
	global_load_lds_dwordx4 v[236:237], off
	v_lshl_add_u64 v[236:237], s[34:35], 0, v[140:141]
	s_mov_b32 m0, s40
	s_nop 0
	global_load_lds_dwordx4 v[236:237], off
	s_waitcnt vmcnt(8)
	s_waitcnt lgkmcnt(0)
	s_barrier
	s_setprio 0
	s_waitcnt lgkmcnt(0)
	v_mfma_f32_16x16x32_bf16 v[124:127], v[156:159], v[198:201], v[124:127]
	v_mfma_f32_16x16x32_bf16 v[120:123], v[174:177], v[198:201], v[120:123]
	v_mfma_f32_16x16x32_bf16 v[108:111], v[156:159], v[206:209], v[108:111]
	v_mfma_f32_16x16x32_bf16 v[104:107], v[174:177], v[206:209], v[104:107]
	v_mfma_f32_16x16x32_bf16 v[92:95], v[156:159], v[214:217], v[92:95]
	v_mfma_f32_16x16x32_bf16 v[88:91], v[174:177], v[214:217], v[88:91]
	v_mfma_f32_16x16x32_bf16 v[76:79], v[156:159], v[222:225], v[76:79]
	v_mfma_f32_16x16x32_bf16 v[72:75], v[174:177], v[222:225], v[72:75]
	v_mfma_f32_16x16x32_bf16 v[124:127], v[170:173], v[202:205], v[124:127]
	v_mfma_f32_16x16x32_bf16 v[120:123], v[178:181], v[202:205], v[120:123]
	v_mfma_f32_16x16x32_bf16 v[108:111], v[170:173], v[210:213], v[108:111]
	v_mfma_f32_16x16x32_bf16 v[104:107], v[178:181], v[210:213], v[104:107]
	v_mfma_f32_16x16x32_bf16 v[92:95], v[170:173], v[218:221], v[92:95]
	v_mfma_f32_16x16x32_bf16 v[88:91], v[178:181], v[218:221], v[88:91]
	v_mfma_f32_16x16x32_bf16 v[76:79], v[170:173], v[226:229], v[76:79]
	v_mfma_f32_16x16x32_bf16 v[72:75], v[178:181], v[226:229], v[72:75]
	s_setprio 1
	s_setprio 0
	v_mfma_f32_16x16x32_bf16 v[116:119], v[182:185], v[198:201], v[116:119]
	v_mfma_f32_16x16x32_bf16 v[112:115], v[190:193], v[198:201], v[112:115]
	v_mfma_f32_16x16x32_bf16 v[100:103], v[182:185], v[206:209], v[100:103]
	v_mfma_f32_16x16x32_bf16 v[96:99], v[190:193], v[206:209], v[96:99]
	v_mfma_f32_16x16x32_bf16 v[84:87], v[182:185], v[214:217], v[84:87]
	v_mfma_f32_16x16x32_bf16 v[80:83], v[190:193], v[214:217], v[80:83]
	v_mfma_f32_16x16x32_bf16 v[68:71], v[182:185], v[222:225], v[68:71]
	v_mfma_f32_16x16x32_bf16 v[64:67], v[190:193], v[222:225], v[64:67]
	v_mfma_f32_16x16x32_bf16 v[116:119], v[186:189], v[202:205], v[116:119]
	v_mfma_f32_16x16x32_bf16 v[112:115], v[194:197], v[202:205], v[112:115]
	v_mfma_f32_16x16x32_bf16 v[100:103], v[186:189], v[210:213], v[100:103]
	v_mfma_f32_16x16x32_bf16 v[96:99], v[194:197], v[210:213], v[96:99]
	v_mfma_f32_16x16x32_bf16 v[84:87], v[186:189], v[218:221], v[84:87]
	v_mfma_f32_16x16x32_bf16 v[80:83], v[194:197], v[218:221], v[80:83]
	v_mfma_f32_16x16x32_bf16 v[68:71], v[186:189], v[226:229], v[68:71]
	v_mfma_f32_16x16x32_bf16 v[64:67], v[194:197], v[226:229], v[64:67]
	s_setprio 1
	s_barrier
; #define PG8_STAGE(bufoff, gbase, voff) do { _Pragma("unroll") for (int _i = 0; _i < 2; ++_i) \
;         __builtin_amdgcn_global_load_lds((const unsigned*)((const char*)(gbase) + (voff)[_i]), (PG8_LAS unsigned*)(lds + (bufoff) + ldsw + _i * 8192), 16, 0, 0); } while (0)
; #define PG8_LDA(dst, b, h) do { _Pragma("unroll") for (int m = 0; m < 4; ++m) _Pragma("unroll") for (int k = 0; k < 2; ++k) dst[m][k] = *(const PG8_LAS bf16x8*)(lds + PG8_SA(b, h) + aoff + m * 2048 + k * 1024); } while (0)
; #define PG8_MMA(ai, bj, At, Bt) do { __builtin_amdgcn_s_setprio(1); _Pragma("unroll") for (int m = 0; m < 4; ++m) _Pragma("unroll") for (int n = 0; n < 2; ++n) _Pragma("unroll") for (int k = 0; k < 2; ++k) \
;         acc[ai][bj][m][n] = __builtin_amdgcn_mfma_f32_16x16x32_bf16(Bt[n][k], At[m][k], acc[ai][bj][m][n], 0, 0, 0); __builtin_amdgcn_s_setprio(0); } while (0)
; #define PG8_WAIT_V(n) asm volatile("s_waitcnt vmcnt(" #n ")" ::: "memory")
; #define PG8_WAIT_L(n) asm volatile("s_waitcnt lgkmcnt(" #n ")" ::: "memory")
; #define PG8_BAR __builtin_amdgcn_s_barrier()
; #define PG8_SCHED __builtin_amdgcn_sched_barrier(0)
; template <class Epi, class Sched, bool ALIGN_EPI = false, bool SP2 = false>
; __device__ __forceinline__ void gemm_phase(PG8_LAS unsigned char* lds, const Gemm g, const Sched& S, const Epi& E) {
;     ...
;         for (int t = 0; t < nt; t += 2) {
;             const bool last = (t == nt - 2);
;     ...
;             PG8_LDA(At, 1, 1); PG8_STAGE(PG8_SB(1, 0), b3, voffB); PG8_STAGE(PG8_SB(1, 1), b3 + hstep, voffB); PG8_STAGE(PG8_SA(1, 0), a3, voffA);
;             PG8_WAIT_V(8); PG8_WAIT_L(0); PG8_BAR; PG8_MMA(1, 0, At, B0); PG8_MMA(1, 1, At, B1); PG8_BAR; PG8_SCHED;
	s_add_i32 s34, s68, s37
	v_lshl_add_u64 v[160:161], v[160:161], 0, s[6:7]
	s_mov_b32 m0, s34
	ds_read_b128 v[198:201], v163 offset:49152
	ds_read_b128 v[202:205], v163 offset:50176
	ds_read_b128 v[206:209], v163 offset:51200
	ds_read_b128 v[210:213], v163 offset:52224
	ds_read_b128 v[214:217], v163 offset:53248
	ds_read_b128 v[218:221], v163 offset:54272
	ds_read_b128 v[222:225], v163 offset:55296
	ds_read_b128 v[226:229], v163 offset:56320
	global_load_lds_dwordx4 v[160:161], off
	s_add_i32 m0, s34, 0x2000
	s_add_u32 s30, s30, 0x20080
	v_lshl_add_u64 v[160:161], v[230:231], 0, s[6:7]
	s_addc_u32 s31, s31, 0
	s_add_i32 s34, s69, s37
	global_load_lds_dwordx4 v[160:161], off
	v_lshl_add_u64 v[160:161], s[30:31], 0, v[138:139]
	s_mov_b32 m0, s34
	s_nop 0
	global_load_lds_dwordx4 v[160:161], off
	v_lshl_add_u64 v[160:161], s[30:31], 0, v[142:143]
	s_add_i32 m0, s34, 0x2000
	s_nop 0
	global_load_lds_dwordx4 v[160:161], off
	v_lshl_add_u64 v[160:161], v[232:233], 0, s[6:7]
	s_mov_b32 m0, s42
	s_nop 0
	global_load_lds_dwordx4 v[160:161], off
	v_lshl_add_u64 v[160:161], v[234:235], 0, s[6:7]
	s_mov_b32 m0, s43
	s_nop 0
	global_load_lds_dwordx4 v[160:161], off
	s_waitcnt vmcnt(8)
	s_waitcnt lgkmcnt(0)
	s_barrier
	s_setprio 0
	s_waitcnt lgkmcnt(0)
	v_mfma_f32_16x16x32_bf16 v[60:63], v[156:159], v[198:201], v[60:63]
	v_mfma_f32_16x16x32_bf16 v[56:59], v[174:177], v[198:201], v[56:59]
	v_mfma_f32_16x16x32_bf16 v[44:47], v[156:159], v[206:209], v[44:47]
	v_mfma_f32_16x16x32_bf16 v[40:43], v[174:177], v[206:209], v[40:43]
	v_mfma_f32_16x16x32_bf16 v[28:31], v[156:159], v[214:217], v[28:31]
	v_mfma_f32_16x16x32_bf16 v[24:27], v[174:177], v[214:217], v[24:27]
	v_mfma_f32_16x16x32_bf16 v[12:15], v[156:159], v[222:225], v[12:15]
	v_mfma_f32_16x16x32_bf16 v[8:11], v[174:177], v[222:225], v[8:11]
	v_mfma_f32_16x16x32_bf16 v[60:63], v[170:173], v[202:205], v[60:63]
	v_mfma_f32_16x16x32_bf16 v[56:59], v[178:181], v[202:205], v[56:59]
	v_mfma_f32_16x16x32_bf16 v[44:47], v[170:173], v[210:213], v[44:47]
	v_mfma_f32_16x16x32_bf16 v[40:43], v[178:181], v[210:213], v[40:43]
	v_mfma_f32_16x16x32_bf16 v[28:31], v[170:173], v[218:221], v[28:31]
	v_mfma_f32_16x16x32_bf16 v[24:27], v[178:181], v[218:221], v[24:27]
	v_mfma_f32_16x16x32_bf16 v[12:15], v[170:173], v[226:229], v[12:15]
	v_mfma_f32_16x16x32_bf16 v[8:11], v[178:181], v[226:229], v[8:11]
	s_setprio 1
	s_setprio 0
	v_mfma_f32_16x16x32_bf16 v[52:55], v[182:185], v[198:201], v[52:55]
	v_mfma_f32_16x16x32_bf16 v[48:51], v[190:193], v[198:201], v[48:51]
	v_mfma_f32_16x16x32_bf16 v[36:39], v[182:185], v[206:209], v[36:39]
	v_mfma_f32_16x16x32_bf16 v[32:35], v[190:193], v[206:209], v[32:35]
	v_mfma_f32_16x16x32_bf16 v[20:23], v[182:185], v[214:217], v[20:23]
	v_mfma_f32_16x16x32_bf16 v[16:19], v[190:193], v[214:217], v[16:19]
	v_mfma_f32_16x16x32_bf16 v[4:7], v[182:185], v[222:225], v[4:7]
	v_mfma_f32_16x16x32_bf16 v[0:3], v[190:193], v[222:225], v[0:3]
	v_mfma_f32_16x16x32_bf16 v[52:55], v[186:189], v[202:205], v[52:55]
	v_mfma_f32_16x16x32_bf16 v[48:51], v[194:197], v[202:205], v[48:51]
	v_mfma_f32_16x16x32_bf16 v[36:39], v[186:189], v[210:213], v[36:39]
	v_mfma_f32_16x16x32_bf16 v[32:35], v[194:197], v[210:213], v[32:35]
	v_mfma_f32_16x16x32_bf16 v[20:23], v[186:189], v[218:221], v[20:23]
	v_mfma_f32_16x16x32_bf16 v[16:19], v[194:197], v[218:221], v[16:19]
	v_mfma_f32_16x16x32_bf16 v[4:7], v[186:189], v[226:229], v[4:7]
	v_mfma_f32_16x16x32_bf16 v[0:3], v[194:197], v[226:229], v[0:3]
	s_setprio 1
	s_barrier
	s_add_i32 s63, s63, 2
	s_add_u32 s28, s28, 0x100
	s_addc_u32 s29, s29, 0
	s_add_u32 s61, s61, 0x100
	s_addc_u32 s62, s62, 0
	s_cmp_gt_u32 s63, 5
	s_cbranch_scc0 .LBB0_1271
	s_and_b64 vcc, exec, s[8:9]
	s_cbranch_vccz .LBB0_1274
	s_barrier

; #define PG8_STAGE(bufoff, gbase, voff) do { _Pragma("unroll") for (int _i = 0; _i < 2; ++_i) \
;         __builtin_amdgcn_global_load_lds((const unsigned*)((const char*)(gbase) + (voff)[_i]), (PG8_LAS unsigned*)(lds + (bufoff) + ldsw + _i * 8192), 16, 0, 0); } while (0)
; #define PG8_LDA(dst, b, h) do { _Pragma("unroll") for (int m = 0; m < 4; ++m) _Pragma("unroll") for (int k = 0; k < 2; ++k) dst[m][k] = *(const PG8_LAS bf16x8*)(lds + PG8_SA(b, h) + aoff + m * 2048 + k * 1024); } while (0)
; #define PG8_LDB(dst, b, h) do { _Pragma("unroll") for (int n = 0; n < 2; ++n) _Pragma("unroll") for (int k = 0; k < 2; ++k) dst[n][k] = *(const PG8_LAS bf16x8*)(lds + PG8_SB(b, h) + boff + n * 2048 + k * 1024); } while (0)
; #define PG8_MMA(ai, bj, At, Bt) do { __builtin_amdgcn_s_setprio(1); _Pragma("unroll") for (int m = 0; m < 4; ++m) _Pragma("unroll") for (int n = 0; n < 2; ++n) _Pragma("unroll") for (int k = 0; k < 2; ++k) \
;         acc[ai][bj][m][n] = __builtin_amdgcn_mfma_f32_16x16x32_bf16(Bt[n][k], At[m][k], acc[ai][bj][m][n], 0, 0, 0); __builtin_amdgcn_s_setprio(0); } while (0)
; #define PG8_WAIT_V(n) asm volatile("s_waitcnt vmcnt(" #n ")" ::: "memory")
; #define PG8_WAIT_L(n) asm volatile("s_waitcnt lgkmcnt(" #n ")" ::: "memory")
; #define PG8_BAR __builtin_amdgcn_s_barrier()
; #define PG8_SCHED __builtin_amdgcn_sched_barrier(0)
; template <class Epi, class Sched, bool ALIGN_EPI = false, bool SP2 = false>
; __device__ __forceinline__ void gemm_phase(PG8_LAS unsigned char* lds, const Gemm g, const Sched& S, const Epi& E) {
;     ...
;             const bool last = (t == nt - 2);
;             const char* a1 = cA + (size_t)(t + 1) * kstep;
;             const char* a2 = last ? nA : cA + (size_t)(t + 2) * kstep; const char* b2 = last ? nB : cB + (size_t)(t + 2) * kstep;
;     ...
;             PG8_LDB(B0, 0, 0); PG8_LDB(B1, 0, 1); PG8_SCHED; PG8_LDA(At, 0, 0); PG8_STAGE(PG8_SA(1, 1), a1 + hstep, voffA);
;             PG8_WAIT_V(8); PG8_WAIT_L(0); PG8_BAR; PG8_MMA(0, 0, At, B0); PG8_MMA(0, 1, At, B1); PG8_BAR; PG8_SCHED;
;             PG8_LDA(At, 0, 1); PG8_STAGE(PG8_SB(0, 0), b2, voffB); PG8_STAGE(PG8_SB(0, 1), b2 + hstep, voffB); PG8_STAGE(PG8_SA(0, 0), a2, voffA);
.LBB0_1295:
	ds_read_b128 v[156:159], v143
	ds_read_b128 v[172:175], v143 offset:1024
	ds_read_b128 v[176:179], v143 offset:2048
	ds_read_b128 v[180:183], v143 offset:3072
	ds_read_b128 v[184:187], v161
	ds_read_b128 v[188:191], v161 offset:1024
	ds_read_b128 v[192:195], v161 offset:2048
	ds_read_b128 v[196:199], v161 offset:3072
	s_add_u32 s8, s6, 0xfffc0080
	s_addc_u32 s9, s7, -1
	s_cmp_eq_u32 s68, 12
	s_cselect_b32 s11, s12, s9
	s_cselect_b32 s10, s13, s8
	s_cselect_b32 s9, s27, s53
	s_cselect_b32 s8, s29, s52
	v_lshl_add_u64 v[162:163], s[6:7], 0, v[144:145]
	s_add_i32 m0, s40, 0xc000
	ds_read_b128 v[200:203], v170
	ds_read_b128 v[204:207], v170 offset:1024
	ds_read_b128 v[208:211], v170 offset:2048
	ds_read_b128 v[212:215], v170 offset:3072
	ds_read_b128 v[216:219], v170 offset:4096
	ds_read_b128 v[220:223], v170 offset:5120
	ds_read_b128 v[224:227], v170 offset:6144
	ds_read_b128 v[228:231], v170 offset:7168
	global_load_lds_dwordx4 v[162:163], off
	v_lshl_add_u64 v[162:163], s[6:7], 0, v[146:147]
	s_add_i32 m0, s40, 0xe000
	s_nop 0
	global_load_lds_dwordx4 v[162:163], off
	s_waitcnt vmcnt(8)
	s_waitcnt lgkmcnt(0)
	s_barrier
	s_setprio 0
	s_waitcnt lgkmcnt(0)
	v_mfma_f32_16x16x32_bf16 v[124:127], v[156:159], v[200:203], v[124:127]
	v_mfma_f32_16x16x32_bf16 v[120:123], v[176:179], v[200:203], v[120:123]
	v_mfma_f32_16x16x32_bf16 v[108:111], v[156:159], v[208:211], v[108:111]
	v_mfma_f32_16x16x32_bf16 v[104:107], v[176:179], v[208:211], v[104:107]
	v_mfma_f32_16x16x32_bf16 v[92:95], v[156:159], v[216:219], v[92:95]
	v_mfma_f32_16x16x32_bf16 v[88:91], v[176:179], v[216:219], v[88:91]
	v_mfma_f32_16x16x32_bf16 v[76:79], v[156:159], v[224:227], v[76:79]
	v_mfma_f32_16x16x32_bf16 v[72:75], v[176:179], v[224:227], v[72:75]
	v_mfma_f32_16x16x32_bf16 v[124:127], v[172:175], v[204:207], v[124:127]
	v_mfma_f32_16x16x32_bf16 v[120:123], v[180:183], v[204:207], v[120:123]
	v_mfma_f32_16x16x32_bf16 v[108:111], v[172:175], v[212:215], v[108:111]
	v_mfma_f32_16x16x32_bf16 v[104:107], v[180:183], v[212:215], v[104:107]
	v_mfma_f32_16x16x32_bf16 v[92:95], v[172:175], v[220:223], v[92:95]
	v_mfma_f32_16x16x32_bf16 v[88:91], v[180:183], v[220:223], v[88:91]
	v_mfma_f32_16x16x32_bf16 v[76:79], v[172:175], v[228:231], v[76:79]
	v_mfma_f32_16x16x32_bf16 v[72:75], v[180:183], v[228:231], v[72:75]
	s_setprio 1
	s_setprio 0
	v_mfma_f32_16x16x32_bf16 v[116:119], v[184:187], v[200:203], v[116:119]
	v_mfma_f32_16x16x32_bf16 v[112:115], v[192:195], v[200:203], v[112:115]
	v_mfma_f32_16x16x32_bf16 v[100:103], v[184:187], v[208:211], v[100:103]
	v_mfma_f32_16x16x32_bf16 v[96:99], v[192:195], v[208:211], v[96:99]
	v_mfma_f32_16x16x32_bf16 v[84:87], v[184:187], v[216:219], v[84:87]
	v_mfma_f32_16x16x32_bf16 v[80:83], v[192:195], v[216:219], v[80:83]
	v_mfma_f32_16x16x32_bf16 v[68:71], v[184:187], v[224:227], v[68:71]
	v_mfma_f32_16x16x32_bf16 v[64:67], v[192:195], v[224:227], v[64:67]
	v_mfma_f32_16x16x32_bf16 v[116:119], v[188:191], v[204:207], v[116:119]
	v_mfma_f32_16x16x32_bf16 v[112:115], v[196:199], v[204:207], v[112:115]
	v_mfma_f32_16x16x32_bf16 v[100:103], v[188:191], v[212:215], v[100:103]
	v_mfma_f32_16x16x32_bf16 v[96:99], v[196:199], v[212:215], v[96:99]
	v_mfma_f32_16x16x32_bf16 v[84:87], v[188:191], v[220:223], v[84:87]
	v_mfma_f32_16x16x32_bf16 v[80:83], v[196:199], v[220:223], v[80:83]
	v_mfma_f32_16x16x32_bf16 v[68:71], v[188:191], v[228:231], v[68:71]
	v_mfma_f32_16x16x32_bf16 v[64:67], v[196:199], v[228:231], v[64:67]
	s_setprio 1
	s_barrier
	s_add_i32 s69, s56, s39
	v_lshl_add_u64 v[162:163], s[8:9], 0, v[130:131]
	s_mov_b32 m0, s69
	ds_read_b128 v[200:203], v170 offset:16384
	ds_read_b128 v[204:207], v170 offset:17408
	ds_read_b128 v[208:211], v170 offset:18432
	ds_read_b128 v[212:215], v170 offset:19456
	ds_read_b128 v[216:219], v170 offset:20480
	ds_read_b128 v[220:223], v170 offset:21504
	ds_read_b128 v[224:227], v170 offset:22528
	ds_read_b128 v[228:231], v170 offset:23552
	global_load_lds_dwordx4 v[162:163], off
	s_add_i32 m0, s69, 0x2000
	s_add_u32 s70, s8, 0x40000
	v_lshl_add_u64 v[232:233], s[8:9], 0, v[134:135]
	s_addc_u32 s71, s9, 0
	s_add_i32 s69, s57, s39
	global_load_lds_dwordx4 v[232:233], off
	v_lshl_add_u64 v[234:235], s[70:71], 0, v[130:131]
	s_mov_b32 m0, s69
	v_lshl_add_u64 v[236:237], s[10:11], 0, v[132:133]
	global_load_lds_dwordx4 v[234:235], off
	v_lshl_add_u64 v[234:235], s[70:71], 0, v[134:135]
	s_add_i32 m0, s69, 0x2000
	s_nop 0
	global_load_lds_dwordx4 v[234:235], off
	v_lshl_add_u64 v[234:235], s[10:11], 0, v[128:129]
	s_mov_b32 m0, s40
	s_nop 0
	global_load_lds_dwordx4 v[234:235], off
	s_mov_b32 m0, s41
	s_nop 0
	global_load_lds_dwordx4 v[236:237], off
	s_waitcnt vmcnt(8)
	s_waitcnt lgkmcnt(0)
	s_barrier
; #define PG8_STAGE(bufoff, gbase, voff) do { _Pragma("unroll") for (int _i = 0; _i < 2; ++_i) \
;         __builtin_amdgcn_global_load_lds((const unsigned*)((const char*)(gbase) + (voff)[_i]), (PG8_LAS unsigned*)(lds + (bufoff) + ldsw + _i * 8192), 16, 0, 0); } while (0)
; #define PG8_LDA(dst, b, h) do { _Pragma("unroll") for (int m = 0; m < 4; ++m) _Pragma("unroll") for (int k = 0; k < 2; ++k) dst[m][k] = *(const PG8_LAS bf16x8*)(lds + PG8_SA(b, h) + aoff + m * 2048 + k * 1024); } while (0)
; #define PG8_LDB(dst, b, h) do { _Pragma("unroll") for (int n = 0; n < 2; ++n) _Pragma("unroll") for (int k = 0; k < 2; ++k) dst[n][k] = *(const PG8_LAS bf16x8*)(lds + PG8_SB(b, h) + boff + n * 2048 + k * 1024); } while (0)
; #define PG8_MMA(ai, bj, At, Bt) do { __builtin_amdgcn_s_setprio(1); _Pragma("unroll") for (int m = 0; m < 4; ++m) _Pragma("unroll") for (int n = 0; n < 2; ++n) _Pragma("unroll") for (int k = 0; k < 2; ++k) \
;         acc[ai][bj][m][n] = __builtin_amdgcn_mfma_f32_16x16x32_bf16(Bt[n][k], At[m][k], acc[ai][bj][m][n], 0, 0, 0); __builtin_amdgcn_s_setprio(0); } while (0)
; #define PG8_WAIT_V(n) asm volatile("s_waitcnt vmcnt(" #n ")" ::: "memory")
; #define PG8_WAIT_L(n) asm volatile("s_waitcnt lgkmcnt(" #n ")" ::: "memory")
; #define PG8_BAR __builtin_amdgcn_s_barrier()
; #define PG8_SCHED __builtin_amdgcn_sched_barrier(0)
; template <class Epi, class Sched, bool ALIGN_EPI = false, bool SP2 = false>
; __device__ __forceinline__ void gemm_phase(PG8_LAS unsigned char* lds, const Gemm g, const Sched& S, const Epi& E) {
;     ...
;             PG8_WAIT_V(8); PG8_WAIT_L(0); PG8_BAR; PG8_MMA(1, 0, At, B0); PG8_MMA(1, 1, At, B1); PG8_BAR; PG8_SCHED;
;             PG8_LDB(B0, 1, 0); PG8_LDB(B1, 1, 1); PG8_SCHED; PG8_LDA(At, 1, 0); PG8_STAGE(PG8_SA(0, 1), a2 + hstep, voffA);
;             PG8_WAIT_V(8); PG8_WAIT_L(0); PG8_BAR; PG8_MMA(0, 0, At, B0); PG8_MMA(0, 1, At, B1); PG8_BAR; PG8_SCHED;
	s_setprio 0
	s_waitcnt lgkmcnt(0)
	v_mfma_f32_16x16x32_bf16 v[60:63], v[156:159], v[200:203], v[60:63]
	v_mfma_f32_16x16x32_bf16 v[56:59], v[176:179], v[200:203], v[56:59]
	v_mfma_f32_16x16x32_bf16 v[44:47], v[156:159], v[208:211], v[44:47]
	v_mfma_f32_16x16x32_bf16 v[40:43], v[176:179], v[208:211], v[40:43]
	v_mfma_f32_16x16x32_bf16 v[28:31], v[156:159], v[216:219], v[28:31]
	v_mfma_f32_16x16x32_bf16 v[24:27], v[176:179], v[216:219], v[24:27]
	v_mfma_f32_16x16x32_bf16 v[12:15], v[156:159], v[224:227], v[12:15]
	v_mfma_f32_16x16x32_bf16 v[8:11], v[176:179], v[224:227], v[8:11]
	v_mfma_f32_16x16x32_bf16 v[60:63], v[172:175], v[204:207], v[60:63]
	v_mfma_f32_16x16x32_bf16 v[56:59], v[180:183], v[204:207], v[56:59]
	v_mfma_f32_16x16x32_bf16 v[44:47], v[172:175], v[212:215], v[44:47]
	v_mfma_f32_16x16x32_bf16 v[40:43], v[180:183], v[212:215], v[40:43]
	v_mfma_f32_16x16x32_bf16 v[28:31], v[172:175], v[220:223], v[28:31]
	v_mfma_f32_16x16x32_bf16 v[24:27], v[180:183], v[220:223], v[24:27]
	v_mfma_f32_16x16x32_bf16 v[12:15], v[172:175], v[228:231], v[12:15]
	v_mfma_f32_16x16x32_bf16 v[8:11], v[180:183], v[228:231], v[8:11]
	s_setprio 1
	s_setprio 0
	v_mfma_f32_16x16x32_bf16 v[52:55], v[184:187], v[200:203], v[52:55]
	v_mfma_f32_16x16x32_bf16 v[48:51], v[192:195], v[200:203], v[48:51]
	v_mfma_f32_16x16x32_bf16 v[36:39], v[184:187], v[208:211], v[36:39]
	v_mfma_f32_16x16x32_bf16 v[32:35], v[192:195], v[208:211], v[32:35]
	v_mfma_f32_16x16x32_bf16 v[20:23], v[184:187], v[216:219], v[20:23]
	v_mfma_f32_16x16x32_bf16 v[16:19], v[192:195], v[216:219], v[16:19]
	v_mfma_f32_16x16x32_bf16 v[4:7], v[184:187], v[224:227], v[4:7]
	v_mfma_f32_16x16x32_bf16 v[0:3], v[192:195], v[224:227], v[0:3]
	v_mfma_f32_16x16x32_bf16 v[52:55], v[188:191], v[204:207], v[52:55]
	v_mfma_f32_16x16x32_bf16 v[48:51], v[196:199], v[204:207], v[48:51]
	v_mfma_f32_16x16x32_bf16 v[36:39], v[188:191], v[212:215], v[36:39]
	v_mfma_f32_16x16x32_bf16 v[32:35], v[196:199], v[212:215], v[32:35]
	v_mfma_f32_16x16x32_bf16 v[20:23], v[188:191], v[220:223], v[20:23]
	v_mfma_f32_16x16x32_bf16 v[16:19], v[196:199], v[220:223], v[16:19]
	v_mfma_f32_16x16x32_bf16 v[4:7], v[188:191], v[228:231], v[4:7]
	v_mfma_f32_16x16x32_bf16 v[0:3], v[196:199], v[228:231], v[0:3]
	s_setprio 1
	s_barrier
	s_add_i32 s69, 0, 0x18000
	v_add_u32_e32 v160, s69, v139
	s_add_i32 s70, 0, 0x1c000
	ds_read_b128 v[156:159], v160
	ds_read_b128 v[172:175], v160 offset:1024
	ds_read_b128 v[176:179], v160 offset:2048
	ds_read_b128 v[180:183], v160 offset:3072
	v_add_u32_e32 v160, s70, v139
	ds_read_b128 v[184:187], v160
	ds_read_b128 v[188:191], v160 offset:1024
	ds_read_b128 v[192:195], v160 offset:2048
	ds_read_b128 v[196:199], v160 offset:3072
	s_add_u32 s10, s10, 0x40000
	s_addc_u32 s11, s11, 0
	s_mov_b32 m0, s42
	v_lshl_add_u64 v[238:239], s[10:11], 0, v[128:129]
	ds_read_b128 v[200:203], v170 offset:32768
	ds_read_b128 v[204:207], v170 offset:33792
	ds_read_b128 v[208:211], v170 offset:34816
	ds_read_b128 v[212:215], v170 offset:35840
	ds_read_b128 v[216:219], v170 offset:36864
	ds_read_b128 v[220:223], v170 offset:37888
	ds_read_b128 v[224:227], v170 offset:38912
	ds_read_b128 v[228:231], v170 offset:39936
	global_load_lds_dwordx4 v[238:239], off
	v_lshl_add_u64 v[238:239], s[10:11], 0, v[132:133]
	s_mov_b32 m0, s43
	s_nop 0
	global_load_lds_dwordx4 v[238:239], off
	s_waitcnt vmcnt(8)
	s_waitcnt lgkmcnt(0)
	s_barrier
	s_setprio 0
	s_waitcnt lgkmcnt(0)
	v_mfma_f32_16x16x32_bf16 v[124:127], v[156:159], v[200:203], v[124:127]
	v_mfma_f32_16x16x32_bf16 v[120:123], v[176:179], v[200:203], v[120:123]
	v_mfma_f32_16x16x32_bf16 v[108:111], v[156:159], v[208:211], v[108:111]
	v_mfma_f32_16x16x32_bf16 v[104:107], v[176:179], v[208:211], v[104:107]
	v_mfma_f32_16x16x32_bf16 v[92:95], v[156:159], v[216:219], v[92:95]
	v_mfma_f32_16x16x32_bf16 v[88:91], v[176:179], v[216:219], v[88:91]
	v_mfma_f32_16x16x32_bf16 v[76:79], v[156:159], v[224:227], v[76:79]
	v_mfma_f32_16x16x32_bf16 v[72:75], v[176:179], v[224:227], v[72:75]
	v_mfma_f32_16x16x32_bf16 v[124:127], v[172:175], v[204:207], v[124:127]
	v_mfma_f32_16x16x32_bf16 v[120:123], v[180:183], v[204:207], v[120:123]
	v_mfma_f32_16x16x32_bf16 v[108:111], v[172:175], v[212:215], v[108:111]
	v_mfma_f32_16x16x32_bf16 v[104:107], v[180:183], v[212:215], v[104:107]
	v_mfma_f32_16x16x32_bf16 v[92:95], v[172:175], v[220:223], v[92:95]
	v_mfma_f32_16x16x32_bf16 v[88:91], v[180:183], v[220:223], v[88:91]
	v_mfma_f32_16x16x32_bf16 v[76:79], v[172:175], v[228:231], v[76:79]
	v_mfma_f32_16x16x32_bf16 v[72:75], v[180:183], v[228:231], v[72:75]
	s_setprio 1
	s_setprio 0
	v_mfma_f32_16x16x32_bf16 v[116:119], v[184:187], v[200:203], v[116:119]
	v_mfma_f32_16x16x32_bf16 v[112:115], v[192:195], v[200:203], v[112:115]
	v_mfma_f32_16x16x32_bf16 v[100:103], v[184:187], v[208:211], v[100:103]
	v_mfma_f32_16x16x32_bf16 v[96:99], v[192:195], v[208:211], v[96:99]
	v_mfma_f32_16x16x32_bf16 v[84:87], v[184:187], v[216:219], v[84:87]
	v_mfma_f32_16x16x32_bf16 v[80:83], v[192:195], v[216:219], v[80:83]
	v_mfma_f32_16x16x32_bf16 v[68:71], v[184:187], v[224:227], v[68:71]
	v_mfma_f32_16x16x32_bf16 v[64:67], v[192:195], v[224:227], v[64:67]
	v_mfma_f32_16x16x32_bf16 v[116:119], v[188:191], v[204:207], v[116:119]
	v_mfma_f32_16x16x32_bf16 v[112:115], v[196:199], v[204:207], v[112:115]
	v_mfma_f32_16x16x32_bf16 v[100:103], v[188:191], v[212:215], v[100:103]
	v_mfma_f32_16x16x32_bf16 v[96:99], v[196:199], v[212:215], v[96:99]
	v_mfma_f32_16x16x32_bf16 v[84:87], v[188:191], v[220:223], v[84:87]
	v_mfma_f32_16x16x32_bf16 v[80:83], v[196:199], v[220:223], v[80:83]
	v_mfma_f32_16x16x32_bf16 v[68:71], v[188:191], v[228:231], v[68:71]
	v_mfma_f32_16x16x32_bf16 v[64:67], v[196:199], v[228:231], v[64:67]
	s_setprio 1
	s_barrier
; #define PG8_STAGE(bufoff, gbase, voff) do { _Pragma("unroll") for (int _i = 0; _i < 2; ++_i) \
;         __builtin_amdgcn_global_load_lds((const unsigned*)((const char*)(gbase) + (voff)[_i]), (PG8_LAS unsigned*)(lds + (bufoff) + ldsw + _i * 8192), 16, 0, 0); } while (0)
; #define PG8_LDA(dst, b, h) do { _Pragma("unroll") for (int m = 0; m < 4; ++m) _Pragma("unroll") for (int k = 0; k < 2; ++k) dst[m][k] = *(const PG8_LAS bf16x8*)(lds + PG8_SA(b, h) + aoff + m * 2048 + k * 1024); } while (0)
; #define PG8_MMA(ai, bj, At, Bt) do { __builtin_amdgcn_s_setprio(1); _Pragma("unroll") for (int m = 0; m < 4; ++m) _Pragma("unroll") for (int n = 0; n < 2; ++n) _Pragma("unroll") for (int k = 0; k < 2; ++k) \
;         acc[ai][bj][m][n] = __builtin_amdgcn_mfma_f32_16x16x32_bf16(Bt[n][k], At[m][k], acc[ai][bj][m][n], 0, 0, 0); __builtin_amdgcn_s_setprio(0); } while (0)
; #define PG8_WAIT_V(n) asm volatile("s_waitcnt vmcnt(" #n ")" ::: "memory")
; #define PG8_WAIT_L(n) asm volatile("s_waitcnt lgkmcnt(" #n ")" ::: "memory")
; #define PG8_BAR __builtin_amdgcn_s_barrier()
; #define PG8_SCHED __builtin_amdgcn_sched_barrier(0)
; template <class Epi, class Sched, bool ALIGN_EPI = false, bool SP2 = false>
; __device__ __forceinline__ void gemm_phase(PG8_LAS unsigned char* lds, const Gemm g, const Sched& S, const Epi& E) {
;     ...
;         for (int t = 0; t < nt; t += 2) {
;             const bool last = (t == nt - 2);
;     ...
;             PG8_LDA(At, 1, 1); PG8_STAGE(PG8_SB(1, 0), b3, voffB); PG8_STAGE(PG8_SB(1, 1), b3 + hstep, voffB); PG8_STAGE(PG8_SA(1, 0), a3, voffA);
;             PG8_WAIT_V(8); PG8_WAIT_L(0); PG8_BAR; PG8_MMA(1, 0, At, B0); PG8_MMA(1, 1, At, B1); PG8_BAR; PG8_SCHED;
	s_add_i32 s10, s69, s39
	v_lshl_add_u64 v[162:163], v[162:163], 0, s[18:19]
	s_mov_b32 m0, s10
	ds_read_b128 v[200:203], v170 offset:49152
	ds_read_b128 v[204:207], v170 offset:50176
	ds_read_b128 v[208:211], v170 offset:51200
	ds_read_b128 v[212:215], v170 offset:52224
	ds_read_b128 v[216:219], v170 offset:53248
	ds_read_b128 v[220:223], v170 offset:54272
	ds_read_b128 v[224:227], v170 offset:55296
	ds_read_b128 v[228:231], v170 offset:56320
	global_load_lds_dwordx4 v[162:163], off
	s_add_i32 m0, s10, 0x2000
	s_add_u32 s8, s8, 0x40080
	v_lshl_add_u64 v[162:163], v[232:233], 0, s[18:19]
	s_addc_u32 s9, s9, 0
	s_add_i32 s10, s70, s39
	global_load_lds_dwordx4 v[162:163], off
	v_lshl_add_u64 v[162:163], s[8:9], 0, v[130:131]
	s_mov_b32 m0, s10
	s_nop 0
	global_load_lds_dwordx4 v[162:163], off
	v_lshl_add_u64 v[162:163], s[8:9], 0, v[134:135]
	s_add_i32 m0, s10, 0x2000
	s_nop 0
	global_load_lds_dwordx4 v[162:163], off
	v_lshl_add_u64 v[162:163], v[234:235], 0, s[18:19]
	s_mov_b32 m0, s45
	s_nop 0
	global_load_lds_dwordx4 v[162:163], off
	v_lshl_add_u64 v[162:163], v[236:237], 0, s[18:19]
	s_mov_b32 m0, s50
	s_nop 0
	global_load_lds_dwordx4 v[162:163], off
	s_waitcnt vmcnt(8)
	s_waitcnt lgkmcnt(0)
	s_barrier
	s_setprio 0
	s_waitcnt lgkmcnt(0)
	v_mfma_f32_16x16x32_bf16 v[60:63], v[156:159], v[200:203], v[60:63]
	v_mfma_f32_16x16x32_bf16 v[56:59], v[176:179], v[200:203], v[56:59]
	v_mfma_f32_16x16x32_bf16 v[44:47], v[156:159], v[208:211], v[44:47]
	v_mfma_f32_16x16x32_bf16 v[40:43], v[176:179], v[208:211], v[40:43]
	v_mfma_f32_16x16x32_bf16 v[28:31], v[156:159], v[216:219], v[28:31]
	v_mfma_f32_16x16x32_bf16 v[24:27], v[176:179], v[216:219], v[24:27]
	v_mfma_f32_16x16x32_bf16 v[12:15], v[156:159], v[224:227], v[12:15]
	v_mfma_f32_16x16x32_bf16 v[8:11], v[176:179], v[224:227], v[8:11]
	v_mfma_f32_16x16x32_bf16 v[60:63], v[172:175], v[204:207], v[60:63]
	v_mfma_f32_16x16x32_bf16 v[56:59], v[180:183], v[204:207], v[56:59]
	v_mfma_f32_16x16x32_bf16 v[44:47], v[172:175], v[212:215], v[44:47]
	v_mfma_f32_16x16x32_bf16 v[40:43], v[180:183], v[212:215], v[40:43]
	v_mfma_f32_16x16x32_bf16 v[28:31], v[172:175], v[220:223], v[28:31]
	v_mfma_f32_16x16x32_bf16 v[24:27], v[180:183], v[220:223], v[24:27]
	v_mfma_f32_16x16x32_bf16 v[12:15], v[172:175], v[228:231], v[12:15]
	v_mfma_f32_16x16x32_bf16 v[8:11], v[180:183], v[228:231], v[8:11]
	s_setprio 1
	s_setprio 0
	v_mfma_f32_16x16x32_bf16 v[52:55], v[184:187], v[200:203], v[52:55]
	v_mfma_f32_16x16x32_bf16 v[48:51], v[192:195], v[200:203], v[48:51]
	v_mfma_f32_16x16x32_bf16 v[36:39], v[184:187], v[208:211], v[36:39]
	v_mfma_f32_16x16x32_bf16 v[32:35], v[192:195], v[208:211], v[32:35]
	v_mfma_f32_16x16x32_bf16 v[20:23], v[184:187], v[216:219], v[20:23]
	v_mfma_f32_16x16x32_bf16 v[16:19], v[192:195], v[216:219], v[16:19]
	v_mfma_f32_16x16x32_bf16 v[4:7], v[184:187], v[224:227], v[4:7]
	v_mfma_f32_16x16x32_bf16 v[0:3], v[192:195], v[224:227], v[0:3]
	v_mfma_f32_16x16x32_bf16 v[52:55], v[188:191], v[204:207], v[52:55]
	v_mfma_f32_16x16x32_bf16 v[48:51], v[196:199], v[204:207], v[48:51]
	v_mfma_f32_16x16x32_bf16 v[36:39], v[188:191], v[212:215], v[36:39]
	v_mfma_f32_16x16x32_bf16 v[32:35], v[196:199], v[212:215], v[32:35]
	v_mfma_f32_16x16x32_bf16 v[20:23], v[188:191], v[220:223], v[20:23]
	v_mfma_f32_16x16x32_bf16 v[16:19], v[196:199], v[220:223], v[16:19]
	v_mfma_f32_16x16x32_bf16 v[4:7], v[188:191], v[228:231], v[4:7]
	v_mfma_f32_16x16x32_bf16 v[0:3], v[196:199], v[228:231], v[0:3]
	s_setprio 1
	s_barrier
	s_add_i32 s68, s68, 2
	s_add_u32 s6, s6, 0x100
	s_addc_u32 s7, s7, 0
	s_add_u32 s52, s52, 0x100
	s_addc_u32 s53, s53, 0
	s_cmp_gt_u32 s68, 13
	s_cbranch_scc0 .LBB0_1295
	s_and_b64 vcc, exec, s[20:21]
	s_cbranch_vccz .LBB0_1298
	s_barrier

; #define PG8_STAGE(bufoff, gbase, voff) do { _Pragma("unroll") for (int _i = 0; _i < 2; ++_i) \
;         __builtin_amdgcn_global_load_lds((const unsigned*)((const char*)(gbase) + (voff)[_i]), (PG8_LAS unsigned*)(lds + (bufoff) + ldsw + _i * 8192), 16, 0, 0); } while (0)
; #define PG8_LDA(dst, b, h) do { _Pragma("unroll") for (int m = 0; m < 4; ++m) _Pragma("unroll") for (int k = 0; k < 2; ++k) dst[m][k] = *(const PG8_LAS bf16x8*)(lds + PG8_SA(b, h) + aoff + m * 2048 + k * 1024); } while (0)
; #define PG8_LDB(dst, b, h) do { _Pragma("unroll") for (int n = 0; n < 2; ++n) _Pragma("unroll") for (int k = 0; k < 2; ++k) dst[n][k] = *(const PG8_LAS bf16x8*)(lds + PG8_SB(b, h) + boff + n * 2048 + k * 1024); } while (0)
; #define PG8_MMA(ai, bj, At, Bt) do { __builtin_amdgcn_s_setprio(1); _Pragma("unroll") for (int m = 0; m < 4; ++m) _Pragma("unroll") for (int n = 0; n < 2; ++n) _Pragma("unroll") for (int k = 0; k < 2; ++k) \
;         acc[ai][bj][m][n] = __builtin_amdgcn_mfma_f32_16x16x32_bf16(Bt[n][k], At[m][k], acc[ai][bj][m][n], 0, 0, 0); __builtin_amdgcn_s_setprio(0); } while (0)
; #define PG8_WAIT_V(n) asm volatile("s_waitcnt vmcnt(" #n ")" ::: "memory")
; #define PG8_WAIT_L(n) asm volatile("s_waitcnt lgkmcnt(" #n ")" ::: "memory")
; #define PG8_BAR __builtin_amdgcn_s_barrier()
; #define PG8_SCHED __builtin_amdgcn_sched_barrier(0)
; template <class Epi, class Sched, bool ALIGN_EPI = false, bool SP2 = false>
; __device__ __forceinline__ void gemm_phase(PG8_LAS unsigned char* lds, const Gemm g, const Sched& S, const Epi& E) {
;     ...
;             const bool last = (t == nt - 2);
;             const char* a1 = cA + (size_t)(t + 1) * kstep;
;             const char* a2 = last ? nA : cA + (size_t)(t + 2) * kstep; const char* b2 = last ? nB : cB + (size_t)(t + 2) * kstep;
;     ...
;             PG8_LDB(B0, 0, 0); PG8_LDB(B1, 0, 1); PG8_SCHED; PG8_LDA(At, 0, 0); PG8_STAGE(PG8_SA(1, 1), a1 + hstep, voffA);
;             PG8_WAIT_V(8); PG8_WAIT_L(0); PG8_BAR; PG8_MMA(0, 0, At, B0); PG8_MMA(0, 1, At, B1); PG8_BAR; PG8_SCHED;
;             PG8_LDA(At, 0, 1); PG8_STAGE(PG8_SB(0, 0), b2, voffB); PG8_STAGE(PG8_SB(0, 1), b2 + hstep, voffB); PG8_STAGE(PG8_SA(0, 0), a2, voffA);
.LBB0_1319:
	ds_read_b128 v[144:147], v149
	ds_read_b128 v[152:155], v149 offset:1024
	ds_read_b128 v[160:163], v149 offset:2048
	ds_read_b128 v[164:167], v149 offset:3072
	ds_read_b128 v[168:171], v151
	ds_read_b128 v[172:175], v151 offset:1024
	ds_read_b128 v[176:179], v151 offset:2048
	ds_read_b128 v[180:183], v151 offset:3072
	s_add_u32 s34, s30, 0xfffe0080
	s_addc_u32 s35, s31, -1
	s_cmp_eq_u32 s69, 4
	s_cselect_b32 s37, s23, s35
	s_cselect_b32 s36, s53, s34
	s_cselect_b32 s35, s21, s68
	s_cselect_b32 s34, s62, s63
	v_lshl_add_u64 v[216:217], s[30:31], 0, v[128:129]
	s_add_i32 m0, s29, 0xc000
	ds_read_b128 v[184:187], v159
	ds_read_b128 v[188:191], v159 offset:1024
	ds_read_b128 v[192:195], v159 offset:2048
	ds_read_b128 v[196:199], v159 offset:3072
	ds_read_b128 v[200:203], v159 offset:4096
	ds_read_b128 v[204:207], v159 offset:5120
	ds_read_b128 v[208:211], v159 offset:6144
	ds_read_b128 v[212:215], v159 offset:7168
	global_load_lds_dwordx4 v[216:217], off
	v_lshl_add_u64 v[216:217], s[30:31], 0, v[130:131]
	s_add_i32 m0, s29, 0xe000
	s_nop 0
	global_load_lds_dwordx4 v[216:217], off
	s_waitcnt vmcnt(8)
	s_waitcnt lgkmcnt(0)
	s_barrier
	s_setprio 0
	s_waitcnt lgkmcnt(0)
	v_mfma_f32_16x16x32_bf16 v[124:127], v[144:147], v[184:187], v[124:127]
	v_mfma_f32_16x16x32_bf16 v[120:123], v[160:163], v[184:187], v[120:123]
	v_mfma_f32_16x16x32_bf16 v[108:111], v[144:147], v[192:195], v[108:111]
	v_mfma_f32_16x16x32_bf16 v[104:107], v[160:163], v[192:195], v[104:107]
	v_mfma_f32_16x16x32_bf16 v[92:95], v[144:147], v[200:203], v[92:95]
	v_mfma_f32_16x16x32_bf16 v[88:91], v[160:163], v[200:203], v[88:91]
	v_mfma_f32_16x16x32_bf16 v[76:79], v[144:147], v[208:211], v[76:79]
	v_mfma_f32_16x16x32_bf16 v[72:75], v[160:163], v[208:211], v[72:75]
	v_mfma_f32_16x16x32_bf16 v[124:127], v[152:155], v[188:191], v[124:127]
	v_mfma_f32_16x16x32_bf16 v[120:123], v[164:167], v[188:191], v[120:123]
	v_mfma_f32_16x16x32_bf16 v[108:111], v[152:155], v[196:199], v[108:111]
	v_mfma_f32_16x16x32_bf16 v[104:107], v[164:167], v[196:199], v[104:107]
	v_mfma_f32_16x16x32_bf16 v[92:95], v[152:155], v[204:207], v[92:95]
	v_mfma_f32_16x16x32_bf16 v[88:91], v[164:167], v[204:207], v[88:91]
	v_mfma_f32_16x16x32_bf16 v[76:79], v[152:155], v[212:215], v[76:79]
	v_mfma_f32_16x16x32_bf16 v[72:75], v[164:167], v[212:215], v[72:75]
	s_setprio 1
	s_setprio 0
	v_mfma_f32_16x16x32_bf16 v[116:119], v[168:171], v[184:187], v[116:119]
	v_mfma_f32_16x16x32_bf16 v[112:115], v[176:179], v[184:187], v[112:115]
	v_mfma_f32_16x16x32_bf16 v[100:103], v[168:171], v[192:195], v[100:103]
	v_mfma_f32_16x16x32_bf16 v[96:99], v[176:179], v[192:195], v[96:99]
	v_mfma_f32_16x16x32_bf16 v[84:87], v[168:171], v[200:203], v[84:87]
	v_mfma_f32_16x16x32_bf16 v[80:83], v[176:179], v[200:203], v[80:83]
	v_mfma_f32_16x16x32_bf16 v[68:71], v[168:171], v[208:211], v[68:71]
	v_mfma_f32_16x16x32_bf16 v[64:67], v[176:179], v[208:211], v[64:67]
	v_mfma_f32_16x16x32_bf16 v[116:119], v[172:175], v[188:191], v[116:119]
	v_mfma_f32_16x16x32_bf16 v[112:115], v[180:183], v[188:191], v[112:115]
	v_mfma_f32_16x16x32_bf16 v[100:103], v[172:175], v[196:199], v[100:103]
	v_mfma_f32_16x16x32_bf16 v[96:99], v[180:183], v[196:199], v[96:99]
	v_mfma_f32_16x16x32_bf16 v[84:87], v[172:175], v[204:207], v[84:87]
	v_mfma_f32_16x16x32_bf16 v[80:83], v[180:183], v[204:207], v[80:83]
	v_mfma_f32_16x16x32_bf16 v[68:71], v[172:175], v[212:215], v[68:71]
	v_mfma_f32_16x16x32_bf16 v[64:67], v[180:183], v[212:215], v[64:67]
	s_setprio 1
	s_barrier
	s_add_i32 s70, s51, s39
	v_lshl_add_u64 v[216:217], s[34:35], 0, v[138:139]
	s_mov_b32 m0, s70
	ds_read_b128 v[184:187], v159 offset:16384
	ds_read_b128 v[188:191], v159 offset:17408
	ds_read_b128 v[192:195], v159 offset:18432
	ds_read_b128 v[196:199], v159 offset:19456
	ds_read_b128 v[200:203], v159 offset:20480
	ds_read_b128 v[204:207], v159 offset:21504
	ds_read_b128 v[208:211], v159 offset:22528
	ds_read_b128 v[212:215], v159 offset:23552
	global_load_lds_dwordx4 v[216:217], off
	s_add_i32 m0, s70, 0x2000
	s_add_u32 s70, s34, 0x20000
	v_lshl_add_u64 v[218:219], s[34:35], 0, v[142:143]
	s_addc_u32 s71, s35, 0
	s_add_i32 s72, s56, s39
	global_load_lds_dwordx4 v[218:219], off
	v_lshl_add_u64 v[220:221], s[70:71], 0, v[138:139]
	s_mov_b32 m0, s72
	v_lshl_add_u64 v[222:223], s[36:37], 0, v[140:141]
	global_load_lds_dwordx4 v[220:221], off
	v_lshl_add_u64 v[220:221], s[70:71], 0, v[142:143]
	s_add_i32 m0, s72, 0x2000
	s_nop 0
	global_load_lds_dwordx4 v[220:221], off
	v_lshl_add_u64 v[220:221], s[36:37], 0, v[136:137]
	s_mov_b32 m0, s29
	s_nop 0
	global_load_lds_dwordx4 v[220:221], off
	s_mov_b32 m0, s40
	s_nop 0
	global_load_lds_dwordx4 v[222:223], off
	s_waitcnt vmcnt(8)
	s_waitcnt lgkmcnt(0)
	s_barrier
; #define PG8_STAGE(bufoff, gbase, voff) do { _Pragma("unroll") for (int _i = 0; _i < 2; ++_i) \
;         __builtin_amdgcn_global_load_lds((const unsigned*)((const char*)(gbase) + (voff)[_i]), (PG8_LAS unsigned*)(lds + (bufoff) + ldsw + _i * 8192), 16, 0, 0); } while (0)
; #define PG8_LDA(dst, b, h) do { _Pragma("unroll") for (int m = 0; m < 4; ++m) _Pragma("unroll") for (int k = 0; k < 2; ++k) dst[m][k] = *(const PG8_LAS bf16x8*)(lds + PG8_SA(b, h) + aoff + m * 2048 + k * 1024); } while (0)
; #define PG8_LDB(dst, b, h) do { _Pragma("unroll") for (int n = 0; n < 2; ++n) _Pragma("unroll") for (int k = 0; k < 2; ++k) dst[n][k] = *(const PG8_LAS bf16x8*)(lds + PG8_SB(b, h) + boff + n * 2048 + k * 1024); } while (0)
; #define PG8_MMA(ai, bj, At, Bt) do { __builtin_amdgcn_s_setprio(1); _Pragma("unroll") for (int m = 0; m < 4; ++m) _Pragma("unroll") for (int n = 0; n < 2; ++n) _Pragma("unroll") for (int k = 0; k < 2; ++k) \
;         acc[ai][bj][m][n] = __builtin_amdgcn_mfma_f32_16x16x32_bf16(Bt[n][k], At[m][k], acc[ai][bj][m][n], 0, 0, 0); __builtin_amdgcn_s_setprio(0); } while (0)
; #define PG8_WAIT_V(n) asm volatile("s_waitcnt vmcnt(" #n ")" ::: "memory")
; #define PG8_WAIT_L(n) asm volatile("s_waitcnt lgkmcnt(" #n ")" ::: "memory")
; #define PG8_BAR __builtin_amdgcn_s_barrier()
; #define PG8_SCHED __builtin_amdgcn_sched_barrier(0)
; template <class Epi, class Sched, bool ALIGN_EPI = false, bool SP2 = false>
; __device__ __forceinline__ void gemm_phase(PG8_LAS unsigned char* lds, const Gemm g, const Sched& S, const Epi& E) {
;     ...
;             PG8_WAIT_V(8); PG8_WAIT_L(0); PG8_BAR; PG8_MMA(1, 0, At, B0); PG8_MMA(1, 1, At, B1); PG8_BAR; PG8_SCHED;
;             PG8_LDB(B0, 1, 0); PG8_LDB(B1, 1, 1); PG8_SCHED; PG8_LDA(At, 1, 0); PG8_STAGE(PG8_SA(0, 1), a2 + hstep, voffA);
;             PG8_WAIT_V(8); PG8_WAIT_L(0); PG8_BAR; PG8_MMA(0, 0, At, B0); PG8_MMA(0, 1, At, B1); PG8_BAR; PG8_SCHED;
	s_setprio 0
	s_waitcnt lgkmcnt(0)
	v_mfma_f32_16x16x32_bf16 v[60:63], v[144:147], v[184:187], v[60:63]
	v_mfma_f32_16x16x32_bf16 v[56:59], v[160:163], v[184:187], v[56:59]
	v_mfma_f32_16x16x32_bf16 v[44:47], v[144:147], v[192:195], v[44:47]
	v_mfma_f32_16x16x32_bf16 v[40:43], v[160:163], v[192:195], v[40:43]
	v_mfma_f32_16x16x32_bf16 v[28:31], v[144:147], v[200:203], v[28:31]
	v_mfma_f32_16x16x32_bf16 v[24:27], v[160:163], v[200:203], v[24:27]
	v_mfma_f32_16x16x32_bf16 v[12:15], v[144:147], v[208:211], v[12:15]
	v_mfma_f32_16x16x32_bf16 v[8:11], v[160:163], v[208:211], v[8:11]
	v_mfma_f32_16x16x32_bf16 v[60:63], v[152:155], v[188:191], v[60:63]
	v_mfma_f32_16x16x32_bf16 v[56:59], v[164:167], v[188:191], v[56:59]
	v_mfma_f32_16x16x32_bf16 v[44:47], v[152:155], v[196:199], v[44:47]
	v_mfma_f32_16x16x32_bf16 v[40:43], v[164:167], v[196:199], v[40:43]
	v_mfma_f32_16x16x32_bf16 v[28:31], v[152:155], v[204:207], v[28:31]
	v_mfma_f32_16x16x32_bf16 v[24:27], v[164:167], v[204:207], v[24:27]
	v_mfma_f32_16x16x32_bf16 v[12:15], v[152:155], v[212:215], v[12:15]
	v_mfma_f32_16x16x32_bf16 v[8:11], v[164:167], v[212:215], v[8:11]
	s_setprio 1
	s_setprio 0
	v_mfma_f32_16x16x32_bf16 v[52:55], v[168:171], v[184:187], v[52:55]
	v_mfma_f32_16x16x32_bf16 v[48:51], v[176:179], v[184:187], v[48:51]
	v_mfma_f32_16x16x32_bf16 v[36:39], v[168:171], v[192:195], v[36:39]
	v_mfma_f32_16x16x32_bf16 v[32:35], v[176:179], v[192:195], v[32:35]
	v_mfma_f32_16x16x32_bf16 v[20:23], v[168:171], v[200:203], v[20:23]
	v_mfma_f32_16x16x32_bf16 v[16:19], v[176:179], v[200:203], v[16:19]
	v_mfma_f32_16x16x32_bf16 v[4:7], v[168:171], v[208:211], v[4:7]
	v_mfma_f32_16x16x32_bf16 v[0:3], v[176:179], v[208:211], v[0:3]
	v_mfma_f32_16x16x32_bf16 v[52:55], v[172:175], v[188:191], v[52:55]
	v_mfma_f32_16x16x32_bf16 v[48:51], v[180:183], v[188:191], v[48:51]
	v_mfma_f32_16x16x32_bf16 v[36:39], v[172:175], v[196:199], v[36:39]
	v_mfma_f32_16x16x32_bf16 v[32:35], v[180:183], v[196:199], v[32:35]
	v_mfma_f32_16x16x32_bf16 v[20:23], v[172:175], v[204:207], v[20:23]
	v_mfma_f32_16x16x32_bf16 v[16:19], v[180:183], v[204:207], v[16:19]
	v_mfma_f32_16x16x32_bf16 v[4:7], v[172:175], v[212:215], v[4:7]
	v_mfma_f32_16x16x32_bf16 v[0:3], v[180:183], v[212:215], v[0:3]
	s_setprio 1
	s_barrier
	s_add_i32 s70, 0, 0x18000
	s_add_i32 s71, 0, 0x1c000
	v_add_u32_e32 v164, s70, v157
	v_add_u32_e32 v180, s71, v157
	ds_read_b128 v[144:147], v164
	ds_read_b128 v[152:155], v164 offset:1024
	ds_read_b128 v[160:163], v164 offset:2048
	ds_read_b128 v[164:167], v164 offset:3072
	ds_read_b128 v[168:171], v180
	ds_read_b128 v[172:175], v180 offset:1024
	ds_read_b128 v[176:179], v180 offset:2048
	ds_read_b128 v[180:183], v180 offset:3072
	s_add_u32 s36, s36, 0x20000
	s_addc_u32 s37, s37, 0
	s_mov_b32 m0, s41
	v_lshl_add_u64 v[224:225], s[36:37], 0, v[136:137]
	ds_read_b128 v[184:187], v159 offset:32768
	ds_read_b128 v[188:191], v159 offset:33792
	ds_read_b128 v[192:195], v159 offset:34816
	ds_read_b128 v[196:199], v159 offset:35840
	ds_read_b128 v[200:203], v159 offset:36864
	ds_read_b128 v[204:207], v159 offset:37888
	ds_read_b128 v[208:211], v159 offset:38912
	ds_read_b128 v[212:215], v159 offset:39936
	global_load_lds_dwordx4 v[224:225], off
	v_lshl_add_u64 v[224:225], s[36:37], 0, v[140:141]
	s_mov_b32 m0, s42
	s_nop 0
	global_load_lds_dwordx4 v[224:225], off
	s_waitcnt vmcnt(8)
	s_waitcnt lgkmcnt(0)
	s_barrier
	s_setprio 0
	s_waitcnt lgkmcnt(0)
	v_mfma_f32_16x16x32_bf16 v[124:127], v[144:147], v[184:187], v[124:127]
	v_mfma_f32_16x16x32_bf16 v[120:123], v[160:163], v[184:187], v[120:123]
	v_mfma_f32_16x16x32_bf16 v[108:111], v[144:147], v[192:195], v[108:111]
	v_mfma_f32_16x16x32_bf16 v[104:107], v[160:163], v[192:195], v[104:107]
	v_mfma_f32_16x16x32_bf16 v[92:95], v[144:147], v[200:203], v[92:95]
	v_mfma_f32_16x16x32_bf16 v[88:91], v[160:163], v[200:203], v[88:91]
	v_mfma_f32_16x16x32_bf16 v[76:79], v[144:147], v[208:211], v[76:79]
	v_mfma_f32_16x16x32_bf16 v[72:75], v[160:163], v[208:211], v[72:75]
	v_mfma_f32_16x16x32_bf16 v[124:127], v[152:155], v[188:191], v[124:127]
	v_mfma_f32_16x16x32_bf16 v[120:123], v[164:167], v[188:191], v[120:123]
	v_mfma_f32_16x16x32_bf16 v[108:111], v[152:155], v[196:199], v[108:111]
	v_mfma_f32_16x16x32_bf16 v[104:107], v[164:167], v[196:199], v[104:107]
	v_mfma_f32_16x16x32_bf16 v[92:95], v[152:155], v[204:207], v[92:95]
	v_mfma_f32_16x16x32_bf16 v[88:91], v[164:167], v[204:207], v[88:91]
	v_mfma_f32_16x16x32_bf16 v[76:79], v[152:155], v[212:215], v[76:79]
	v_mfma_f32_16x16x32_bf16 v[72:75], v[164:167], v[212:215], v[72:75]
	s_setprio 1
	s_setprio 0
	v_mfma_f32_16x16x32_bf16 v[116:119], v[168:171], v[184:187], v[116:119]
	v_mfma_f32_16x16x32_bf16 v[112:115], v[176:179], v[184:187], v[112:115]
	v_mfma_f32_16x16x32_bf16 v[100:103], v[168:171], v[192:195], v[100:103]
	v_mfma_f32_16x16x32_bf16 v[96:99], v[176:179], v[192:195], v[96:99]
	v_mfma_f32_16x16x32_bf16 v[84:87], v[168:171], v[200:203], v[84:87]
	v_mfma_f32_16x16x32_bf16 v[80:83], v[176:179], v[200:203], v[80:83]
	v_mfma_f32_16x16x32_bf16 v[68:71], v[168:171], v[208:211], v[68:71]
	v_mfma_f32_16x16x32_bf16 v[64:67], v[176:179], v[208:211], v[64:67]
	v_mfma_f32_16x16x32_bf16 v[116:119], v[172:175], v[188:191], v[116:119]
	v_mfma_f32_16x16x32_bf16 v[112:115], v[180:183], v[188:191], v[112:115]
	v_mfma_f32_16x16x32_bf16 v[100:103], v[172:175], v[196:199], v[100:103]
	v_mfma_f32_16x16x32_bf16 v[96:99], v[180:183], v[196:199], v[96:99]
	v_mfma_f32_16x16x32_bf16 v[84:87], v[172:175], v[204:207], v[84:87]
	v_mfma_f32_16x16x32_bf16 v[80:83], v[180:183], v[204:207], v[80:83]
	v_mfma_f32_16x16x32_bf16 v[68:71], v[172:175], v[212:215], v[68:71]
	v_mfma_f32_16x16x32_bf16 v[64:67], v[180:183], v[212:215], v[64:67]
	s_setprio 1
	s_barrier
; #define PG8_STAGE(bufoff, gbase, voff) do { _Pragma("unroll") for (int _i = 0; _i < 2; ++_i) \
;         __builtin_amdgcn_global_load_lds((const unsigned*)((const char*)(gbase) + (voff)[_i]), (PG8_LAS unsigned*)(lds + (bufoff) + ldsw + _i * 8192), 16, 0, 0); } while (0)
; #define PG8_LDA(dst, b, h) do { _Pragma("unroll") for (int m = 0; m < 4; ++m) _Pragma("unroll") for (int k = 0; k < 2; ++k) dst[m][k] = *(const PG8_LAS bf16x8*)(lds + PG8_SA(b, h) + aoff + m * 2048 + k * 1024); } while (0)
; #define PG8_MMA(ai, bj, At, Bt) do { __builtin_amdgcn_s_setprio(1); _Pragma("unroll") for (int m = 0; m < 4; ++m) _Pragma("unroll") for (int n = 0; n < 2; ++n) _Pragma("unroll") for (int k = 0; k < 2; ++k) \
;         acc[ai][bj][m][n] = __builtin_amdgcn_mfma_f32_16x16x32_bf16(Bt[n][k], At[m][k], acc[ai][bj][m][n], 0, 0, 0); __builtin_amdgcn_s_setprio(0); } while (0)
; #define PG8_WAIT_V(n) asm volatile("s_waitcnt vmcnt(" #n ")" ::: "memory")
; #define PG8_WAIT_L(n) asm volatile("s_waitcnt lgkmcnt(" #n ")" ::: "memory")
; #define PG8_BAR __builtin_amdgcn_s_barrier()
; #define PG8_SCHED __builtin_amdgcn_sched_barrier(0)
; template <class Epi, class Sched, bool ALIGN_EPI = false, bool SP2 = false>
; __device__ __forceinline__ void gemm_phase(PG8_LAS unsigned char* lds, const Gemm g, const Sched& S, const Epi& E) {
;     ...
;         for (int t = 0; t < nt; t += 2) {
;             const bool last = (t == nt - 2);
;     ...
;             PG8_LDA(At, 1, 1); PG8_STAGE(PG8_SB(1, 0), b3, voffB); PG8_STAGE(PG8_SB(1, 1), b3 + hstep, voffB); PG8_STAGE(PG8_SA(1, 0), a3, voffA);
;             PG8_WAIT_V(8); PG8_WAIT_L(0); PG8_BAR; PG8_MMA(1, 0, At, B0); PG8_MMA(1, 1, At, B1); PG8_BAR; PG8_SCHED;
	s_add_i32 s36, s70, s39
	v_lshl_add_u64 v[216:217], v[216:217], 0, s[4:5]
	s_mov_b32 m0, s36
	ds_read_b128 v[184:187], v159 offset:49152
	ds_read_b128 v[188:191], v159 offset:50176
	ds_read_b128 v[192:195], v159 offset:51200
	ds_read_b128 v[196:199], v159 offset:52224
	ds_read_b128 v[200:203], v159 offset:53248
	ds_read_b128 v[204:207], v159 offset:54272
	ds_read_b128 v[208:211], v159 offset:55296
	ds_read_b128 v[212:215], v159 offset:56320
	global_load_lds_dwordx4 v[216:217], off
	s_add_i32 m0, s36, 0x2000
	s_add_u32 s34, s34, 0x20080
	v_lshl_add_u64 v[216:217], v[218:219], 0, s[4:5]
	s_addc_u32 s35, s35, 0
	s_add_i32 s36, s71, s39
	global_load_lds_dwordx4 v[216:217], off
	v_lshl_add_u64 v[216:217], s[34:35], 0, v[138:139]
	s_mov_b32 m0, s36
	s_nop 0
	global_load_lds_dwordx4 v[216:217], off
	v_lshl_add_u64 v[216:217], s[34:35], 0, v[142:143]
	s_add_i32 m0, s36, 0x2000
	s_nop 0
	global_load_lds_dwordx4 v[216:217], off
	v_lshl_add_u64 v[216:217], v[220:221], 0, s[4:5]
	s_mov_b32 m0, s44
	s_nop 0
	global_load_lds_dwordx4 v[216:217], off
	v_lshl_add_u64 v[216:217], v[222:223], 0, s[4:5]
	s_mov_b32 m0, s45
	s_nop 0
	global_load_lds_dwordx4 v[216:217], off
	s_waitcnt vmcnt(8)
	s_waitcnt lgkmcnt(0)
	s_barrier
	s_setprio 0
	s_waitcnt lgkmcnt(0)
	v_mfma_f32_16x16x32_bf16 v[60:63], v[144:147], v[184:187], v[60:63]
	v_mfma_f32_16x16x32_bf16 v[56:59], v[160:163], v[184:187], v[56:59]
	v_mfma_f32_16x16x32_bf16 v[44:47], v[144:147], v[192:195], v[44:47]
	v_mfma_f32_16x16x32_bf16 v[40:43], v[160:163], v[192:195], v[40:43]
	v_mfma_f32_16x16x32_bf16 v[28:31], v[144:147], v[200:203], v[28:31]
	v_mfma_f32_16x16x32_bf16 v[24:27], v[160:163], v[200:203], v[24:27]
	v_mfma_f32_16x16x32_bf16 v[12:15], v[144:147], v[208:211], v[12:15]
	v_mfma_f32_16x16x32_bf16 v[8:11], v[160:163], v[208:211], v[8:11]
	v_mfma_f32_16x16x32_bf16 v[60:63], v[152:155], v[188:191], v[60:63]
	v_mfma_f32_16x16x32_bf16 v[56:59], v[164:167], v[188:191], v[56:59]
	v_mfma_f32_16x16x32_bf16 v[44:47], v[152:155], v[196:199], v[44:47]
	v_mfma_f32_16x16x32_bf16 v[40:43], v[164:167], v[196:199], v[40:43]
	v_mfma_f32_16x16x32_bf16 v[28:31], v[152:155], v[204:207], v[28:31]
	v_mfma_f32_16x16x32_bf16 v[24:27], v[164:167], v[204:207], v[24:27]
	v_mfma_f32_16x16x32_bf16 v[12:15], v[152:155], v[212:215], v[12:15]
	v_mfma_f32_16x16x32_bf16 v[8:11], v[164:167], v[212:215], v[8:11]
	s_setprio 1
	s_setprio 0
	v_mfma_f32_16x16x32_bf16 v[52:55], v[168:171], v[184:187], v[52:55]
	v_mfma_f32_16x16x32_bf16 v[48:51], v[176:179], v[184:187], v[48:51]
	v_mfma_f32_16x16x32_bf16 v[36:39], v[168:171], v[192:195], v[36:39]
	v_mfma_f32_16x16x32_bf16 v[32:35], v[176:179], v[192:195], v[32:35]
	v_mfma_f32_16x16x32_bf16 v[20:23], v[168:171], v[200:203], v[20:23]
	v_mfma_f32_16x16x32_bf16 v[16:19], v[176:179], v[200:203], v[16:19]
	v_mfma_f32_16x16x32_bf16 v[4:7], v[168:171], v[208:211], v[4:7]
	v_mfma_f32_16x16x32_bf16 v[0:3], v[176:179], v[208:211], v[0:3]
	v_mfma_f32_16x16x32_bf16 v[52:55], v[172:175], v[188:191], v[52:55]
	v_mfma_f32_16x16x32_bf16 v[48:51], v[180:183], v[188:191], v[48:51]
	v_mfma_f32_16x16x32_bf16 v[36:39], v[172:175], v[196:199], v[36:39]
	v_mfma_f32_16x16x32_bf16 v[32:35], v[180:183], v[196:199], v[32:35]
	v_mfma_f32_16x16x32_bf16 v[20:23], v[172:175], v[204:207], v[20:23]
	v_mfma_f32_16x16x32_bf16 v[16:19], v[180:183], v[204:207], v[16:19]
	v_mfma_f32_16x16x32_bf16 v[4:7], v[172:175], v[212:215], v[4:7]
	v_mfma_f32_16x16x32_bf16 v[0:3], v[180:183], v[212:215], v[0:3]
	s_setprio 1
	s_barrier
	s_add_i32 s69, s69, 2
	s_add_u32 s30, s30, 0x100
	s_addc_u32 s31, s31, 0
	s_add_u32 s63, s63, 0x100
	s_addc_u32 s68, s68, 0
	s_cmp_gt_u32 s69, 5
	s_cbranch_scc0 .LBB0_1319
	s_and_b64 vcc, exec, s[6:7]
	s_cbranch_vccz .LBB0_1322
	s_barrier

; #define PG8_STAGE(bufoff, gbase, voff) do { _Pragma("unroll") for (int _i = 0; _i < 2; ++_i) \
;         __builtin_amdgcn_global_load_lds((const unsigned*)((const char*)(gbase) + (voff)[_i]), (PG8_LAS unsigned*)(lds + (bufoff) + ldsw + _i * 8192), 16, 0, 0); } while (0)
; #define PG8_LDA(dst, b, h) do { _Pragma("unroll") for (int m = 0; m < 4; ++m) _Pragma("unroll") for (int k = 0; k < 2; ++k) dst[m][k] = *(const PG8_LAS bf16x8*)(lds + PG8_SA(b, h) + aoff + m * 2048 + k * 1024); } while (0)
; #define PG8_LDB(dst, b, h) do { _Pragma("unroll") for (int n = 0; n < 2; ++n) _Pragma("unroll") for (int k = 0; k < 2; ++k) dst[n][k] = *(const PG8_LAS bf16x8*)(lds + PG8_SB(b, h) + boff + n * 2048 + k * 1024); } while (0)
; #define PG8_MMA(ai, bj, At, Bt) do { __builtin_amdgcn_s_setprio(1); _Pragma("unroll") for (int m = 0; m < 4; ++m) _Pragma("unroll") for (int n = 0; n < 2; ++n) _Pragma("unroll") for (int k = 0; k < 2; ++k) \
;         acc[ai][bj][m][n] = __builtin_amdgcn_mfma_f32_16x16x32_bf16(Bt[n][k], At[m][k], acc[ai][bj][m][n], 0, 0, 0); __builtin_amdgcn_s_setprio(0); } while (0)
; #define PG8_WAIT_V(n) asm volatile("s_waitcnt vmcnt(" #n ")" ::: "memory")
; #define PG8_WAIT_L(n) asm volatile("s_waitcnt lgkmcnt(" #n ")" ::: "memory")
; #define PG8_BAR __builtin_amdgcn_s_barrier()
; #define PG8_SCHED __builtin_amdgcn_sched_barrier(0)
; template <class Epi, class Sched, bool ALIGN_EPI = false, bool SP2 = false>
; __device__ __forceinline__ void gemm_phase(PG8_LAS unsigned char* lds, const Gemm g, const Sched& S, const Epi& E) {
;     ...
;             const bool last = (t == nt - 2);
;             const char* a1 = cA + (size_t)(t + 1) * kstep;
;             const char* a2 = last ? nA : cA + (size_t)(t + 2) * kstep; const char* b2 = last ? nB : cB + (size_t)(t + 2) * kstep;
;     ...
;             PG8_LDB(B0, 0, 0); PG8_LDB(B1, 0, 1); PG8_SCHED; PG8_LDA(At, 0, 0); PG8_STAGE(PG8_SA(1, 1), a1 + hstep, voffA);
;             PG8_WAIT_V(8); PG8_WAIT_L(0); PG8_BAR; PG8_MMA(0, 0, At, B0); PG8_MMA(0, 1, At, B1); PG8_BAR; PG8_SCHED;
;             PG8_LDA(At, 0, 1); PG8_STAGE(PG8_SB(0, 0), b2, voffB); PG8_STAGE(PG8_SB(0, 1), b2 + hstep, voffB); PG8_STAGE(PG8_SA(0, 0), a2, voffA);
.LBB0_1400:
	ds_read_b128 v[140:143], v147
	ds_read_b128 v[154:157], v147 offset:1024
	ds_read_b128 v[158:161], v147 offset:2048
	ds_read_b128 v[162:165], v147 offset:3072
	ds_read_b128 v[166:169], v149
	ds_read_b128 v[170:173], v149 offset:1024
	ds_read_b128 v[174:177], v149 offset:2048
	ds_read_b128 v[178:181], v149 offset:3072
	s_add_u32 s26, s24, 0xfffc0080
	s_addc_u32 s27, s25, -1
	s_cmp_eq_u32 s60, 12
	s_cselect_b32 s29, s15, s27
	s_cselect_b32 s28, s21, s26
	s_cselect_b32 s27, s13, s59
	s_cselect_b32 s26, s57, s58
	v_lshl_add_u64 v[214:215], s[24:25], 0, v[132:133]
	s_add_i32 m0, s23, 0xc000
	ds_read_b128 v[182:185], v151
	ds_read_b128 v[186:189], v151 offset:1024
	ds_read_b128 v[190:193], v151 offset:2048
	ds_read_b128 v[194:197], v151 offset:3072
	ds_read_b128 v[198:201], v151 offset:4096
	ds_read_b128 v[202:205], v151 offset:5120
	ds_read_b128 v[206:209], v151 offset:6144
	ds_read_b128 v[210:213], v151 offset:7168
	global_load_lds_dwordx4 v[214:215], off
	v_lshl_add_u64 v[214:215], s[24:25], 0, v[134:135]
	s_add_i32 m0, s23, 0xe000
	s_nop 0
	global_load_lds_dwordx4 v[214:215], off
	s_waitcnt vmcnt(8)
	s_waitcnt lgkmcnt(0)
	s_barrier
	s_setprio 0
	s_waitcnt lgkmcnt(0)
	v_mfma_f32_16x16x32_bf16 v[124:127], v[140:143], v[182:185], v[124:127]
	v_mfma_f32_16x16x32_bf16 v[120:123], v[158:161], v[182:185], v[120:123]
	v_mfma_f32_16x16x32_bf16 v[108:111], v[140:143], v[190:193], v[108:111]
	v_mfma_f32_16x16x32_bf16 v[104:107], v[158:161], v[190:193], v[104:107]
	v_mfma_f32_16x16x32_bf16 v[92:95], v[140:143], v[198:201], v[92:95]
	v_mfma_f32_16x16x32_bf16 v[88:91], v[158:161], v[198:201], v[88:91]
	v_mfma_f32_16x16x32_bf16 v[76:79], v[140:143], v[206:209], v[76:79]
	v_mfma_f32_16x16x32_bf16 v[72:75], v[158:161], v[206:209], v[72:75]
	v_mfma_f32_16x16x32_bf16 v[124:127], v[154:157], v[186:189], v[124:127]
	v_mfma_f32_16x16x32_bf16 v[120:123], v[162:165], v[186:189], v[120:123]
	v_mfma_f32_16x16x32_bf16 v[108:111], v[154:157], v[194:197], v[108:111]
	v_mfma_f32_16x16x32_bf16 v[104:107], v[162:165], v[194:197], v[104:107]
	v_mfma_f32_16x16x32_bf16 v[92:95], v[154:157], v[202:205], v[92:95]
	v_mfma_f32_16x16x32_bf16 v[88:91], v[162:165], v[202:205], v[88:91]
	v_mfma_f32_16x16x32_bf16 v[76:79], v[154:157], v[210:213], v[76:79]
	v_mfma_f32_16x16x32_bf16 v[72:75], v[162:165], v[210:213], v[72:75]
	s_setprio 1
	s_setprio 0
	v_mfma_f32_16x16x32_bf16 v[116:119], v[166:169], v[182:185], v[116:119]
	v_mfma_f32_16x16x32_bf16 v[112:115], v[174:177], v[182:185], v[112:115]
	v_mfma_f32_16x16x32_bf16 v[100:103], v[166:169], v[190:193], v[100:103]
	v_mfma_f32_16x16x32_bf16 v[96:99], v[174:177], v[190:193], v[96:99]
	v_mfma_f32_16x16x32_bf16 v[84:87], v[166:169], v[198:201], v[84:87]
	v_mfma_f32_16x16x32_bf16 v[80:83], v[174:177], v[198:201], v[80:83]
	v_mfma_f32_16x16x32_bf16 v[68:71], v[166:169], v[206:209], v[68:71]
	v_mfma_f32_16x16x32_bf16 v[64:67], v[174:177], v[206:209], v[64:67]
	v_mfma_f32_16x16x32_bf16 v[116:119], v[170:173], v[186:189], v[116:119]
	v_mfma_f32_16x16x32_bf16 v[112:115], v[178:181], v[186:189], v[112:115]
	v_mfma_f32_16x16x32_bf16 v[100:103], v[170:173], v[194:197], v[100:103]
	v_mfma_f32_16x16x32_bf16 v[96:99], v[178:181], v[194:197], v[96:99]
	v_mfma_f32_16x16x32_bf16 v[84:87], v[170:173], v[202:205], v[84:87]
	v_mfma_f32_16x16x32_bf16 v[80:83], v[178:181], v[202:205], v[80:83]
	v_mfma_f32_16x16x32_bf16 v[68:71], v[170:173], v[210:213], v[68:71]
	v_mfma_f32_16x16x32_bf16 v[64:67], v[178:181], v[210:213], v[64:67]
	s_setprio 1
	s_barrier
	s_add_i32 s61, s42, s30
	v_lshl_add_u64 v[214:215], s[26:27], 0, v[128:129]
	s_mov_b32 m0, s61
	ds_read_b128 v[182:185], v151 offset:16384
	ds_read_b128 v[186:189], v151 offset:17408
	ds_read_b128 v[190:193], v151 offset:18432
	ds_read_b128 v[194:197], v151 offset:19456
	ds_read_b128 v[198:201], v151 offset:20480
	ds_read_b128 v[202:205], v151 offset:21504
	ds_read_b128 v[206:209], v151 offset:22528
	ds_read_b128 v[210:213], v151 offset:23552
	global_load_lds_dwordx4 v[214:215], off
	s_add_i32 m0, s61, 0x2000
	s_add_u32 s62, s26, 0x40000
	v_lshl_add_u64 v[216:217], s[26:27], 0, v[130:131]
	s_addc_u32 s63, s27, 0
	s_add_i32 s61, s43, s30
	global_load_lds_dwordx4 v[216:217], off
	v_lshl_add_u64 v[218:219], s[62:63], 0, v[128:129]
	s_mov_b32 m0, s61
	v_lshl_add_u64 v[220:221], s[28:29], 0, v[130:131]
	global_load_lds_dwordx4 v[218:219], off
	v_lshl_add_u64 v[218:219], s[62:63], 0, v[130:131]
	s_add_i32 m0, s61, 0x2000
	s_nop 0
	global_load_lds_dwordx4 v[218:219], off
	v_lshl_add_u64 v[218:219], s[28:29], 0, v[128:129]
	s_mov_b32 m0, s23
	s_nop 0
	global_load_lds_dwordx4 v[218:219], off
	s_mov_b32 m0, s31
	s_nop 0
	global_load_lds_dwordx4 v[220:221], off
	s_waitcnt vmcnt(8)
	s_waitcnt lgkmcnt(0)
	s_barrier
; #define PG8_STAGE(bufoff, gbase, voff) do { _Pragma("unroll") for (int _i = 0; _i < 2; ++_i) \
;         __builtin_amdgcn_global_load_lds((const unsigned*)((const char*)(gbase) + (voff)[_i]), (PG8_LAS unsigned*)(lds + (bufoff) + ldsw + _i * 8192), 16, 0, 0); } while (0)
; #define PG8_LDA(dst, b, h) do { _Pragma("unroll") for (int m = 0; m < 4; ++m) _Pragma("unroll") for (int k = 0; k < 2; ++k) dst[m][k] = *(const PG8_LAS bf16x8*)(lds + PG8_SA(b, h) + aoff + m * 2048 + k * 1024); } while (0)
; #define PG8_LDB(dst, b, h) do { _Pragma("unroll") for (int n = 0; n < 2; ++n) _Pragma("unroll") for (int k = 0; k < 2; ++k) dst[n][k] = *(const PG8_LAS bf16x8*)(lds + PG8_SB(b, h) + boff + n * 2048 + k * 1024); } while (0)
; #define PG8_MMA(ai, bj, At, Bt) do { __builtin_amdgcn_s_setprio(1); _Pragma("unroll") for (int m = 0; m < 4; ++m) _Pragma("unroll") for (int n = 0; n < 2; ++n) _Pragma("unroll") for (int k = 0; k < 2; ++k) \
;         acc[ai][bj][m][n] = __builtin_amdgcn_mfma_f32_16x16x32_bf16(Bt[n][k], At[m][k], acc[ai][bj][m][n], 0, 0, 0); __builtin_amdgcn_s_setprio(0); } while (0)
; #define PG8_WAIT_V(n) asm volatile("s_waitcnt vmcnt(" #n ")" ::: "memory")
; #define PG8_WAIT_L(n) asm volatile("s_waitcnt lgkmcnt(" #n ")" ::: "memory")
; #define PG8_BAR __builtin_amdgcn_s_barrier()
; #define PG8_SCHED __builtin_amdgcn_sched_barrier(0)
; template <class Epi, class Sched, bool ALIGN_EPI = false, bool SP2 = false>
; __device__ __forceinline__ void gemm_phase(PG8_LAS unsigned char* lds, const Gemm g, const Sched& S, const Epi& E) {
;     ...
;             PG8_WAIT_V(8); PG8_WAIT_L(0); PG8_BAR; PG8_MMA(1, 0, At, B0); PG8_MMA(1, 1, At, B1); PG8_BAR; PG8_SCHED;
;             PG8_LDB(B0, 1, 0); PG8_LDB(B1, 1, 1); PG8_SCHED; PG8_LDA(At, 1, 0); PG8_STAGE(PG8_SA(0, 1), a2 + hstep, voffA);
;             PG8_WAIT_V(8); PG8_WAIT_L(0); PG8_BAR; PG8_MMA(0, 0, At, B0); PG8_MMA(0, 1, At, B1); PG8_BAR; PG8_SCHED;
	s_setprio 0
	s_waitcnt lgkmcnt(0)
	v_mfma_f32_16x16x32_bf16 v[60:63], v[140:143], v[182:185], v[60:63]
	v_mfma_f32_16x16x32_bf16 v[56:59], v[158:161], v[182:185], v[56:59]
	v_mfma_f32_16x16x32_bf16 v[44:47], v[140:143], v[190:193], v[44:47]
	v_mfma_f32_16x16x32_bf16 v[40:43], v[158:161], v[190:193], v[40:43]
	v_mfma_f32_16x16x32_bf16 v[28:31], v[140:143], v[198:201], v[28:31]
	v_mfma_f32_16x16x32_bf16 v[24:27], v[158:161], v[198:201], v[24:27]
	v_mfma_f32_16x16x32_bf16 v[12:15], v[140:143], v[206:209], v[12:15]
	v_mfma_f32_16x16x32_bf16 v[8:11], v[158:161], v[206:209], v[8:11]
	v_mfma_f32_16x16x32_bf16 v[60:63], v[154:157], v[186:189], v[60:63]
	v_mfma_f32_16x16x32_bf16 v[56:59], v[162:165], v[186:189], v[56:59]
	v_mfma_f32_16x16x32_bf16 v[44:47], v[154:157], v[194:197], v[44:47]
	v_mfma_f32_16x16x32_bf16 v[40:43], v[162:165], v[194:197], v[40:43]
	v_mfma_f32_16x16x32_bf16 v[28:31], v[154:157], v[202:205], v[28:31]
	v_mfma_f32_16x16x32_bf16 v[24:27], v[162:165], v[202:205], v[24:27]
	v_mfma_f32_16x16x32_bf16 v[12:15], v[154:157], v[210:213], v[12:15]
	v_mfma_f32_16x16x32_bf16 v[8:11], v[162:165], v[210:213], v[8:11]
	s_setprio 1
	s_setprio 0
	v_mfma_f32_16x16x32_bf16 v[52:55], v[166:169], v[182:185], v[52:55]
	v_mfma_f32_16x16x32_bf16 v[48:51], v[174:177], v[182:185], v[48:51]
	v_mfma_f32_16x16x32_bf16 v[36:39], v[166:169], v[190:193], v[36:39]
	v_mfma_f32_16x16x32_bf16 v[32:35], v[174:177], v[190:193], v[32:35]
	v_mfma_f32_16x16x32_bf16 v[20:23], v[166:169], v[198:201], v[20:23]
	v_mfma_f32_16x16x32_bf16 v[16:19], v[174:177], v[198:201], v[16:19]
	v_mfma_f32_16x16x32_bf16 v[4:7], v[166:169], v[206:209], v[4:7]
	v_mfma_f32_16x16x32_bf16 v[0:3], v[174:177], v[206:209], v[0:3]
	v_mfma_f32_16x16x32_bf16 v[52:55], v[170:173], v[186:189], v[52:55]
	v_mfma_f32_16x16x32_bf16 v[48:51], v[178:181], v[186:189], v[48:51]
	v_mfma_f32_16x16x32_bf16 v[36:39], v[170:173], v[194:197], v[36:39]
	v_mfma_f32_16x16x32_bf16 v[32:35], v[178:181], v[194:197], v[32:35]
	v_mfma_f32_16x16x32_bf16 v[20:23], v[170:173], v[202:205], v[20:23]
	v_mfma_f32_16x16x32_bf16 v[16:19], v[178:181], v[202:205], v[16:19]
	v_mfma_f32_16x16x32_bf16 v[4:7], v[170:173], v[210:213], v[4:7]
	v_mfma_f32_16x16x32_bf16 v[0:3], v[178:181], v[210:213], v[0:3]
	s_setprio 1
	s_barrier
	s_add_i32 s61, 0, 0x18000
	v_add_u32_e32 v153, s61, v145
	s_add_i32 s62, 0, 0x1c000
	ds_read_b128 v[140:143], v153
	ds_read_b128 v[154:157], v153 offset:1024
	ds_read_b128 v[158:161], v153 offset:2048
	ds_read_b128 v[162:165], v153 offset:3072
	v_add_u32_e32 v153, s62, v145
	ds_read_b128 v[166:169], v153
	ds_read_b128 v[170:173], v153 offset:1024
	ds_read_b128 v[174:177], v153 offset:2048
	ds_read_b128 v[178:181], v153 offset:3072
	s_add_u32 s28, s28, 0x40000
	s_addc_u32 s29, s29, 0
	s_mov_b32 m0, s34
	v_lshl_add_u64 v[222:223], s[28:29], 0, v[128:129]
	ds_read_b128 v[182:185], v151 offset:32768
	ds_read_b128 v[186:189], v151 offset:33792
	ds_read_b128 v[190:193], v151 offset:34816
	ds_read_b128 v[194:197], v151 offset:35840
	ds_read_b128 v[198:201], v151 offset:36864
	ds_read_b128 v[202:205], v151 offset:37888
	ds_read_b128 v[206:209], v151 offset:38912
	ds_read_b128 v[210:213], v151 offset:39936
	global_load_lds_dwordx4 v[222:223], off
	v_lshl_add_u64 v[222:223], s[28:29], 0, v[130:131]
	s_mov_b32 m0, s35
	s_nop 0
	global_load_lds_dwordx4 v[222:223], off
	s_waitcnt vmcnt(8)
	s_waitcnt lgkmcnt(0)
	s_barrier
	s_setprio 0
	s_waitcnt lgkmcnt(0)
	v_mfma_f32_16x16x32_bf16 v[124:127], v[140:143], v[182:185], v[124:127]
	v_mfma_f32_16x16x32_bf16 v[120:123], v[158:161], v[182:185], v[120:123]
	v_mfma_f32_16x16x32_bf16 v[108:111], v[140:143], v[190:193], v[108:111]
	v_mfma_f32_16x16x32_bf16 v[104:107], v[158:161], v[190:193], v[104:107]
	v_mfma_f32_16x16x32_bf16 v[92:95], v[140:143], v[198:201], v[92:95]
	v_mfma_f32_16x16x32_bf16 v[88:91], v[158:161], v[198:201], v[88:91]
	v_mfma_f32_16x16x32_bf16 v[76:79], v[140:143], v[206:209], v[76:79]
	v_mfma_f32_16x16x32_bf16 v[72:75], v[158:161], v[206:209], v[72:75]
	v_mfma_f32_16x16x32_bf16 v[124:127], v[154:157], v[186:189], v[124:127]
	v_mfma_f32_16x16x32_bf16 v[120:123], v[162:165], v[186:189], v[120:123]
	v_mfma_f32_16x16x32_bf16 v[108:111], v[154:157], v[194:197], v[108:111]
	v_mfma_f32_16x16x32_bf16 v[104:107], v[162:165], v[194:197], v[104:107]
	v_mfma_f32_16x16x32_bf16 v[92:95], v[154:157], v[202:205], v[92:95]
	v_mfma_f32_16x16x32_bf16 v[88:91], v[162:165], v[202:205], v[88:91]
	v_mfma_f32_16x16x32_bf16 v[76:79], v[154:157], v[210:213], v[76:79]
	v_mfma_f32_16x16x32_bf16 v[72:75], v[162:165], v[210:213], v[72:75]
	s_setprio 1
	s_setprio 0
	v_mfma_f32_16x16x32_bf16 v[116:119], v[166:169], v[182:185], v[116:119]
	v_mfma_f32_16x16x32_bf16 v[112:115], v[174:177], v[182:185], v[112:115]
	v_mfma_f32_16x16x32_bf16 v[100:103], v[166:169], v[190:193], v[100:103]
	v_mfma_f32_16x16x32_bf16 v[96:99], v[174:177], v[190:193], v[96:99]
	v_mfma_f32_16x16x32_bf16 v[84:87], v[166:169], v[198:201], v[84:87]
	v_mfma_f32_16x16x32_bf16 v[80:83], v[174:177], v[198:201], v[80:83]
	v_mfma_f32_16x16x32_bf16 v[68:71], v[166:169], v[206:209], v[68:71]
	v_mfma_f32_16x16x32_bf16 v[64:67], v[174:177], v[206:209], v[64:67]
	v_mfma_f32_16x16x32_bf16 v[116:119], v[170:173], v[186:189], v[116:119]
	v_mfma_f32_16x16x32_bf16 v[112:115], v[178:181], v[186:189], v[112:115]
	v_mfma_f32_16x16x32_bf16 v[100:103], v[170:173], v[194:197], v[100:103]
	v_mfma_f32_16x16x32_bf16 v[96:99], v[178:181], v[194:197], v[96:99]
	v_mfma_f32_16x16x32_bf16 v[84:87], v[170:173], v[202:205], v[84:87]
	v_mfma_f32_16x16x32_bf16 v[80:83], v[178:181], v[202:205], v[80:83]
	v_mfma_f32_16x16x32_bf16 v[68:71], v[170:173], v[210:213], v[68:71]
	v_mfma_f32_16x16x32_bf16 v[64:67], v[178:181], v[210:213], v[64:67]
	s_setprio 1
	s_barrier
; #define PG8_STAGE(bufoff, gbase, voff) do { _Pragma("unroll") for (int _i = 0; _i < 2; ++_i) \
;         __builtin_amdgcn_global_load_lds((const unsigned*)((const char*)(gbase) + (voff)[_i]), (PG8_LAS unsigned*)(lds + (bufoff) + ldsw + _i * 8192), 16, 0, 0); } while (0)
; #define PG8_LDA(dst, b, h) do { _Pragma("unroll") for (int m = 0; m < 4; ++m) _Pragma("unroll") for (int k = 0; k < 2; ++k) dst[m][k] = *(const PG8_LAS bf16x8*)(lds + PG8_SA(b, h) + aoff + m * 2048 + k * 1024); } while (0)
; #define PG8_MMA(ai, bj, At, Bt) do { __builtin_amdgcn_s_setprio(1); _Pragma("unroll") for (int m = 0; m < 4; ++m) _Pragma("unroll") for (int n = 0; n < 2; ++n) _Pragma("unroll") for (int k = 0; k < 2; ++k) \
;         acc[ai][bj][m][n] = __builtin_amdgcn_mfma_f32_16x16x32_bf16(Bt[n][k], At[m][k], acc[ai][bj][m][n], 0, 0, 0); __builtin_amdgcn_s_setprio(0); } while (0)
; #define PG8_WAIT_V(n) asm volatile("s_waitcnt vmcnt(" #n ")" ::: "memory")
; #define PG8_WAIT_L(n) asm volatile("s_waitcnt lgkmcnt(" #n ")" ::: "memory")
; #define PG8_BAR __builtin_amdgcn_s_barrier()
; #define PG8_SCHED __builtin_amdgcn_sched_barrier(0)
; template <class Epi, class Sched, bool ALIGN_EPI = false, bool SP2 = false>
; __device__ __forceinline__ void gemm_phase(PG8_LAS unsigned char* lds, const Gemm g, const Sched& S, const Epi& E) {
;     ...
;         for (int t = 0; t < nt; t += 2) {
;             const bool last = (t == nt - 2);
;     ...
;             PG8_LDA(At, 1, 1); PG8_STAGE(PG8_SB(1, 0), b3, voffB); PG8_STAGE(PG8_SB(1, 1), b3 + hstep, voffB); PG8_STAGE(PG8_SA(1, 0), a3, voffA);
;             PG8_WAIT_V(8); PG8_WAIT_L(0); PG8_BAR; PG8_MMA(1, 0, At, B0); PG8_MMA(1, 1, At, B1); PG8_BAR; PG8_SCHED;
	s_add_i32 s28, s61, s30
	v_lshl_add_u64 v[214:215], v[214:215], 0, s[8:9]
	s_mov_b32 m0, s28
	ds_read_b128 v[182:185], v151 offset:49152
	ds_read_b128 v[186:189], v151 offset:50176
	ds_read_b128 v[190:193], v151 offset:51200
	ds_read_b128 v[194:197], v151 offset:52224
	ds_read_b128 v[198:201], v151 offset:53248
	ds_read_b128 v[202:205], v151 offset:54272
	ds_read_b128 v[206:209], v151 offset:55296
	ds_read_b128 v[210:213], v151 offset:56320
	global_load_lds_dwordx4 v[214:215], off
	s_add_i32 m0, s28, 0x2000
	s_add_u32 s26, s26, 0x40080
	v_lshl_add_u64 v[214:215], v[216:217], 0, s[8:9]
	s_addc_u32 s27, s27, 0
	s_add_i32 s28, s62, s30
	global_load_lds_dwordx4 v[214:215], off
	v_lshl_add_u64 v[214:215], s[26:27], 0, v[128:129]
	s_mov_b32 m0, s28
	s_nop 0
	global_load_lds_dwordx4 v[214:215], off
	v_lshl_add_u64 v[214:215], s[26:27], 0, v[130:131]
	s_add_i32 m0, s28, 0x2000
	s_nop 0
	global_load_lds_dwordx4 v[214:215], off
	v_lshl_add_u64 v[214:215], v[218:219], 0, s[8:9]
	s_mov_b32 m0, s38
	s_nop 0
	global_load_lds_dwordx4 v[214:215], off
	v_lshl_add_u64 v[214:215], v[220:221], 0, s[8:9]
	s_mov_b32 m0, s39
	s_nop 0
	global_load_lds_dwordx4 v[214:215], off
	s_waitcnt vmcnt(8)
	s_waitcnt lgkmcnt(0)
	s_barrier
	s_setprio 0
	s_waitcnt lgkmcnt(0)
	v_mfma_f32_16x16x32_bf16 v[60:63], v[140:143], v[182:185], v[60:63]
	v_mfma_f32_16x16x32_bf16 v[56:59], v[158:161], v[182:185], v[56:59]
	v_mfma_f32_16x16x32_bf16 v[44:47], v[140:143], v[190:193], v[44:47]
	v_mfma_f32_16x16x32_bf16 v[40:43], v[158:161], v[190:193], v[40:43]
	v_mfma_f32_16x16x32_bf16 v[28:31], v[140:143], v[198:201], v[28:31]
	v_mfma_f32_16x16x32_bf16 v[24:27], v[158:161], v[198:201], v[24:27]
	v_mfma_f32_16x16x32_bf16 v[12:15], v[140:143], v[206:209], v[12:15]
	v_mfma_f32_16x16x32_bf16 v[8:11], v[158:161], v[206:209], v[8:11]
	v_mfma_f32_16x16x32_bf16 v[60:63], v[154:157], v[186:189], v[60:63]
	v_mfma_f32_16x16x32_bf16 v[56:59], v[162:165], v[186:189], v[56:59]
	v_mfma_f32_16x16x32_bf16 v[44:47], v[154:157], v[194:197], v[44:47]
	v_mfma_f32_16x16x32_bf16 v[40:43], v[162:165], v[194:197], v[40:43]
	v_mfma_f32_16x16x32_bf16 v[28:31], v[154:157], v[202:205], v[28:31]
	v_mfma_f32_16x16x32_bf16 v[24:27], v[162:165], v[202:205], v[24:27]
	v_mfma_f32_16x16x32_bf16 v[12:15], v[154:157], v[210:213], v[12:15]
	v_mfma_f32_16x16x32_bf16 v[8:11], v[162:165], v[210:213], v[8:11]
	s_setprio 1
	s_setprio 0
	v_mfma_f32_16x16x32_bf16 v[52:55], v[166:169], v[182:185], v[52:55]
	v_mfma_f32_16x16x32_bf16 v[48:51], v[174:177], v[182:185], v[48:51]
	v_mfma_f32_16x16x32_bf16 v[36:39], v[166:169], v[190:193], v[36:39]
	v_mfma_f32_16x16x32_bf16 v[32:35], v[174:177], v[190:193], v[32:35]
	v_mfma_f32_16x16x32_bf16 v[20:23], v[166:169], v[198:201], v[20:23]
	v_mfma_f32_16x16x32_bf16 v[16:19], v[174:177], v[198:201], v[16:19]
	v_mfma_f32_16x16x32_bf16 v[4:7], v[166:169], v[206:209], v[4:7]
	v_mfma_f32_16x16x32_bf16 v[0:3], v[174:177], v[206:209], v[0:3]
	v_mfma_f32_16x16x32_bf16 v[52:55], v[170:173], v[186:189], v[52:55]
	v_mfma_f32_16x16x32_bf16 v[48:51], v[178:181], v[186:189], v[48:51]
	v_mfma_f32_16x16x32_bf16 v[36:39], v[170:173], v[194:197], v[36:39]
	v_mfma_f32_16x16x32_bf16 v[32:35], v[178:181], v[194:197], v[32:35]
	v_mfma_f32_16x16x32_bf16 v[20:23], v[170:173], v[202:205], v[20:23]
	v_mfma_f32_16x16x32_bf16 v[16:19], v[178:181], v[202:205], v[16:19]
	v_mfma_f32_16x16x32_bf16 v[4:7], v[170:173], v[210:213], v[4:7]
	v_mfma_f32_16x16x32_bf16 v[0:3], v[178:181], v[210:213], v[0:3]
	s_setprio 1
	s_barrier
	s_add_i32 s60, s60, 2
	s_add_u32 s24, s24, 0x100
	s_addc_u32 s25, s25, 0
	s_add_u32 s58, s58, 0x100
	s_addc_u32 s59, s59, 0
	s_cmp_gt_u32 s60, 13
	s_cbranch_scc0 .LBB0_1400
	s_and_b64 vcc, exec, s[10:11]
	s_cbranch_vccz .LBB0_1403
	s_barrier

; #define PG8_STAGE(bufoff, gbase, voff) do { _Pragma("unroll") for (int _i = 0; _i < 2; ++_i) \
;         __builtin_amdgcn_global_load_lds((const unsigned*)((const char*)(gbase) + (voff)[_i]), (PG8_LAS unsigned*)(lds + (bufoff) + ldsw + _i * 8192), 16, 0, 0); } while (0)
; #define PG8_LDA(dst, b, h) do { _Pragma("unroll") for (int m = 0; m < 4; ++m) _Pragma("unroll") for (int k = 0; k < 2; ++k) dst[m][k] = *(const PG8_LAS bf16x8*)(lds + PG8_SA(b, h) + aoff + m * 2048 + k * 1024); } while (0)
; #define PG8_LDB(dst, b, h) do { _Pragma("unroll") for (int n = 0; n < 2; ++n) _Pragma("unroll") for (int k = 0; k < 2; ++k) dst[n][k] = *(const PG8_LAS bf16x8*)(lds + PG8_SB(b, h) + boff + n * 2048 + k * 1024); } while (0)
; #define PG8_MMA(ai, bj, At, Bt) do { __builtin_amdgcn_s_setprio(1); _Pragma("unroll") for (int m = 0; m < 4; ++m) _Pragma("unroll") for (int n = 0; n < 2; ++n) _Pragma("unroll") for (int k = 0; k < 2; ++k) \
;         acc[ai][bj][m][n] = __builtin_amdgcn_mfma_f32_16x16x32_bf16(Bt[n][k], At[m][k], acc[ai][bj][m][n], 0, 0, 0); __builtin_amdgcn_s_setprio(0); } while (0)
; #define PG8_WAIT_V(n) asm volatile("s_waitcnt vmcnt(" #n ")" ::: "memory")
; #define PG8_WAIT_L(n) asm volatile("s_waitcnt lgkmcnt(" #n ")" ::: "memory")
; #define PG8_BAR __builtin_amdgcn_s_barrier()
; #define PG8_SCHED __builtin_amdgcn_sched_barrier(0)
; template <class Epi, class Sched, bool ALIGN_EPI = false, bool SP2 = false>
; __device__ __forceinline__ void gemm_phase(PG8_LAS unsigned char* lds, const Gemm g, const Sched& S, const Epi& E) {
;     ...
;             const bool last = (t == nt - 2);
;             const char* a1 = cA + (size_t)(t + 1) * kstep;
;             const char* a2 = last ? nA : cA + (size_t)(t + 2) * kstep; const char* b2 = last ? nB : cB + (size_t)(t + 2) * kstep;
;     ...
;             PG8_LDB(B0, 0, 0); PG8_LDB(B1, 0, 1); PG8_SCHED; PG8_LDA(At, 0, 0); PG8_STAGE(PG8_SA(1, 1), a1 + hstep, voffA);
;             PG8_WAIT_V(8); PG8_WAIT_L(0); PG8_BAR; PG8_MMA(0, 0, At, B0); PG8_MMA(0, 1, At, B1); PG8_BAR; PG8_SCHED;
;             PG8_LDA(At, 0, 1); PG8_STAGE(PG8_SB(0, 0), b2, voffB); PG8_STAGE(PG8_SB(0, 1), b2 + hstep, voffB); PG8_STAGE(PG8_SA(0, 0), a2, voffA);
.LBB0_1487:
	ds_read_b128 v[144:147], v155
	ds_read_b128 v[160:163], v155 offset:1024
	ds_read_b128 v[164:167], v155 offset:2048
	ds_read_b128 v[168:171], v155 offset:3072
	ds_read_b128 v[172:175], v156
	ds_read_b128 v[176:179], v156 offset:1024
	ds_read_b128 v[180:183], v156 offset:2048
	ds_read_b128 v[184:187], v156 offset:3072
	s_add_u32 s6, s4, 0xfffc0080
	s_addc_u32 s7, s5, -1
	s_cmp_eq_u32 s51, 12
	s_cselect_b32 s9, s10, s7
	s_cselect_b32 s8, s11, s6
	s_cselect_b32 s7, s21, s50
	s_cselect_b32 s6, s23, s45
	v_lshl_add_u64 v[152:153], s[4:5], 0, v[136:137]
	s_add_i32 m0, s31, 0xc000
	ds_read_b128 v[188:191], v157
	ds_read_b128 v[192:195], v157 offset:1024
	ds_read_b128 v[196:199], v157 offset:2048
	ds_read_b128 v[200:203], v157 offset:3072
	ds_read_b128 v[204:207], v157 offset:4096
	ds_read_b128 v[208:211], v157 offset:5120
	ds_read_b128 v[212:215], v157 offset:6144
	ds_read_b128 v[216:219], v157 offset:7168
	global_load_lds_dwordx4 v[152:153], off
	v_lshl_add_u64 v[152:153], s[4:5], 0, v[138:139]
	s_add_i32 m0, s31, 0xe000
	s_nop 0
	global_load_lds_dwordx4 v[152:153], off
	s_waitcnt vmcnt(8)
	s_waitcnt lgkmcnt(0)
	s_barrier
	s_setprio 0
	s_waitcnt lgkmcnt(0)
	v_mfma_f32_16x16x32_bf16 v[124:127], v[144:147], v[188:191], v[124:127]
	v_mfma_f32_16x16x32_bf16 v[116:119], v[164:167], v[188:191], v[116:119]
	v_mfma_f32_16x16x32_bf16 v[108:111], v[144:147], v[196:199], v[108:111]
	v_mfma_f32_16x16x32_bf16 v[100:103], v[164:167], v[196:199], v[100:103]
	v_mfma_f32_16x16x32_bf16 v[92:95], v[144:147], v[204:207], v[92:95]
	v_mfma_f32_16x16x32_bf16 v[84:87], v[164:167], v[204:207], v[84:87]
	v_mfma_f32_16x16x32_bf16 v[76:79], v[144:147], v[212:215], v[76:79]
	v_mfma_f32_16x16x32_bf16 v[68:71], v[164:167], v[212:215], v[68:71]
	v_mfma_f32_16x16x32_bf16 v[124:127], v[160:163], v[192:195], v[124:127]
	v_mfma_f32_16x16x32_bf16 v[116:119], v[168:171], v[192:195], v[116:119]
	v_mfma_f32_16x16x32_bf16 v[108:111], v[160:163], v[200:203], v[108:111]
	v_mfma_f32_16x16x32_bf16 v[100:103], v[168:171], v[200:203], v[100:103]
	v_mfma_f32_16x16x32_bf16 v[92:95], v[160:163], v[208:211], v[92:95]
	v_mfma_f32_16x16x32_bf16 v[84:87], v[168:171], v[208:211], v[84:87]
	v_mfma_f32_16x16x32_bf16 v[76:79], v[160:163], v[216:219], v[76:79]
	v_mfma_f32_16x16x32_bf16 v[68:71], v[168:171], v[216:219], v[68:71]
	s_setprio 1
	s_setprio 0
	v_mfma_f32_16x16x32_bf16 v[120:123], v[172:175], v[188:191], v[120:123]
	v_mfma_f32_16x16x32_bf16 v[112:115], v[180:183], v[188:191], v[112:115]
	v_mfma_f32_16x16x32_bf16 v[104:107], v[172:175], v[196:199], v[104:107]
	v_mfma_f32_16x16x32_bf16 v[96:99], v[180:183], v[196:199], v[96:99]
	v_mfma_f32_16x16x32_bf16 v[88:91], v[172:175], v[204:207], v[88:91]
	v_mfma_f32_16x16x32_bf16 v[80:83], v[180:183], v[204:207], v[80:83]
	v_mfma_f32_16x16x32_bf16 v[72:75], v[172:175], v[212:215], v[72:75]
	v_mfma_f32_16x16x32_bf16 v[64:67], v[180:183], v[212:215], v[64:67]
	v_mfma_f32_16x16x32_bf16 v[120:123], v[176:179], v[192:195], v[120:123]
	v_mfma_f32_16x16x32_bf16 v[112:115], v[184:187], v[192:195], v[112:115]
	v_mfma_f32_16x16x32_bf16 v[104:107], v[176:179], v[200:203], v[104:107]
	v_mfma_f32_16x16x32_bf16 v[96:99], v[184:187], v[200:203], v[96:99]
	v_mfma_f32_16x16x32_bf16 v[88:91], v[176:179], v[208:211], v[88:91]
	v_mfma_f32_16x16x32_bf16 v[80:83], v[184:187], v[208:211], v[80:83]
	v_mfma_f32_16x16x32_bf16 v[72:75], v[176:179], v[216:219], v[72:75]
	v_mfma_f32_16x16x32_bf16 v[64:67], v[184:187], v[216:219], v[64:67]
	s_setprio 1
	s_barrier
	s_add_i32 s52, s41, s28
	v_lshl_add_u64 v[152:153], s[6:7], 0, v[132:133]
	s_mov_b32 m0, s52
	ds_read_b128 v[188:191], v157 offset:16384
	ds_read_b128 v[192:195], v157 offset:17408
	ds_read_b128 v[196:199], v157 offset:18432
	ds_read_b128 v[200:203], v157 offset:19456
	ds_read_b128 v[204:207], v157 offset:20480
	ds_read_b128 v[208:211], v157 offset:21504
	ds_read_b128 v[212:215], v157 offset:22528
	ds_read_b128 v[216:219], v157 offset:23552
	global_load_lds_dwordx4 v[152:153], off
	s_add_i32 m0, s52, 0x2000
	s_add_u32 s52, s6, 0x40000
	v_lshl_add_u64 v[220:221], s[6:7], 0, v[128:129]
	s_addc_u32 s53, s7, 0
	s_add_i32 s54, s42, s28
	global_load_lds_dwordx4 v[220:221], off
	v_lshl_add_u64 v[222:223], s[52:53], 0, v[132:133]
	s_mov_b32 m0, s54
	v_lshl_add_u64 v[224:225], s[8:9], 0, v[130:131]
	global_load_lds_dwordx4 v[222:223], off
	v_lshl_add_u64 v[222:223], s[52:53], 0, v[128:129]
	s_add_i32 m0, s54, 0x2000
	s_nop 0
	global_load_lds_dwordx4 v[222:223], off
	v_lshl_add_u64 v[222:223], s[8:9], 0, v[134:135]
	s_mov_b32 m0, s31
	s_nop 0
	global_load_lds_dwordx4 v[222:223], off
	s_mov_b32 m0, s34
	s_nop 0
	global_load_lds_dwordx4 v[224:225], off
	s_waitcnt vmcnt(8)
	s_waitcnt lgkmcnt(0)
	s_barrier
; #define PG8_STAGE(bufoff, gbase, voff) do { _Pragma("unroll") for (int _i = 0; _i < 2; ++_i) \
;         __builtin_amdgcn_global_load_lds((const unsigned*)((const char*)(gbase) + (voff)[_i]), (PG8_LAS unsigned*)(lds + (bufoff) + ldsw + _i * 8192), 16, 0, 0); } while (0)
; #define PG8_LDA(dst, b, h) do { _Pragma("unroll") for (int m = 0; m < 4; ++m) _Pragma("unroll") for (int k = 0; k < 2; ++k) dst[m][k] = *(const PG8_LAS bf16x8*)(lds + PG8_SA(b, h) + aoff + m * 2048 + k * 1024); } while (0)
; #define PG8_LDB(dst, b, h) do { _Pragma("unroll") for (int n = 0; n < 2; ++n) _Pragma("unroll") for (int k = 0; k < 2; ++k) dst[n][k] = *(const PG8_LAS bf16x8*)(lds + PG8_SB(b, h) + boff + n * 2048 + k * 1024); } while (0)
; #define PG8_MMA(ai, bj, At, Bt) do { __builtin_amdgcn_s_setprio(1); _Pragma("unroll") for (int m = 0; m < 4; ++m) _Pragma("unroll") for (int n = 0; n < 2; ++n) _Pragma("unroll") for (int k = 0; k < 2; ++k) \
;         acc[ai][bj][m][n] = __builtin_amdgcn_mfma_f32_16x16x32_bf16(Bt[n][k], At[m][k], acc[ai][bj][m][n], 0, 0, 0); __builtin_amdgcn_s_setprio(0); } while (0)
; #define PG8_WAIT_V(n) asm volatile("s_waitcnt vmcnt(" #n ")" ::: "memory")
; #define PG8_WAIT_L(n) asm volatile("s_waitcnt lgkmcnt(" #n ")" ::: "memory")
; #define PG8_BAR __builtin_amdgcn_s_barrier()
; #define PG8_SCHED __builtin_amdgcn_sched_barrier(0)
; template <class Epi, class Sched, bool ALIGN_EPI = false, bool SP2 = false>
; __device__ __forceinline__ void gemm_phase(PG8_LAS unsigned char* lds, const Gemm g, const Sched& S, const Epi& E) {
;     ...
;             PG8_WAIT_V(8); PG8_WAIT_L(0); PG8_BAR; PG8_MMA(1, 0, At, B0); PG8_MMA(1, 1, At, B1); PG8_BAR; PG8_SCHED;
;             PG8_LDB(B0, 1, 0); PG8_LDB(B1, 1, 1); PG8_SCHED; PG8_LDA(At, 1, 0); PG8_STAGE(PG8_SA(0, 1), a2 + hstep, voffA);
;             PG8_WAIT_V(8); PG8_WAIT_L(0); PG8_BAR; PG8_MMA(0, 0, At, B0); PG8_MMA(0, 1, At, B1); PG8_BAR; PG8_SCHED;
	s_setprio 0
	s_waitcnt lgkmcnt(0)
	v_mfma_f32_16x16x32_bf16 v[60:63], v[144:147], v[188:191], v[60:63]
	v_mfma_f32_16x16x32_bf16 v[52:55], v[164:167], v[188:191], v[52:55]
	v_mfma_f32_16x16x32_bf16 v[44:47], v[144:147], v[196:199], v[44:47]
	v_mfma_f32_16x16x32_bf16 v[36:39], v[164:167], v[196:199], v[36:39]
	v_mfma_f32_16x16x32_bf16 v[28:31], v[144:147], v[204:207], v[28:31]
	v_mfma_f32_16x16x32_bf16 v[20:23], v[164:167], v[204:207], v[20:23]
	v_mfma_f32_16x16x32_bf16 v[12:15], v[144:147], v[212:215], v[12:15]
	v_mfma_f32_16x16x32_bf16 v[4:7], v[164:167], v[212:215], v[4:7]
	v_mfma_f32_16x16x32_bf16 v[60:63], v[160:163], v[192:195], v[60:63]
	v_mfma_f32_16x16x32_bf16 v[52:55], v[168:171], v[192:195], v[52:55]
	v_mfma_f32_16x16x32_bf16 v[44:47], v[160:163], v[200:203], v[44:47]
	v_mfma_f32_16x16x32_bf16 v[36:39], v[168:171], v[200:203], v[36:39]
	v_mfma_f32_16x16x32_bf16 v[28:31], v[160:163], v[208:211], v[28:31]
	v_mfma_f32_16x16x32_bf16 v[20:23], v[168:171], v[208:211], v[20:23]
	v_mfma_f32_16x16x32_bf16 v[12:15], v[160:163], v[216:219], v[12:15]
	v_mfma_f32_16x16x32_bf16 v[4:7], v[168:171], v[216:219], v[4:7]
	s_setprio 1
	s_setprio 0
	v_mfma_f32_16x16x32_bf16 v[56:59], v[172:175], v[188:191], v[56:59]
	v_mfma_f32_16x16x32_bf16 v[48:51], v[180:183], v[188:191], v[48:51]
	v_mfma_f32_16x16x32_bf16 v[40:43], v[172:175], v[196:199], v[40:43]
	v_mfma_f32_16x16x32_bf16 v[32:35], v[180:183], v[196:199], v[32:35]
	v_mfma_f32_16x16x32_bf16 v[24:27], v[172:175], v[204:207], v[24:27]
	v_mfma_f32_16x16x32_bf16 v[16:19], v[180:183], v[204:207], v[16:19]
	v_mfma_f32_16x16x32_bf16 v[8:11], v[172:175], v[212:215], v[8:11]
	v_mfma_f32_16x16x32_bf16 v[0:3], v[180:183], v[212:215], v[0:3]
	v_mfma_f32_16x16x32_bf16 v[56:59], v[176:179], v[192:195], v[56:59]
	v_mfma_f32_16x16x32_bf16 v[48:51], v[184:187], v[192:195], v[48:51]
	v_mfma_f32_16x16x32_bf16 v[40:43], v[176:179], v[200:203], v[40:43]
	v_mfma_f32_16x16x32_bf16 v[32:35], v[184:187], v[200:203], v[32:35]
	v_mfma_f32_16x16x32_bf16 v[24:27], v[176:179], v[208:211], v[24:27]
	v_mfma_f32_16x16x32_bf16 v[16:19], v[184:187], v[208:211], v[16:19]
	v_mfma_f32_16x16x32_bf16 v[8:11], v[176:179], v[216:219], v[8:11]
	v_mfma_f32_16x16x32_bf16 v[0:3], v[184:187], v[216:219], v[0:3]
	s_setprio 1
	s_barrier
	s_add_i32 s52, 0, 0x18000
	v_add_u32_e32 v159, s52, v151
	s_add_i32 s53, 0, 0x1c000
	ds_read_b128 v[144:147], v159
	ds_read_b128 v[160:163], v159 offset:1024
	ds_read_b128 v[164:167], v159 offset:2048
	ds_read_b128 v[168:171], v159 offset:3072
	v_add_u32_e32 v159, s53, v151
	ds_read_b128 v[172:175], v159
	ds_read_b128 v[176:179], v159 offset:1024
	ds_read_b128 v[180:183], v159 offset:2048
	ds_read_b128 v[184:187], v159 offset:3072
	s_add_u32 s8, s8, 0x40000
	s_addc_u32 s9, s9, 0
	s_mov_b32 m0, s35
	v_lshl_add_u64 v[226:227], s[8:9], 0, v[134:135]
	ds_read_b128 v[188:191], v157 offset:32768
	ds_read_b128 v[192:195], v157 offset:33792
	ds_read_b128 v[196:199], v157 offset:34816
	ds_read_b128 v[200:203], v157 offset:35840
	ds_read_b128 v[204:207], v157 offset:36864
	ds_read_b128 v[208:211], v157 offset:37888
	ds_read_b128 v[212:215], v157 offset:38912
	ds_read_b128 v[216:219], v157 offset:39936
	global_load_lds_dwordx4 v[226:227], off
	v_lshl_add_u64 v[226:227], s[8:9], 0, v[130:131]
	s_mov_b32 m0, s36
	s_nop 0
	global_load_lds_dwordx4 v[226:227], off
	s_waitcnt vmcnt(8)
	s_waitcnt lgkmcnt(0)
	s_barrier
	s_setprio 0
	s_waitcnt lgkmcnt(0)
	v_mfma_f32_16x16x32_bf16 v[124:127], v[144:147], v[188:191], v[124:127]
	v_mfma_f32_16x16x32_bf16 v[116:119], v[164:167], v[188:191], v[116:119]
	v_mfma_f32_16x16x32_bf16 v[108:111], v[144:147], v[196:199], v[108:111]
	v_mfma_f32_16x16x32_bf16 v[100:103], v[164:167], v[196:199], v[100:103]
	v_mfma_f32_16x16x32_bf16 v[92:95], v[144:147], v[204:207], v[92:95]
	v_mfma_f32_16x16x32_bf16 v[84:87], v[164:167], v[204:207], v[84:87]
	v_mfma_f32_16x16x32_bf16 v[76:79], v[144:147], v[212:215], v[76:79]
	v_mfma_f32_16x16x32_bf16 v[68:71], v[164:167], v[212:215], v[68:71]
	v_mfma_f32_16x16x32_bf16 v[124:127], v[160:163], v[192:195], v[124:127]
	v_mfma_f32_16x16x32_bf16 v[116:119], v[168:171], v[192:195], v[116:119]
	v_mfma_f32_16x16x32_bf16 v[108:111], v[160:163], v[200:203], v[108:111]
	v_mfma_f32_16x16x32_bf16 v[100:103], v[168:171], v[200:203], v[100:103]
	v_mfma_f32_16x16x32_bf16 v[92:95], v[160:163], v[208:211], v[92:95]
	v_mfma_f32_16x16x32_bf16 v[84:87], v[168:171], v[208:211], v[84:87]
	v_mfma_f32_16x16x32_bf16 v[76:79], v[160:163], v[216:219], v[76:79]
	v_mfma_f32_16x16x32_bf16 v[68:71], v[168:171], v[216:219], v[68:71]
	s_setprio 1
	s_setprio 0
	v_mfma_f32_16x16x32_bf16 v[120:123], v[172:175], v[188:191], v[120:123]
	v_mfma_f32_16x16x32_bf16 v[112:115], v[180:183], v[188:191], v[112:115]
	v_mfma_f32_16x16x32_bf16 v[104:107], v[172:175], v[196:199], v[104:107]
	v_mfma_f32_16x16x32_bf16 v[96:99], v[180:183], v[196:199], v[96:99]
	v_mfma_f32_16x16x32_bf16 v[88:91], v[172:175], v[204:207], v[88:91]
	v_mfma_f32_16x16x32_bf16 v[80:83], v[180:183], v[204:207], v[80:83]
	v_mfma_f32_16x16x32_bf16 v[72:75], v[172:175], v[212:215], v[72:75]
	v_mfma_f32_16x16x32_bf16 v[64:67], v[180:183], v[212:215], v[64:67]
	v_mfma_f32_16x16x32_bf16 v[120:123], v[176:179], v[192:195], v[120:123]
	v_mfma_f32_16x16x32_bf16 v[112:115], v[184:187], v[192:195], v[112:115]
	v_mfma_f32_16x16x32_bf16 v[104:107], v[176:179], v[200:203], v[104:107]
	v_mfma_f32_16x16x32_bf16 v[96:99], v[184:187], v[200:203], v[96:99]
	v_mfma_f32_16x16x32_bf16 v[88:91], v[176:179], v[208:211], v[88:91]
	v_mfma_f32_16x16x32_bf16 v[80:83], v[184:187], v[208:211], v[80:83]
	v_mfma_f32_16x16x32_bf16 v[72:75], v[176:179], v[216:219], v[72:75]
	v_mfma_f32_16x16x32_bf16 v[64:67], v[184:187], v[216:219], v[64:67]
	s_setprio 1
	s_barrier
; #define PG8_STAGE(bufoff, gbase, voff) do { _Pragma("unroll") for (int _i = 0; _i < 2; ++_i) \
;         __builtin_amdgcn_global_load_lds((const unsigned*)((const char*)(gbase) + (voff)[_i]), (PG8_LAS unsigned*)(lds + (bufoff) + ldsw + _i * 8192), 16, 0, 0); } while (0)
; #define PG8_LDA(dst, b, h) do { _Pragma("unroll") for (int m = 0; m < 4; ++m) _Pragma("unroll") for (int k = 0; k < 2; ++k) dst[m][k] = *(const PG8_LAS bf16x8*)(lds + PG8_SA(b, h) + aoff + m * 2048 + k * 1024); } while (0)
; #define PG8_MMA(ai, bj, At, Bt) do { __builtin_amdgcn_s_setprio(1); _Pragma("unroll") for (int m = 0; m < 4; ++m) _Pragma("unroll") for (int n = 0; n < 2; ++n) _Pragma("unroll") for (int k = 0; k < 2; ++k) \
;         acc[ai][bj][m][n] = __builtin_amdgcn_mfma_f32_16x16x32_bf16(Bt[n][k], At[m][k], acc[ai][bj][m][n], 0, 0, 0); __builtin_amdgcn_s_setprio(0); } while (0)
; #define PG8_WAIT_V(n) asm volatile("s_waitcnt vmcnt(" #n ")" ::: "memory")
; #define PG8_WAIT_L(n) asm volatile("s_waitcnt lgkmcnt(" #n ")" ::: "memory")
; #define PG8_BAR __builtin_amdgcn_s_barrier()
; #define PG8_SCHED __builtin_amdgcn_sched_barrier(0)
; template <class Epi, class Sched, bool ALIGN_EPI = false, bool SP2 = false>
; __device__ __forceinline__ void gemm_phase(PG8_LAS unsigned char* lds, const Gemm g, const Sched& S, const Epi& E) {
;     ...
;         for (int t = 0; t < nt; t += 2) {
;             const bool last = (t == nt - 2);
;     ...
;             PG8_LDA(At, 1, 1); PG8_STAGE(PG8_SB(1, 0), b3, voffB); PG8_STAGE(PG8_SB(1, 1), b3 + hstep, voffB); PG8_STAGE(PG8_SA(1, 0), a3, voffA);
;             PG8_WAIT_V(8); PG8_WAIT_L(0); PG8_BAR; PG8_MMA(1, 0, At, B0); PG8_MMA(1, 1, At, B1); PG8_BAR; PG8_SCHED;
	s_add_i32 s8, s52, s28
	v_lshl_add_u64 v[152:153], v[152:153], 0, s[16:17]
	s_mov_b32 m0, s8
	ds_read_b128 v[188:191], v157 offset:49152
	ds_read_b128 v[192:195], v157 offset:50176
	ds_read_b128 v[196:199], v157 offset:51200
	ds_read_b128 v[200:203], v157 offset:52224
	ds_read_b128 v[204:207], v157 offset:53248
	ds_read_b128 v[208:211], v157 offset:54272
	ds_read_b128 v[212:215], v157 offset:55296
	ds_read_b128 v[216:219], v157 offset:56320
	global_load_lds_dwordx4 v[152:153], off
	s_add_i32 m0, s8, 0x2000
	s_add_u32 s6, s6, 0x40080
	v_lshl_add_u64 v[152:153], v[220:221], 0, s[16:17]
	s_addc_u32 s7, s7, 0
	s_add_i32 s8, s53, s28
	global_load_lds_dwordx4 v[152:153], off
	v_lshl_add_u64 v[152:153], s[6:7], 0, v[132:133]
	s_mov_b32 m0, s8
	s_nop 0
	global_load_lds_dwordx4 v[152:153], off
	v_lshl_add_u64 v[152:153], s[6:7], 0, v[128:129]
	s_add_i32 m0, s8, 0x2000
	s_nop 0
	global_load_lds_dwordx4 v[152:153], off
	v_lshl_add_u64 v[152:153], v[222:223], 0, s[16:17]
	s_mov_b32 m0, s38
	s_nop 0
	global_load_lds_dwordx4 v[152:153], off
	v_lshl_add_u64 v[152:153], v[224:225], 0, s[16:17]
	s_mov_b32 m0, s39
	s_nop 0
	global_load_lds_dwordx4 v[152:153], off
	s_waitcnt vmcnt(8)
	s_waitcnt lgkmcnt(0)
	s_barrier
	s_setprio 0
	s_waitcnt lgkmcnt(0)
	v_mfma_f32_16x16x32_bf16 v[60:63], v[144:147], v[188:191], v[60:63]
	v_mfma_f32_16x16x32_bf16 v[52:55], v[164:167], v[188:191], v[52:55]
	v_mfma_f32_16x16x32_bf16 v[44:47], v[144:147], v[196:199], v[44:47]
	v_mfma_f32_16x16x32_bf16 v[36:39], v[164:167], v[196:199], v[36:39]
	v_mfma_f32_16x16x32_bf16 v[28:31], v[144:147], v[204:207], v[28:31]
	v_mfma_f32_16x16x32_bf16 v[20:23], v[164:167], v[204:207], v[20:23]
	v_mfma_f32_16x16x32_bf16 v[12:15], v[144:147], v[212:215], v[12:15]
	v_mfma_f32_16x16x32_bf16 v[4:7], v[164:167], v[212:215], v[4:7]
	v_mfma_f32_16x16x32_bf16 v[60:63], v[160:163], v[192:195], v[60:63]
	v_mfma_f32_16x16x32_bf16 v[52:55], v[168:171], v[192:195], v[52:55]
	v_mfma_f32_16x16x32_bf16 v[44:47], v[160:163], v[200:203], v[44:47]
	v_mfma_f32_16x16x32_bf16 v[36:39], v[168:171], v[200:203], v[36:39]
	v_mfma_f32_16x16x32_bf16 v[28:31], v[160:163], v[208:211], v[28:31]
	v_mfma_f32_16x16x32_bf16 v[20:23], v[168:171], v[208:211], v[20:23]
	v_mfma_f32_16x16x32_bf16 v[12:15], v[160:163], v[216:219], v[12:15]
	v_mfma_f32_16x16x32_bf16 v[4:7], v[168:171], v[216:219], v[4:7]
	s_setprio 1
	s_setprio 0
	v_mfma_f32_16x16x32_bf16 v[56:59], v[172:175], v[188:191], v[56:59]
	v_mfma_f32_16x16x32_bf16 v[48:51], v[180:183], v[188:191], v[48:51]
	v_mfma_f32_16x16x32_bf16 v[40:43], v[172:175], v[196:199], v[40:43]
	v_mfma_f32_16x16x32_bf16 v[32:35], v[180:183], v[196:199], v[32:35]
	v_mfma_f32_16x16x32_bf16 v[24:27], v[172:175], v[204:207], v[24:27]
	v_mfma_f32_16x16x32_bf16 v[16:19], v[180:183], v[204:207], v[16:19]
	v_mfma_f32_16x16x32_bf16 v[8:11], v[172:175], v[212:215], v[8:11]
	v_mfma_f32_16x16x32_bf16 v[0:3], v[180:183], v[212:215], v[0:3]
	v_mfma_f32_16x16x32_bf16 v[56:59], v[176:179], v[192:195], v[56:59]
	v_mfma_f32_16x16x32_bf16 v[48:51], v[184:187], v[192:195], v[48:51]
	v_mfma_f32_16x16x32_bf16 v[40:43], v[176:179], v[200:203], v[40:43]
	v_mfma_f32_16x16x32_bf16 v[32:35], v[184:187], v[200:203], v[32:35]
	v_mfma_f32_16x16x32_bf16 v[24:27], v[176:179], v[208:211], v[24:27]
	v_mfma_f32_16x16x32_bf16 v[16:19], v[184:187], v[208:211], v[16:19]
	v_mfma_f32_16x16x32_bf16 v[8:11], v[176:179], v[216:219], v[8:11]
	v_mfma_f32_16x16x32_bf16 v[0:3], v[184:187], v[216:219], v[0:3]
	s_setprio 1
	s_barrier
	s_add_i32 s51, s51, 2
	s_add_u32 s4, s4, 0x100
	s_addc_u32 s5, s5, 0
	s_add_u32 s45, s45, 0x100
	s_addc_u32 s50, s50, 0
	s_cmp_gt_u32 s51, 13
	s_cbranch_scc0 .LBB0_1487
	s_and_b64 vcc, exec, s[18:19]
	s_cbranch_vccz .LBB0_1490
	s_barrier

; #define PG8_STAGE(bufoff, gbase, voff) do { _Pragma("unroll") for (int _i = 0; _i < 2; ++_i) \
;         __builtin_amdgcn_global_load_lds((const unsigned*)((const char*)(gbase) + (voff)[_i]), (PG8_LAS unsigned*)(lds + (bufoff) + ldsw + _i * 8192), 16, 0, 0); } while (0)
; #define PG8_LDA(dst, b, h) do { _Pragma("unroll") for (int m = 0; m < 4; ++m) _Pragma("unroll") for (int k = 0; k < 2; ++k) dst[m][k] = *(const PG8_LAS bf16x8*)(lds + PG8_SA(b, h) + aoff + m * 2048 + k * 1024); } while (0)
; #define PG8_LDB(dst, b, h) do { _Pragma("unroll") for (int n = 0; n < 2; ++n) _Pragma("unroll") for (int k = 0; k < 2; ++k) dst[n][k] = *(const PG8_LAS bf16x8*)(lds + PG8_SB(b, h) + boff + n * 2048 + k * 1024); } while (0)
; #define PG8_MMA(ai, bj, At, Bt) do { __builtin_amdgcn_s_setprio(1); _Pragma("unroll") for (int m = 0; m < 4; ++m) _Pragma("unroll") for (int n = 0; n < 2; ++n) _Pragma("unroll") for (int k = 0; k < 2; ++k) \
;         acc[ai][bj][m][n] = __builtin_amdgcn_mfma_f32_16x16x32_bf16(Bt[n][k], At[m][k], acc[ai][bj][m][n], 0, 0, 0); __builtin_amdgcn_s_setprio(0); } while (0)
; #define PG8_WAIT_V(n) asm volatile("s_waitcnt vmcnt(" #n ")" ::: "memory")
; #define PG8_WAIT_L(n) asm volatile("s_waitcnt lgkmcnt(" #n ")" ::: "memory")
; #define PG8_BAR __builtin_amdgcn_s_barrier()
; #define PG8_SCHED __builtin_amdgcn_sched_barrier(0)
; template <class Epi, class Sched, bool ALIGN_EPI = false, bool SP2 = false>
; __device__ __forceinline__ void gemm_phase(PG8_LAS unsigned char* lds, const Gemm g, const Sched& S, const Epi& E) {
;     ...
;             const bool last = (t == nt - 2);
;             const char* a1 = cA + (size_t)(t + 1) * kstep;
;             const char* a2 = last ? nA : cA + (size_t)(t + 2) * kstep; const char* b2 = last ? nB : cB + (size_t)(t + 2) * kstep;
;     ...
;             PG8_LDB(B0, 0, 0); PG8_LDB(B1, 0, 1); PG8_SCHED; PG8_LDA(At, 0, 0); PG8_STAGE(PG8_SA(1, 1), a1 + hstep, voffA);
;             PG8_WAIT_V(8); PG8_WAIT_L(0); PG8_BAR; PG8_MMA(0, 0, At, B0); PG8_MMA(0, 1, At, B1); PG8_BAR; PG8_SCHED;
;             PG8_LDA(At, 0, 1); PG8_STAGE(PG8_SB(0, 0), b2, voffB); PG8_STAGE(PG8_SB(0, 1), b2 + hstep, voffB); PG8_STAGE(PG8_SA(0, 0), a2, voffA);
.LBB0_1572:
	ds_read_b128 v[140:143], v189
	ds_read_b128 v[144:147], v189 offset:1024
	ds_read_b128 v[152:155], v189 offset:2048
	ds_read_b128 v[156:159], v189 offset:3072
	ds_read_b128 v[160:163], v190
	ds_read_b128 v[164:167], v190 offset:1024
	ds_read_b128 v[168:171], v190 offset:2048
	ds_read_b128 v[172:175], v190 offset:3072
	s_add_u32 s22, s20, 0xfff50080
	s_addc_u32 s23, s21, -1
	s_cmp_eq_u32 s47, 40
	s_cselect_b32 s25, s1, s23
	s_cselect_b32 s24, s0, s22
	s_cselect_b32 s23, s19, s46
	s_cselect_b32 s22, s18, s45
	v_lshl_add_u64 v[214:215], s[20:21], 0, v[132:133]
	s_add_i32 m0, s27, 0xc000
	ds_read_b128 v[176:179], v191
	ds_read_b128 v[180:183], v191 offset:1024
	ds_read_b128 v[184:187], v191 offset:2048
	ds_read_b128 v[194:197], v191 offset:3072
	ds_read_b128 v[198:201], v191 offset:4096
	ds_read_b128 v[202:205], v191 offset:5120
	ds_read_b128 v[206:209], v191 offset:6144
	ds_read_b128 v[210:213], v191 offset:7168
	global_load_lds_dwordx4 v[214:215], off
	v_lshl_add_u64 v[214:215], s[20:21], 0, v[134:135]
	s_add_i32 m0, s27, 0xe000
	s_nop 0
	global_load_lds_dwordx4 v[214:215], off
	s_waitcnt vmcnt(8)
	s_waitcnt lgkmcnt(0)
	s_barrier
	s_setprio 0
	s_waitcnt lgkmcnt(0)
	v_mfma_f32_16x16x32_bf16 v[124:127], v[140:143], v[176:179], v[124:127]
	v_mfma_f32_16x16x32_bf16 v[120:123], v[152:155], v[176:179], v[120:123]
	v_mfma_f32_16x16x32_bf16 v[108:111], v[140:143], v[184:187], v[108:111]
	v_mfma_f32_16x16x32_bf16 v[104:107], v[152:155], v[184:187], v[104:107]
	v_mfma_f32_16x16x32_bf16 v[92:95], v[140:143], v[198:201], v[92:95]
	v_mfma_f32_16x16x32_bf16 v[88:91], v[152:155], v[198:201], v[88:91]
	v_mfma_f32_16x16x32_bf16 v[76:79], v[140:143], v[206:209], v[76:79]
	v_mfma_f32_16x16x32_bf16 v[72:75], v[152:155], v[206:209], v[72:75]
	v_mfma_f32_16x16x32_bf16 v[124:127], v[144:147], v[180:183], v[124:127]
	v_mfma_f32_16x16x32_bf16 v[120:123], v[156:159], v[180:183], v[120:123]
	v_mfma_f32_16x16x32_bf16 v[108:111], v[144:147], v[194:197], v[108:111]
	v_mfma_f32_16x16x32_bf16 v[104:107], v[156:159], v[194:197], v[104:107]
	v_mfma_f32_16x16x32_bf16 v[92:95], v[144:147], v[202:205], v[92:95]
	v_mfma_f32_16x16x32_bf16 v[88:91], v[156:159], v[202:205], v[88:91]
	v_mfma_f32_16x16x32_bf16 v[76:79], v[144:147], v[210:213], v[76:79]
	v_mfma_f32_16x16x32_bf16 v[72:75], v[156:159], v[210:213], v[72:75]
	s_setprio 1
	s_setprio 0
	v_mfma_f32_16x16x32_bf16 v[116:119], v[160:163], v[176:179], v[116:119]
	v_mfma_f32_16x16x32_bf16 v[112:115], v[168:171], v[176:179], v[112:115]
	v_mfma_f32_16x16x32_bf16 v[100:103], v[160:163], v[184:187], v[100:103]
	v_mfma_f32_16x16x32_bf16 v[96:99], v[168:171], v[184:187], v[96:99]
	v_mfma_f32_16x16x32_bf16 v[84:87], v[160:163], v[198:201], v[84:87]
	v_mfma_f32_16x16x32_bf16 v[80:83], v[168:171], v[198:201], v[80:83]
	v_mfma_f32_16x16x32_bf16 v[68:71], v[160:163], v[206:209], v[68:71]
	v_mfma_f32_16x16x32_bf16 v[64:67], v[168:171], v[206:209], v[64:67]
	v_mfma_f32_16x16x32_bf16 v[116:119], v[164:167], v[180:183], v[116:119]
	v_mfma_f32_16x16x32_bf16 v[112:115], v[172:175], v[180:183], v[112:115]
	v_mfma_f32_16x16x32_bf16 v[100:103], v[164:167], v[194:197], v[100:103]
	v_mfma_f32_16x16x32_bf16 v[96:99], v[172:175], v[194:197], v[96:99]
	v_mfma_f32_16x16x32_bf16 v[84:87], v[164:167], v[202:205], v[84:87]
	v_mfma_f32_16x16x32_bf16 v[80:83], v[172:175], v[202:205], v[80:83]
	v_mfma_f32_16x16x32_bf16 v[68:71], v[164:167], v[210:213], v[68:71]
	v_mfma_f32_16x16x32_bf16 v[64:67], v[172:175], v[210:213], v[64:67]
	s_setprio 1
	s_barrier
	s_add_i32 s50, s38, s26
	v_lshl_add_u64 v[214:215], s[22:23], 0, v[128:129]
	s_mov_b32 m0, s50
	ds_read_b128 v[176:179], v191 offset:16384
	ds_read_b128 v[180:183], v191 offset:17408
	ds_read_b128 v[184:187], v191 offset:18432
	ds_read_b128 v[194:197], v191 offset:19456
	ds_read_b128 v[198:201], v191 offset:20480
	ds_read_b128 v[202:205], v191 offset:21504
	ds_read_b128 v[206:209], v191 offset:22528
	ds_read_b128 v[210:213], v191 offset:23552
	global_load_lds_dwordx4 v[214:215], off
	s_add_i32 m0, s50, 0x2000
	s_add_u32 s50, s22, 0xb0000
	v_lshl_add_u64 v[216:217], s[22:23], 0, v[130:131]
	s_addc_u32 s51, s23, 0
	s_add_i32 s52, s39, s26
	global_load_lds_dwordx4 v[216:217], off
	v_lshl_add_u64 v[218:219], s[50:51], 0, v[128:129]
	s_mov_b32 m0, s52
	v_lshl_add_u64 v[220:221], s[24:25], 0, v[130:131]
	global_load_lds_dwordx4 v[218:219], off
	v_lshl_add_u64 v[218:219], s[50:51], 0, v[130:131]
	s_add_i32 m0, s52, 0x2000
	s_nop 0
	global_load_lds_dwordx4 v[218:219], off
	v_lshl_add_u64 v[218:219], s[24:25], 0, v[128:129]
	s_mov_b32 m0, s27
	s_nop 0
	global_load_lds_dwordx4 v[218:219], off
	s_mov_b32 m0, s28
	s_nop 0
	global_load_lds_dwordx4 v[220:221], off
	s_waitcnt vmcnt(8)
	s_waitcnt lgkmcnt(0)
	s_barrier
; #define PG8_STAGE(bufoff, gbase, voff) do { _Pragma("unroll") for (int _i = 0; _i < 2; ++_i) \
;         __builtin_amdgcn_global_load_lds((const unsigned*)((const char*)(gbase) + (voff)[_i]), (PG8_LAS unsigned*)(lds + (bufoff) + ldsw + _i * 8192), 16, 0, 0); } while (0)
; #define PG8_LDA(dst, b, h) do { _Pragma("unroll") for (int m = 0; m < 4; ++m) _Pragma("unroll") for (int k = 0; k < 2; ++k) dst[m][k] = *(const PG8_LAS bf16x8*)(lds + PG8_SA(b, h) + aoff + m * 2048 + k * 1024); } while (0)
; #define PG8_LDB(dst, b, h) do { _Pragma("unroll") for (int n = 0; n < 2; ++n) _Pragma("unroll") for (int k = 0; k < 2; ++k) dst[n][k] = *(const PG8_LAS bf16x8*)(lds + PG8_SB(b, h) + boff + n * 2048 + k * 1024); } while (0)
; #define PG8_MMA(ai, bj, At, Bt) do { __builtin_amdgcn_s_setprio(1); _Pragma("unroll") for (int m = 0; m < 4; ++m) _Pragma("unroll") for (int n = 0; n < 2; ++n) _Pragma("unroll") for (int k = 0; k < 2; ++k) \
;         acc[ai][bj][m][n] = __builtin_amdgcn_mfma_f32_16x16x32_bf16(Bt[n][k], At[m][k], acc[ai][bj][m][n], 0, 0, 0); __builtin_amdgcn_s_setprio(0); } while (0)
; #define PG8_WAIT_V(n) asm volatile("s_waitcnt vmcnt(" #n ")" ::: "memory")
; #define PG8_WAIT_L(n) asm volatile("s_waitcnt lgkmcnt(" #n ")" ::: "memory")
; #define PG8_BAR __builtin_amdgcn_s_barrier()
; #define PG8_SCHED __builtin_amdgcn_sched_barrier(0)
; template <class Epi, class Sched, bool ALIGN_EPI = false, bool SP2 = false>
; __device__ __forceinline__ void gemm_phase(PG8_LAS unsigned char* lds, const Gemm g, const Sched& S, const Epi& E) {
;     ...
;             PG8_WAIT_V(8); PG8_WAIT_L(0); PG8_BAR; PG8_MMA(1, 0, At, B0); PG8_MMA(1, 1, At, B1); PG8_BAR; PG8_SCHED;
;             PG8_LDB(B0, 1, 0); PG8_LDB(B1, 1, 1); PG8_SCHED; PG8_LDA(At, 1, 0); PG8_STAGE(PG8_SA(0, 1), a2 + hstep, voffA);
;             PG8_WAIT_V(8); PG8_WAIT_L(0); PG8_BAR; PG8_MMA(0, 0, At, B0); PG8_MMA(0, 1, At, B1); PG8_BAR; PG8_SCHED;
	s_setprio 0
	s_waitcnt lgkmcnt(0)
	v_mfma_f32_16x16x32_bf16 v[60:63], v[140:143], v[176:179], v[60:63]
	v_mfma_f32_16x16x32_bf16 v[56:59], v[152:155], v[176:179], v[56:59]
	v_mfma_f32_16x16x32_bf16 v[44:47], v[140:143], v[184:187], v[44:47]
	v_mfma_f32_16x16x32_bf16 v[40:43], v[152:155], v[184:187], v[40:43]
	v_mfma_f32_16x16x32_bf16 v[28:31], v[140:143], v[198:201], v[28:31]
	v_mfma_f32_16x16x32_bf16 v[24:27], v[152:155], v[198:201], v[24:27]
	v_mfma_f32_16x16x32_bf16 v[12:15], v[140:143], v[206:209], v[12:15]
	v_mfma_f32_16x16x32_bf16 v[8:11], v[152:155], v[206:209], v[8:11]
	v_mfma_f32_16x16x32_bf16 v[60:63], v[144:147], v[180:183], v[60:63]
	v_mfma_f32_16x16x32_bf16 v[56:59], v[156:159], v[180:183], v[56:59]
	v_mfma_f32_16x16x32_bf16 v[44:47], v[144:147], v[194:197], v[44:47]
	v_mfma_f32_16x16x32_bf16 v[40:43], v[156:159], v[194:197], v[40:43]
	v_mfma_f32_16x16x32_bf16 v[28:31], v[144:147], v[202:205], v[28:31]
	v_mfma_f32_16x16x32_bf16 v[24:27], v[156:159], v[202:205], v[24:27]
	v_mfma_f32_16x16x32_bf16 v[12:15], v[144:147], v[210:213], v[12:15]
	v_mfma_f32_16x16x32_bf16 v[8:11], v[156:159], v[210:213], v[8:11]
	s_setprio 1
	s_setprio 0
	v_mfma_f32_16x16x32_bf16 v[52:55], v[160:163], v[176:179], v[52:55]
	v_mfma_f32_16x16x32_bf16 v[48:51], v[168:171], v[176:179], v[48:51]
	v_mfma_f32_16x16x32_bf16 v[36:39], v[160:163], v[184:187], v[36:39]
	v_mfma_f32_16x16x32_bf16 v[32:35], v[168:171], v[184:187], v[32:35]
	v_mfma_f32_16x16x32_bf16 v[20:23], v[160:163], v[198:201], v[20:23]
	v_mfma_f32_16x16x32_bf16 v[16:19], v[168:171], v[198:201], v[16:19]
	v_mfma_f32_16x16x32_bf16 v[4:7], v[160:163], v[206:209], v[4:7]
	v_mfma_f32_16x16x32_bf16 v[0:3], v[168:171], v[206:209], v[0:3]
	v_mfma_f32_16x16x32_bf16 v[52:55], v[164:167], v[180:183], v[52:55]
	v_mfma_f32_16x16x32_bf16 v[48:51], v[172:175], v[180:183], v[48:51]
	v_mfma_f32_16x16x32_bf16 v[36:39], v[164:167], v[194:197], v[36:39]
	v_mfma_f32_16x16x32_bf16 v[32:35], v[172:175], v[194:197], v[32:35]
	v_mfma_f32_16x16x32_bf16 v[20:23], v[164:167], v[202:205], v[20:23]
	v_mfma_f32_16x16x32_bf16 v[16:19], v[172:175], v[202:205], v[16:19]
	v_mfma_f32_16x16x32_bf16 v[4:7], v[164:167], v[210:213], v[4:7]
	v_mfma_f32_16x16x32_bf16 v[0:3], v[172:175], v[210:213], v[0:3]
	s_setprio 1
	s_barrier
	s_add_i32 s50, 0, 0x18000
	s_add_i32 s51, 0, 0x1c000
	v_add_u32_e32 v156, s50, v151
	v_add_u32_e32 v172, s51, v151
	ds_read_b128 v[140:143], v156
	ds_read_b128 v[144:147], v156 offset:1024
	ds_read_b128 v[152:155], v156 offset:2048
	ds_read_b128 v[156:159], v156 offset:3072
	ds_read_b128 v[160:163], v172
	ds_read_b128 v[164:167], v172 offset:1024
	ds_read_b128 v[168:171], v172 offset:2048
	ds_read_b128 v[172:175], v172 offset:3072
	s_add_u32 s24, s24, 0xb0000
	s_addc_u32 s25, s25, 0
	s_mov_b32 m0, s29
	v_lshl_add_u64 v[222:223], s[24:25], 0, v[128:129]
	ds_read_b128 v[176:179], v191 offset:32768
	ds_read_b128 v[180:183], v191 offset:33792
	ds_read_b128 v[184:187], v191 offset:34816
	ds_read_b128 v[194:197], v191 offset:35840
	ds_read_b128 v[198:201], v191 offset:36864
	ds_read_b128 v[202:205], v191 offset:37888
	ds_read_b128 v[206:209], v191 offset:38912
	ds_read_b128 v[210:213], v191 offset:39936
	global_load_lds_dwordx4 v[222:223], off
	v_lshl_add_u64 v[222:223], s[24:25], 0, v[130:131]
	s_mov_b32 m0, s30
	s_nop 0
	global_load_lds_dwordx4 v[222:223], off
	s_waitcnt vmcnt(8)
	s_waitcnt lgkmcnt(0)
	s_barrier
	s_setprio 0
	s_waitcnt lgkmcnt(0)
	v_mfma_f32_16x16x32_bf16 v[124:127], v[140:143], v[176:179], v[124:127]
	v_mfma_f32_16x16x32_bf16 v[120:123], v[152:155], v[176:179], v[120:123]
	v_mfma_f32_16x16x32_bf16 v[108:111], v[140:143], v[184:187], v[108:111]
	v_mfma_f32_16x16x32_bf16 v[104:107], v[152:155], v[184:187], v[104:107]
	v_mfma_f32_16x16x32_bf16 v[92:95], v[140:143], v[198:201], v[92:95]
	v_mfma_f32_16x16x32_bf16 v[88:91], v[152:155], v[198:201], v[88:91]
	v_mfma_f32_16x16x32_bf16 v[76:79], v[140:143], v[206:209], v[76:79]
	v_mfma_f32_16x16x32_bf16 v[72:75], v[152:155], v[206:209], v[72:75]
	v_mfma_f32_16x16x32_bf16 v[124:127], v[144:147], v[180:183], v[124:127]
	v_mfma_f32_16x16x32_bf16 v[120:123], v[156:159], v[180:183], v[120:123]
	v_mfma_f32_16x16x32_bf16 v[108:111], v[144:147], v[194:197], v[108:111]
	v_mfma_f32_16x16x32_bf16 v[104:107], v[156:159], v[194:197], v[104:107]
	v_mfma_f32_16x16x32_bf16 v[92:95], v[144:147], v[202:205], v[92:95]
	v_mfma_f32_16x16x32_bf16 v[88:91], v[156:159], v[202:205], v[88:91]
	v_mfma_f32_16x16x32_bf16 v[76:79], v[144:147], v[210:213], v[76:79]
	v_mfma_f32_16x16x32_bf16 v[72:75], v[156:159], v[210:213], v[72:75]
	s_setprio 1
	s_setprio 0
	v_mfma_f32_16x16x32_bf16 v[116:119], v[160:163], v[176:179], v[116:119]
	v_mfma_f32_16x16x32_bf16 v[112:115], v[168:171], v[176:179], v[112:115]
	v_mfma_f32_16x16x32_bf16 v[100:103], v[160:163], v[184:187], v[100:103]
	v_mfma_f32_16x16x32_bf16 v[96:99], v[168:171], v[184:187], v[96:99]
	v_mfma_f32_16x16x32_bf16 v[84:87], v[160:163], v[198:201], v[84:87]
	v_mfma_f32_16x16x32_bf16 v[80:83], v[168:171], v[198:201], v[80:83]
	v_mfma_f32_16x16x32_bf16 v[68:71], v[160:163], v[206:209], v[68:71]
	v_mfma_f32_16x16x32_bf16 v[64:67], v[168:171], v[206:209], v[64:67]
	v_mfma_f32_16x16x32_bf16 v[116:119], v[164:167], v[180:183], v[116:119]
	v_mfma_f32_16x16x32_bf16 v[112:115], v[172:175], v[180:183], v[112:115]
	v_mfma_f32_16x16x32_bf16 v[100:103], v[164:167], v[194:197], v[100:103]
	v_mfma_f32_16x16x32_bf16 v[96:99], v[172:175], v[194:197], v[96:99]
	v_mfma_f32_16x16x32_bf16 v[84:87], v[164:167], v[202:205], v[84:87]
	v_mfma_f32_16x16x32_bf16 v[80:83], v[172:175], v[202:205], v[80:83]
	v_mfma_f32_16x16x32_bf16 v[68:71], v[164:167], v[210:213], v[68:71]
	v_mfma_f32_16x16x32_bf16 v[64:67], v[172:175], v[210:213], v[64:67]
	s_setprio 1
	s_barrier
; #define PG8_STAGE(bufoff, gbase, voff) do { _Pragma("unroll") for (int _i = 0; _i < 2; ++_i) \
;         __builtin_amdgcn_global_load_lds((const unsigned*)((const char*)(gbase) + (voff)[_i]), (PG8_LAS unsigned*)(lds + (bufoff) + ldsw + _i * 8192), 16, 0, 0); } while (0)
; #define PG8_LDA(dst, b, h) do { _Pragma("unroll") for (int m = 0; m < 4; ++m) _Pragma("unroll") for (int k = 0; k < 2; ++k) dst[m][k] = *(const PG8_LAS bf16x8*)(lds + PG8_SA(b, h) + aoff + m * 2048 + k * 1024); } while (0)
; #define PG8_MMA(ai, bj, At, Bt) do { __builtin_amdgcn_s_setprio(1); _Pragma("unroll") for (int m = 0; m < 4; ++m) _Pragma("unroll") for (int n = 0; n < 2; ++n) _Pragma("unroll") for (int k = 0; k < 2; ++k) \
;         acc[ai][bj][m][n] = __builtin_amdgcn_mfma_f32_16x16x32_bf16(Bt[n][k], At[m][k], acc[ai][bj][m][n], 0, 0, 0); __builtin_amdgcn_s_setprio(0); } while (0)
; #define PG8_WAIT_V(n) asm volatile("s_waitcnt vmcnt(" #n ")" ::: "memory")
; #define PG8_WAIT_L(n) asm volatile("s_waitcnt lgkmcnt(" #n ")" ::: "memory")
; #define PG8_BAR __builtin_amdgcn_s_barrier()
; #define PG8_SCHED __builtin_amdgcn_sched_barrier(0)
; template <class Epi, class Sched, bool ALIGN_EPI = false, bool SP2 = false>
; __device__ __forceinline__ void gemm_phase(PG8_LAS unsigned char* lds, const Gemm g, const Sched& S, const Epi& E) {
;     ...
;         for (int t = 0; t < nt; t += 2) {
;             const bool last = (t == nt - 2);
;     ...
;             PG8_LDA(At, 1, 1); PG8_STAGE(PG8_SB(1, 0), b3, voffB); PG8_STAGE(PG8_SB(1, 1), b3 + hstep, voffB); PG8_STAGE(PG8_SA(1, 0), a3, voffA);
;             PG8_WAIT_V(8); PG8_WAIT_L(0); PG8_BAR; PG8_MMA(1, 0, At, B0); PG8_MMA(1, 1, At, B1); PG8_BAR; PG8_SCHED;
	s_add_i32 s24, s50, s26
	v_lshl_add_u64 v[214:215], v[214:215], 0, s[14:15]
	s_mov_b32 m0, s24
	ds_read_b128 v[176:179], v191 offset:49152
	ds_read_b128 v[180:183], v191 offset:50176
	ds_read_b128 v[184:187], v191 offset:51200
	ds_read_b128 v[194:197], v191 offset:52224
	ds_read_b128 v[198:201], v191 offset:53248
	ds_read_b128 v[202:205], v191 offset:54272
	ds_read_b128 v[206:209], v191 offset:55296
	ds_read_b128 v[210:213], v191 offset:56320
	global_load_lds_dwordx4 v[214:215], off
	s_add_i32 m0, s24, 0x2000
	s_add_u32 s22, s22, 0xb0080
	v_lshl_add_u64 v[214:215], v[216:217], 0, s[14:15]
	s_addc_u32 s23, s23, 0
	s_add_i32 s24, s51, s26
	global_load_lds_dwordx4 v[214:215], off
	v_lshl_add_u64 v[214:215], s[22:23], 0, v[128:129]
	s_mov_b32 m0, s24
	s_nop 0
	global_load_lds_dwordx4 v[214:215], off
	v_lshl_add_u64 v[214:215], s[22:23], 0, v[130:131]
	s_add_i32 m0, s24, 0x2000
	s_nop 0
	global_load_lds_dwordx4 v[214:215], off
	v_lshl_add_u64 v[214:215], v[218:219], 0, s[14:15]
	s_mov_b32 m0, s34
	s_nop 0
	global_load_lds_dwordx4 v[214:215], off
	v_lshl_add_u64 v[214:215], v[220:221], 0, s[14:15]
	s_mov_b32 m0, s35
	s_nop 0
	global_load_lds_dwordx4 v[214:215], off
	s_waitcnt vmcnt(8)
	s_waitcnt lgkmcnt(0)
	s_barrier
	s_setprio 0
	s_waitcnt lgkmcnt(0)
	v_mfma_f32_16x16x32_bf16 v[60:63], v[140:143], v[176:179], v[60:63]
	v_mfma_f32_16x16x32_bf16 v[56:59], v[152:155], v[176:179], v[56:59]
	v_mfma_f32_16x16x32_bf16 v[44:47], v[140:143], v[184:187], v[44:47]
	v_mfma_f32_16x16x32_bf16 v[40:43], v[152:155], v[184:187], v[40:43]
	v_mfma_f32_16x16x32_bf16 v[28:31], v[140:143], v[198:201], v[28:31]
	v_mfma_f32_16x16x32_bf16 v[24:27], v[152:155], v[198:201], v[24:27]
	v_mfma_f32_16x16x32_bf16 v[12:15], v[140:143], v[206:209], v[12:15]
	v_mfma_f32_16x16x32_bf16 v[8:11], v[152:155], v[206:209], v[8:11]
	v_mfma_f32_16x16x32_bf16 v[60:63], v[144:147], v[180:183], v[60:63]
	v_mfma_f32_16x16x32_bf16 v[56:59], v[156:159], v[180:183], v[56:59]
	v_mfma_f32_16x16x32_bf16 v[44:47], v[144:147], v[194:197], v[44:47]
	v_mfma_f32_16x16x32_bf16 v[40:43], v[156:159], v[194:197], v[40:43]
	v_mfma_f32_16x16x32_bf16 v[28:31], v[144:147], v[202:205], v[28:31]
	v_mfma_f32_16x16x32_bf16 v[24:27], v[156:159], v[202:205], v[24:27]
	v_mfma_f32_16x16x32_bf16 v[12:15], v[144:147], v[210:213], v[12:15]
	v_mfma_f32_16x16x32_bf16 v[8:11], v[156:159], v[210:213], v[8:11]
	s_setprio 1
	s_setprio 0
	v_mfma_f32_16x16x32_bf16 v[52:55], v[160:163], v[176:179], v[52:55]
	v_mfma_f32_16x16x32_bf16 v[48:51], v[168:171], v[176:179], v[48:51]
	v_mfma_f32_16x16x32_bf16 v[36:39], v[160:163], v[184:187], v[36:39]
	v_mfma_f32_16x16x32_bf16 v[32:35], v[168:171], v[184:187], v[32:35]
	v_mfma_f32_16x16x32_bf16 v[20:23], v[160:163], v[198:201], v[20:23]
	v_mfma_f32_16x16x32_bf16 v[16:19], v[168:171], v[198:201], v[16:19]
	v_mfma_f32_16x16x32_bf16 v[4:7], v[160:163], v[206:209], v[4:7]
	v_mfma_f32_16x16x32_bf16 v[0:3], v[168:171], v[206:209], v[0:3]
	v_mfma_f32_16x16x32_bf16 v[52:55], v[164:167], v[180:183], v[52:55]
	v_mfma_f32_16x16x32_bf16 v[48:51], v[172:175], v[180:183], v[48:51]
	v_mfma_f32_16x16x32_bf16 v[36:39], v[164:167], v[194:197], v[36:39]
	v_mfma_f32_16x16x32_bf16 v[32:35], v[172:175], v[194:197], v[32:35]
	v_mfma_f32_16x16x32_bf16 v[20:23], v[164:167], v[202:205], v[20:23]
	v_mfma_f32_16x16x32_bf16 v[16:19], v[172:175], v[202:205], v[16:19]
	v_mfma_f32_16x16x32_bf16 v[4:7], v[164:167], v[210:213], v[4:7]
	v_mfma_f32_16x16x32_bf16 v[0:3], v[172:175], v[210:213], v[0:3]
	s_setprio 1
	s_barrier
	s_add_i32 s47, s47, 2
	s_add_u32 s20, s20, 0x100
	s_addc_u32 s21, s21, 0
	s_add_u32 s45, s45, 0x100
	s_addc_u32 s46, s46, 0
	s_cmp_gt_u32 s47, 41
	s_cbranch_scc0 .LBB0_1572
	s_and_b64 vcc, exec, s[16:17]
	s_cbranch_vccz .LBB0_1575
	s_barrier

; #define PG8_STAGE(bufoff, gbase, voff) do { _Pragma("unroll") for (int _i = 0; _i < 2; ++_i) \
;         __builtin_amdgcn_global_load_lds((const unsigned*)((const char*)(gbase) + (voff)[_i]), (PG8_LAS unsigned*)(lds + (bufoff) + ldsw + _i * 8192), 16, 0, 0); } while (0)
; #define PG8_LDA(dst, b, h) do { _Pragma("unroll") for (int m = 0; m < 4; ++m) _Pragma("unroll") for (int k = 0; k < 2; ++k) dst[m][k] = *(const PG8_LAS bf16x8*)(lds + PG8_SA(b, h) + aoff + m * 2048 + k * 1024); } while (0)
; #define PG8_LDB(dst, b, h) do { _Pragma("unroll") for (int n = 0; n < 2; ++n) _Pragma("unroll") for (int k = 0; k < 2; ++k) dst[n][k] = *(const PG8_LAS bf16x8*)(lds + PG8_SB(b, h) + boff + n * 2048 + k * 1024); } while (0)
; #define PG8_MMA(ai, bj, At, Bt) do { __builtin_amdgcn_s_setprio(1); _Pragma("unroll") for (int m = 0; m < 4; ++m) _Pragma("unroll") for (int n = 0; n < 2; ++n) _Pragma("unroll") for (int k = 0; k < 2; ++k) \
;         acc[ai][bj][m][n] = __builtin_amdgcn_mfma_f32_16x16x32_bf16(Bt[n][k], At[m][k], acc[ai][bj][m][n], 0, 0, 0); __builtin_amdgcn_s_setprio(0); } while (0)
; #define PG8_WAIT_V(n) asm volatile("s_waitcnt vmcnt(" #n ")" ::: "memory")
; #define PG8_WAIT_L(n) asm volatile("s_waitcnt lgkmcnt(" #n ")" ::: "memory")
; #define PG8_BAR __builtin_amdgcn_s_barrier()
; #define PG8_SCHED __builtin_amdgcn_sched_barrier(0)
; template <class Epi, class Sched, bool ALIGN_EPI = false, bool SP2 = false>
; __device__ __forceinline__ void gemm_phase(PG8_LAS unsigned char* lds, const Gemm g, const Sched& S, const Epi& E) {
;     ...
;             const bool last = (t == nt - 2);
;             const char* a1 = cA + (size_t)(t + 1) * kstep;
;             const char* a2 = last ? nA : cA + (size_t)(t + 2) * kstep; const char* b2 = last ? nB : cB + (size_t)(t + 2) * kstep;
;     ...
;             PG8_LDB(B0, 0, 0); PG8_LDB(B1, 0, 1); PG8_SCHED; PG8_LDA(At, 0, 0); PG8_STAGE(PG8_SA(1, 1), a1 + hstep, voffA);
;             PG8_WAIT_V(8); PG8_WAIT_L(0); PG8_BAR; PG8_MMA(0, 0, At, B0); PG8_MMA(0, 1, At, B1); PG8_BAR; PG8_SCHED;
;             PG8_LDA(At, 0, 1); PG8_STAGE(PG8_SB(0, 0), b2, voffB); PG8_STAGE(PG8_SB(0, 1), b2 + hstep, voffB); PG8_STAGE(PG8_SA(0, 0), a2, voffA);
.LBB0_1666:
	ds_read_b128 v[144:147], v155
	ds_read_b128 v[160:163], v155 offset:1024
	ds_read_b128 v[164:167], v155 offset:2048
	ds_read_b128 v[168:171], v155 offset:3072
	ds_read_b128 v[172:175], v156
	ds_read_b128 v[176:179], v156 offset:1024
	ds_read_b128 v[180:183], v156 offset:2048
	ds_read_b128 v[184:187], v156 offset:3072
	s_add_u32 s6, s4, 0xfffc0080
	s_addc_u32 s7, s5, -1
	s_cmp_eq_u32 s55, 12
	s_cselect_b32 s9, s10, s7
	s_cselect_b32 s8, s11, s6
	s_cselect_b32 s7, s25, s54
	s_cselect_b32 s6, s27, s53
	v_lshl_add_u64 v[152:153], s[4:5], 0, v[136:137]
	s_add_i32 m0, s39, 0xc000
	ds_read_b128 v[188:191], v157
	ds_read_b128 v[192:195], v157 offset:1024
	ds_read_b128 v[196:199], v157 offset:2048
	ds_read_b128 v[200:203], v157 offset:3072
	ds_read_b128 v[204:207], v157 offset:4096
	ds_read_b128 v[208:211], v157 offset:5120
	ds_read_b128 v[212:215], v157 offset:6144
	ds_read_b128 v[216:219], v157 offset:7168
	global_load_lds_dwordx4 v[152:153], off
	v_lshl_add_u64 v[152:153], s[4:5], 0, v[138:139]
	s_add_i32 m0, s39, 0xe000
	s_nop 0
	global_load_lds_dwordx4 v[152:153], off
	s_waitcnt vmcnt(8)
	s_waitcnt lgkmcnt(0)
	s_barrier
	s_setprio 0
	s_waitcnt lgkmcnt(0)
	v_mfma_f32_16x16x32_bf16 v[124:127], v[144:147], v[188:191], v[124:127]
	v_mfma_f32_16x16x32_bf16 v[116:119], v[164:167], v[188:191], v[116:119]
	v_mfma_f32_16x16x32_bf16 v[108:111], v[144:147], v[196:199], v[108:111]
	v_mfma_f32_16x16x32_bf16 v[100:103], v[164:167], v[196:199], v[100:103]
	v_mfma_f32_16x16x32_bf16 v[92:95], v[144:147], v[204:207], v[92:95]
	v_mfma_f32_16x16x32_bf16 v[84:87], v[164:167], v[204:207], v[84:87]
	v_mfma_f32_16x16x32_bf16 v[76:79], v[144:147], v[212:215], v[76:79]
	v_mfma_f32_16x16x32_bf16 v[68:71], v[164:167], v[212:215], v[68:71]
	v_mfma_f32_16x16x32_bf16 v[124:127], v[160:163], v[192:195], v[124:127]
	v_mfma_f32_16x16x32_bf16 v[116:119], v[168:171], v[192:195], v[116:119]
	v_mfma_f32_16x16x32_bf16 v[108:111], v[160:163], v[200:203], v[108:111]
	v_mfma_f32_16x16x32_bf16 v[100:103], v[168:171], v[200:203], v[100:103]
	v_mfma_f32_16x16x32_bf16 v[92:95], v[160:163], v[208:211], v[92:95]
	v_mfma_f32_16x16x32_bf16 v[84:87], v[168:171], v[208:211], v[84:87]
	v_mfma_f32_16x16x32_bf16 v[76:79], v[160:163], v[216:219], v[76:79]
	v_mfma_f32_16x16x32_bf16 v[68:71], v[168:171], v[216:219], v[68:71]
	s_setprio 1
	s_setprio 0
	v_mfma_f32_16x16x32_bf16 v[120:123], v[172:175], v[188:191], v[120:123]
	v_mfma_f32_16x16x32_bf16 v[112:115], v[180:183], v[188:191], v[112:115]
	v_mfma_f32_16x16x32_bf16 v[104:107], v[172:175], v[196:199], v[104:107]
	v_mfma_f32_16x16x32_bf16 v[96:99], v[180:183], v[196:199], v[96:99]
	v_mfma_f32_16x16x32_bf16 v[88:91], v[172:175], v[204:207], v[88:91]
	v_mfma_f32_16x16x32_bf16 v[80:83], v[180:183], v[204:207], v[80:83]
	v_mfma_f32_16x16x32_bf16 v[72:75], v[172:175], v[212:215], v[72:75]
	v_mfma_f32_16x16x32_bf16 v[64:67], v[180:183], v[212:215], v[64:67]
	v_mfma_f32_16x16x32_bf16 v[120:123], v[176:179], v[192:195], v[120:123]
	v_mfma_f32_16x16x32_bf16 v[112:115], v[184:187], v[192:195], v[112:115]
	v_mfma_f32_16x16x32_bf16 v[104:107], v[176:179], v[200:203], v[104:107]
	v_mfma_f32_16x16x32_bf16 v[96:99], v[184:187], v[200:203], v[96:99]
	v_mfma_f32_16x16x32_bf16 v[88:91], v[176:179], v[208:211], v[88:91]
	v_mfma_f32_16x16x32_bf16 v[80:83], v[184:187], v[208:211], v[80:83]
	v_mfma_f32_16x16x32_bf16 v[72:75], v[176:179], v[216:219], v[72:75]
	v_mfma_f32_16x16x32_bf16 v[64:67], v[184:187], v[216:219], v[64:67]
	s_setprio 1
	s_barrier
	s_add_i32 s56, s47, s36
	v_lshl_add_u64 v[152:153], s[6:7], 0, v[132:133]
	s_mov_b32 m0, s56
	ds_read_b128 v[188:191], v157 offset:16384
	ds_read_b128 v[192:195], v157 offset:17408
	ds_read_b128 v[196:199], v157 offset:18432
	ds_read_b128 v[200:203], v157 offset:19456
	ds_read_b128 v[204:207], v157 offset:20480
	ds_read_b128 v[208:211], v157 offset:21504
	ds_read_b128 v[212:215], v157 offset:22528
	ds_read_b128 v[216:219], v157 offset:23552
	global_load_lds_dwordx4 v[152:153], off
	s_add_i32 m0, s56, 0x2000
	s_add_u32 s56, s6, 0x40000
	v_lshl_add_u64 v[220:221], s[6:7], 0, v[128:129]
	s_addc_u32 s57, s7, 0
	s_add_i32 s58, s50, s36
	global_load_lds_dwordx4 v[220:221], off
	v_lshl_add_u64 v[222:223], s[56:57], 0, v[132:133]
	s_mov_b32 m0, s58
	v_lshl_add_u64 v[224:225], s[8:9], 0, v[130:131]
	global_load_lds_dwordx4 v[222:223], off
	v_lshl_add_u64 v[222:223], s[56:57], 0, v[128:129]
	s_add_i32 m0, s58, 0x2000
	s_nop 0
	global_load_lds_dwordx4 v[222:223], off
	v_lshl_add_u64 v[222:223], s[8:9], 0, v[134:135]
	s_mov_b32 m0, s39
	s_nop 0
	global_load_lds_dwordx4 v[222:223], off
	s_mov_b32 m0, s40
	s_nop 0
	global_load_lds_dwordx4 v[224:225], off
	s_waitcnt vmcnt(8)
	s_waitcnt lgkmcnt(0)
	s_barrier
; #define PG8_STAGE(bufoff, gbase, voff) do { _Pragma("unroll") for (int _i = 0; _i < 2; ++_i) \
;         __builtin_amdgcn_global_load_lds((const unsigned*)((const char*)(gbase) + (voff)[_i]), (PG8_LAS unsigned*)(lds + (bufoff) + ldsw + _i * 8192), 16, 0, 0); } while (0)
; #define PG8_LDA(dst, b, h) do { _Pragma("unroll") for (int m = 0; m < 4; ++m) _Pragma("unroll") for (int k = 0; k < 2; ++k) dst[m][k] = *(const PG8_LAS bf16x8*)(lds + PG8_SA(b, h) + aoff + m * 2048 + k * 1024); } while (0)
; #define PG8_LDB(dst, b, h) do { _Pragma("unroll") for (int n = 0; n < 2; ++n) _Pragma("unroll") for (int k = 0; k < 2; ++k) dst[n][k] = *(const PG8_LAS bf16x8*)(lds + PG8_SB(b, h) + boff + n * 2048 + k * 1024); } while (0)
; #define PG8_MMA(ai, bj, At, Bt) do { __builtin_amdgcn_s_setprio(1); _Pragma("unroll") for (int m = 0; m < 4; ++m) _Pragma("unroll") for (int n = 0; n < 2; ++n) _Pragma("unroll") for (int k = 0; k < 2; ++k) \
;         acc[ai][bj][m][n] = __builtin_amdgcn_mfma_f32_16x16x32_bf16(Bt[n][k], At[m][k], acc[ai][bj][m][n], 0, 0, 0); __builtin_amdgcn_s_setprio(0); } while (0)
; #define PG8_WAIT_V(n) asm volatile("s_waitcnt vmcnt(" #n ")" ::: "memory")
; #define PG8_WAIT_L(n) asm volatile("s_waitcnt lgkmcnt(" #n ")" ::: "memory")
; #define PG8_BAR __builtin_amdgcn_s_barrier()
; #define PG8_SCHED __builtin_amdgcn_sched_barrier(0)
; template <class Epi, class Sched, bool ALIGN_EPI = false, bool SP2 = false>
; __device__ __forceinline__ void gemm_phase(PG8_LAS unsigned char* lds, const Gemm g, const Sched& S, const Epi& E) {
;     ...
;             PG8_WAIT_V(8); PG8_WAIT_L(0); PG8_BAR; PG8_MMA(1, 0, At, B0); PG8_MMA(1, 1, At, B1); PG8_BAR; PG8_SCHED;
;             PG8_LDB(B0, 1, 0); PG8_LDB(B1, 1, 1); PG8_SCHED; PG8_LDA(At, 1, 0); PG8_STAGE(PG8_SA(0, 1), a2 + hstep, voffA);
;             PG8_WAIT_V(8); PG8_WAIT_L(0); PG8_BAR; PG8_MMA(0, 0, At, B0); PG8_MMA(0, 1, At, B1); PG8_BAR; PG8_SCHED;
	s_setprio 0
	s_waitcnt lgkmcnt(0)
	v_mfma_f32_16x16x32_bf16 v[60:63], v[144:147], v[188:191], v[60:63]
	v_mfma_f32_16x16x32_bf16 v[52:55], v[164:167], v[188:191], v[52:55]
	v_mfma_f32_16x16x32_bf16 v[44:47], v[144:147], v[196:199], v[44:47]
	v_mfma_f32_16x16x32_bf16 v[36:39], v[164:167], v[196:199], v[36:39]
	v_mfma_f32_16x16x32_bf16 v[28:31], v[144:147], v[204:207], v[28:31]
	v_mfma_f32_16x16x32_bf16 v[20:23], v[164:167], v[204:207], v[20:23]
	v_mfma_f32_16x16x32_bf16 v[12:15], v[144:147], v[212:215], v[12:15]
	v_mfma_f32_16x16x32_bf16 v[4:7], v[164:167], v[212:215], v[4:7]
	v_mfma_f32_16x16x32_bf16 v[60:63], v[160:163], v[192:195], v[60:63]
	v_mfma_f32_16x16x32_bf16 v[52:55], v[168:171], v[192:195], v[52:55]
	v_mfma_f32_16x16x32_bf16 v[44:47], v[160:163], v[200:203], v[44:47]
	v_mfma_f32_16x16x32_bf16 v[36:39], v[168:171], v[200:203], v[36:39]
	v_mfma_f32_16x16x32_bf16 v[28:31], v[160:163], v[208:211], v[28:31]
	v_mfma_f32_16x16x32_bf16 v[20:23], v[168:171], v[208:211], v[20:23]
	v_mfma_f32_16x16x32_bf16 v[12:15], v[160:163], v[216:219], v[12:15]
	v_mfma_f32_16x16x32_bf16 v[4:7], v[168:171], v[216:219], v[4:7]
	s_setprio 1
	s_setprio 0
	v_mfma_f32_16x16x32_bf16 v[56:59], v[172:175], v[188:191], v[56:59]
	v_mfma_f32_16x16x32_bf16 v[48:51], v[180:183], v[188:191], v[48:51]
	v_mfma_f32_16x16x32_bf16 v[40:43], v[172:175], v[196:199], v[40:43]
	v_mfma_f32_16x16x32_bf16 v[32:35], v[180:183], v[196:199], v[32:35]
	v_mfma_f32_16x16x32_bf16 v[24:27], v[172:175], v[204:207], v[24:27]
	v_mfma_f32_16x16x32_bf16 v[16:19], v[180:183], v[204:207], v[16:19]
	v_mfma_f32_16x16x32_bf16 v[8:11], v[172:175], v[212:215], v[8:11]
	v_mfma_f32_16x16x32_bf16 v[0:3], v[180:183], v[212:215], v[0:3]
	v_mfma_f32_16x16x32_bf16 v[56:59], v[176:179], v[192:195], v[56:59]
	v_mfma_f32_16x16x32_bf16 v[48:51], v[184:187], v[192:195], v[48:51]
	v_mfma_f32_16x16x32_bf16 v[40:43], v[176:179], v[200:203], v[40:43]
	v_mfma_f32_16x16x32_bf16 v[32:35], v[184:187], v[200:203], v[32:35]
	v_mfma_f32_16x16x32_bf16 v[24:27], v[176:179], v[208:211], v[24:27]
	v_mfma_f32_16x16x32_bf16 v[16:19], v[184:187], v[208:211], v[16:19]
	v_mfma_f32_16x16x32_bf16 v[8:11], v[176:179], v[216:219], v[8:11]
	v_mfma_f32_16x16x32_bf16 v[0:3], v[184:187], v[216:219], v[0:3]
	s_setprio 1
	s_barrier
	s_add_i32 s56, 0, 0x18000
	v_add_u32_e32 v159, s56, v151
	s_add_i32 s57, 0, 0x1c000
	ds_read_b128 v[144:147], v159
	ds_read_b128 v[160:163], v159 offset:1024
	ds_read_b128 v[164:167], v159 offset:2048
	ds_read_b128 v[168:171], v159 offset:3072
	v_add_u32_e32 v159, s57, v151
	ds_read_b128 v[172:175], v159
	ds_read_b128 v[176:179], v159 offset:1024
	ds_read_b128 v[180:183], v159 offset:2048
	ds_read_b128 v[184:187], v159 offset:3072
	s_add_u32 s8, s8, 0x40000
	s_addc_u32 s9, s9, 0
	s_mov_b32 m0, s41
	v_lshl_add_u64 v[226:227], s[8:9], 0, v[134:135]
	ds_read_b128 v[188:191], v157 offset:32768
	ds_read_b128 v[192:195], v157 offset:33792
	ds_read_b128 v[196:199], v157 offset:34816
	ds_read_b128 v[200:203], v157 offset:35840
	ds_read_b128 v[204:207], v157 offset:36864
	ds_read_b128 v[208:211], v157 offset:37888
	ds_read_b128 v[212:215], v157 offset:38912
	ds_read_b128 v[216:219], v157 offset:39936
	global_load_lds_dwordx4 v[226:227], off
	v_lshl_add_u64 v[226:227], s[8:9], 0, v[130:131]
	s_mov_b32 m0, s42
	s_nop 0
	global_load_lds_dwordx4 v[226:227], off
	s_waitcnt vmcnt(8)
	s_waitcnt lgkmcnt(0)
	s_barrier
	s_setprio 0
	s_waitcnt lgkmcnt(0)
	v_mfma_f32_16x16x32_bf16 v[124:127], v[144:147], v[188:191], v[124:127]
	v_mfma_f32_16x16x32_bf16 v[116:119], v[164:167], v[188:191], v[116:119]
	v_mfma_f32_16x16x32_bf16 v[108:111], v[144:147], v[196:199], v[108:111]
	v_mfma_f32_16x16x32_bf16 v[100:103], v[164:167], v[196:199], v[100:103]
	v_mfma_f32_16x16x32_bf16 v[92:95], v[144:147], v[204:207], v[92:95]
	v_mfma_f32_16x16x32_bf16 v[84:87], v[164:167], v[204:207], v[84:87]
	v_mfma_f32_16x16x32_bf16 v[76:79], v[144:147], v[212:215], v[76:79]
	v_mfma_f32_16x16x32_bf16 v[68:71], v[164:167], v[212:215], v[68:71]
	v_mfma_f32_16x16x32_bf16 v[124:127], v[160:163], v[192:195], v[124:127]
	v_mfma_f32_16x16x32_bf16 v[116:119], v[168:171], v[192:195], v[116:119]
	v_mfma_f32_16x16x32_bf16 v[108:111], v[160:163], v[200:203], v[108:111]
	v_mfma_f32_16x16x32_bf16 v[100:103], v[168:171], v[200:203], v[100:103]
	v_mfma_f32_16x16x32_bf16 v[92:95], v[160:163], v[208:211], v[92:95]
	v_mfma_f32_16x16x32_bf16 v[84:87], v[168:171], v[208:211], v[84:87]
	v_mfma_f32_16x16x32_bf16 v[76:79], v[160:163], v[216:219], v[76:79]
	v_mfma_f32_16x16x32_bf16 v[68:71], v[168:171], v[216:219], v[68:71]
	s_setprio 1
	s_setprio 0
	v_mfma_f32_16x16x32_bf16 v[120:123], v[172:175], v[188:191], v[120:123]
	v_mfma_f32_16x16x32_bf16 v[112:115], v[180:183], v[188:191], v[112:115]
	v_mfma_f32_16x16x32_bf16 v[104:107], v[172:175], v[196:199], v[104:107]
	v_mfma_f32_16x16x32_bf16 v[96:99], v[180:183], v[196:199], v[96:99]
	v_mfma_f32_16x16x32_bf16 v[88:91], v[172:175], v[204:207], v[88:91]
	v_mfma_f32_16x16x32_bf16 v[80:83], v[180:183], v[204:207], v[80:83]
	v_mfma_f32_16x16x32_bf16 v[72:75], v[172:175], v[212:215], v[72:75]
	v_mfma_f32_16x16x32_bf16 v[64:67], v[180:183], v[212:215], v[64:67]
	v_mfma_f32_16x16x32_bf16 v[120:123], v[176:179], v[192:195], v[120:123]
	v_mfma_f32_16x16x32_bf16 v[112:115], v[184:187], v[192:195], v[112:115]
	v_mfma_f32_16x16x32_bf16 v[104:107], v[176:179], v[200:203], v[104:107]
	v_mfma_f32_16x16x32_bf16 v[96:99], v[184:187], v[200:203], v[96:99]
	v_mfma_f32_16x16x32_bf16 v[88:91], v[176:179], v[208:211], v[88:91]
	v_mfma_f32_16x16x32_bf16 v[80:83], v[184:187], v[208:211], v[80:83]
	v_mfma_f32_16x16x32_bf16 v[72:75], v[176:179], v[216:219], v[72:75]
	v_mfma_f32_16x16x32_bf16 v[64:67], v[184:187], v[216:219], v[64:67]
	s_setprio 1
	s_barrier
; #define PG8_STAGE(bufoff, gbase, voff) do { _Pragma("unroll") for (int _i = 0; _i < 2; ++_i) \
;         __builtin_amdgcn_global_load_lds((const unsigned*)((const char*)(gbase) + (voff)[_i]), (PG8_LAS unsigned*)(lds + (bufoff) + ldsw + _i * 8192), 16, 0, 0); } while (0)
; #define PG8_LDA(dst, b, h) do { _Pragma("unroll") for (int m = 0; m < 4; ++m) _Pragma("unroll") for (int k = 0; k < 2; ++k) dst[m][k] = *(const PG8_LAS bf16x8*)(lds + PG8_SA(b, h) + aoff + m * 2048 + k * 1024); } while (0)
; #define PG8_MMA(ai, bj, At, Bt) do { __builtin_amdgcn_s_setprio(1); _Pragma("unroll") for (int m = 0; m < 4; ++m) _Pragma("unroll") for (int n = 0; n < 2; ++n) _Pragma("unroll") for (int k = 0; k < 2; ++k) \
;         acc[ai][bj][m][n] = __builtin_amdgcn_mfma_f32_16x16x32_bf16(Bt[n][k], At[m][k], acc[ai][bj][m][n], 0, 0, 0); __builtin_amdgcn_s_setprio(0); } while (0)
; #define PG8_WAIT_V(n) asm volatile("s_waitcnt vmcnt(" #n ")" ::: "memory")
; #define PG8_WAIT_L(n) asm volatile("s_waitcnt lgkmcnt(" #n ")" ::: "memory")
; #define PG8_BAR __builtin_amdgcn_s_barrier()
; #define PG8_SCHED __builtin_amdgcn_sched_barrier(0)
; template <class Epi, class Sched, bool ALIGN_EPI = false, bool SP2 = false>
; __device__ __forceinline__ void gemm_phase(PG8_LAS unsigned char* lds, const Gemm g, const Sched& S, const Epi& E) {
;     ...
;         for (int t = 0; t < nt; t += 2) {
;             const bool last = (t == nt - 2);
;     ...
;             PG8_LDA(At, 1, 1); PG8_STAGE(PG8_SB(1, 0), b3, voffB); PG8_STAGE(PG8_SB(1, 1), b3 + hstep, voffB); PG8_STAGE(PG8_SA(1, 0), a3, voffA);
;             PG8_WAIT_V(8); PG8_WAIT_L(0); PG8_BAR; PG8_MMA(1, 0, At, B0); PG8_MMA(1, 1, At, B1); PG8_BAR; PG8_SCHED;
	s_add_i32 s8, s56, s36
	v_lshl_add_u64 v[152:153], v[152:153], 0, s[20:21]
	s_mov_b32 m0, s8
	ds_read_b128 v[188:191], v157 offset:49152
	ds_read_b128 v[192:195], v157 offset:50176
	ds_read_b128 v[196:199], v157 offset:51200
	ds_read_b128 v[200:203], v157 offset:52224
	ds_read_b128 v[204:207], v157 offset:53248
	ds_read_b128 v[208:211], v157 offset:54272
	ds_read_b128 v[212:215], v157 offset:55296
	ds_read_b128 v[216:219], v157 offset:56320
	global_load_lds_dwordx4 v[152:153], off
	s_add_i32 m0, s8, 0x2000
	s_add_u32 s6, s6, 0x40080
	v_lshl_add_u64 v[152:153], v[220:221], 0, s[20:21]
	s_addc_u32 s7, s7, 0
	s_add_i32 s8, s57, s36
	global_load_lds_dwordx4 v[152:153], off
	v_lshl_add_u64 v[152:153], s[6:7], 0, v[132:133]
	s_mov_b32 m0, s8
	s_nop 0
	global_load_lds_dwordx4 v[152:153], off
	v_lshl_add_u64 v[152:153], s[6:7], 0, v[128:129]
	s_add_i32 m0, s8, 0x2000
	s_nop 0
	global_load_lds_dwordx4 v[152:153], off
	v_lshl_add_u64 v[152:153], v[222:223], 0, s[20:21]
	s_mov_b32 m0, s44
	s_nop 0
	global_load_lds_dwordx4 v[152:153], off
	v_lshl_add_u64 v[152:153], v[224:225], 0, s[20:21]
	s_mov_b32 m0, s45
	s_nop 0
	global_load_lds_dwordx4 v[152:153], off
	s_waitcnt vmcnt(8)
	s_waitcnt lgkmcnt(0)
	s_barrier
	s_setprio 0
	s_waitcnt lgkmcnt(0)
	v_mfma_f32_16x16x32_bf16 v[60:63], v[144:147], v[188:191], v[60:63]
	v_mfma_f32_16x16x32_bf16 v[52:55], v[164:167], v[188:191], v[52:55]
	v_mfma_f32_16x16x32_bf16 v[44:47], v[144:147], v[196:199], v[44:47]
	v_mfma_f32_16x16x32_bf16 v[36:39], v[164:167], v[196:199], v[36:39]
	v_mfma_f32_16x16x32_bf16 v[28:31], v[144:147], v[204:207], v[28:31]
	v_mfma_f32_16x16x32_bf16 v[20:23], v[164:167], v[204:207], v[20:23]
	v_mfma_f32_16x16x32_bf16 v[12:15], v[144:147], v[212:215], v[12:15]
	v_mfma_f32_16x16x32_bf16 v[4:7], v[164:167], v[212:215], v[4:7]
	v_mfma_f32_16x16x32_bf16 v[60:63], v[160:163], v[192:195], v[60:63]
	v_mfma_f32_16x16x32_bf16 v[52:55], v[168:171], v[192:195], v[52:55]
	v_mfma_f32_16x16x32_bf16 v[44:47], v[160:163], v[200:203], v[44:47]
	v_mfma_f32_16x16x32_bf16 v[36:39], v[168:171], v[200:203], v[36:39]
	v_mfma_f32_16x16x32_bf16 v[28:31], v[160:163], v[208:211], v[28:31]
	v_mfma_f32_16x16x32_bf16 v[20:23], v[168:171], v[208:211], v[20:23]
	v_mfma_f32_16x16x32_bf16 v[12:15], v[160:163], v[216:219], v[12:15]
	v_mfma_f32_16x16x32_bf16 v[4:7], v[168:171], v[216:219], v[4:7]
	s_setprio 1
	s_setprio 0
	v_mfma_f32_16x16x32_bf16 v[56:59], v[172:175], v[188:191], v[56:59]
	v_mfma_f32_16x16x32_bf16 v[48:51], v[180:183], v[188:191], v[48:51]
	v_mfma_f32_16x16x32_bf16 v[40:43], v[172:175], v[196:199], v[40:43]
	v_mfma_f32_16x16x32_bf16 v[32:35], v[180:183], v[196:199], v[32:35]
	v_mfma_f32_16x16x32_bf16 v[24:27], v[172:175], v[204:207], v[24:27]
	v_mfma_f32_16x16x32_bf16 v[16:19], v[180:183], v[204:207], v[16:19]
	v_mfma_f32_16x16x32_bf16 v[8:11], v[172:175], v[212:215], v[8:11]
	v_mfma_f32_16x16x32_bf16 v[0:3], v[180:183], v[212:215], v[0:3]
	v_mfma_f32_16x16x32_bf16 v[56:59], v[176:179], v[192:195], v[56:59]
	v_mfma_f32_16x16x32_bf16 v[48:51], v[184:187], v[192:195], v[48:51]
	v_mfma_f32_16x16x32_bf16 v[40:43], v[176:179], v[200:203], v[40:43]
	v_mfma_f32_16x16x32_bf16 v[32:35], v[184:187], v[200:203], v[32:35]
	v_mfma_f32_16x16x32_bf16 v[24:27], v[176:179], v[208:211], v[24:27]
	v_mfma_f32_16x16x32_bf16 v[16:19], v[184:187], v[208:211], v[16:19]
	v_mfma_f32_16x16x32_bf16 v[8:11], v[176:179], v[216:219], v[8:11]
	v_mfma_f32_16x16x32_bf16 v[0:3], v[184:187], v[216:219], v[0:3]
	s_setprio 1
	s_barrier
	s_add_i32 s55, s55, 2
	s_add_u32 s4, s4, 0x100
	s_addc_u32 s5, s5, 0
	s_add_u32 s53, s53, 0x100
	s_addc_u32 s54, s54, 0
	s_cmp_gt_u32 s55, 13
	s_cbranch_scc0 .LBB0_1666
	s_and_b64 vcc, exec, s[22:23]
	s_cbranch_vccz .LBB0_1669
	s_barrier

; #define PG8_STAGE(bufoff, gbase, voff) do { _Pragma("unroll") for (int _i = 0; _i < 2; ++_i) \
;         __builtin_amdgcn_global_load_lds((const unsigned*)((const char*)(gbase) + (voff)[_i]), (PG8_LAS unsigned*)(lds + (bufoff) + ldsw + _i * 8192), 16, 0, 0); } while (0)
; #define PG8_LDA(dst, b, h) do { _Pragma("unroll") for (int m = 0; m < 4; ++m) _Pragma("unroll") for (int k = 0; k < 2; ++k) dst[m][k] = *(const PG8_LAS bf16x8*)(lds + PG8_SA(b, h) + aoff + m * 2048 + k * 1024); } while (0)
; #define PG8_LDB(dst, b, h) do { _Pragma("unroll") for (int n = 0; n < 2; ++n) _Pragma("unroll") for (int k = 0; k < 2; ++k) dst[n][k] = *(const PG8_LAS bf16x8*)(lds + PG8_SB(b, h) + boff + n * 2048 + k * 1024); } while (0)
; #define PG8_MMA(ai, bj, At, Bt) do { __builtin_amdgcn_s_setprio(1); _Pragma("unroll") for (int m = 0; m < 4; ++m) _Pragma("unroll") for (int n = 0; n < 2; ++n) _Pragma("unroll") for (int k = 0; k < 2; ++k) \
;         acc[ai][bj][m][n] = __builtin_amdgcn_mfma_f32_16x16x32_bf16(Bt[n][k], At[m][k], acc[ai][bj][m][n], 0, 0, 0); __builtin_amdgcn_s_setprio(0); } while (0)
; #define PG8_WAIT_V(n) asm volatile("s_waitcnt vmcnt(" #n ")" ::: "memory")
; #define PG8_WAIT_L(n) asm volatile("s_waitcnt lgkmcnt(" #n ")" ::: "memory")
; #define PG8_BAR __builtin_amdgcn_s_barrier()
; #define PG8_SCHED __builtin_amdgcn_sched_barrier(0)
; template <class Epi, class Sched, bool ALIGN_EPI = false, bool SP2 = false>
; __device__ __forceinline__ void gemm_phase(PG8_LAS unsigned char* lds, const Gemm g, const Sched& S, const Epi& E) {
;     ...
;             const bool last = (t == nt - 2);
;             const char* a1 = cA + (size_t)(t + 1) * kstep;
;             const char* a2 = last ? nA : cA + (size_t)(t + 2) * kstep; const char* b2 = last ? nB : cB + (size_t)(t + 2) * kstep;
;     ...
;             PG8_LDB(B0, 0, 0); PG8_LDB(B1, 0, 1); PG8_SCHED; PG8_LDA(At, 0, 0); PG8_STAGE(PG8_SA(1, 1), a1 + hstep, voffA);
;             PG8_WAIT_V(8); PG8_WAIT_L(0); PG8_BAR; PG8_MMA(0, 0, At, B0); PG8_MMA(0, 1, At, B1); PG8_BAR; PG8_SCHED;
;             PG8_LDA(At, 0, 1); PG8_STAGE(PG8_SB(0, 0), b2, voffB); PG8_STAGE(PG8_SB(0, 1), b2 + hstep, voffB); PG8_STAGE(PG8_SA(0, 0), a2, voffA);
.LBB0_1751:
	ds_read_b128 v[140:143], v194
	ds_read_b128 v[144:147], v194 offset:1024
	ds_read_b128 v[150:153], v194 offset:2048
	ds_read_b128 v[154:157], v194 offset:3072
	ds_read_b128 v[158:161], v195
	ds_read_b128 v[162:165], v195 offset:1024
	ds_read_b128 v[166:169], v195 offset:2048
	ds_read_b128 v[170:173], v195 offset:3072
	s_add_u32 s22, s20, 0xfff50080
	s_addc_u32 s23, s21, -1
	s_cmp_eq_u32 s47, 40
	s_cselect_b32 s25, s1, s23
	s_cselect_b32 s24, s0, s22
	s_cselect_b32 s23, s19, s46
	s_cselect_b32 s22, s18, s45
	v_lshl_add_u64 v[190:191], s[20:21], 0, v[132:133]
	s_add_i32 m0, s27, 0xc000
	ds_read_b128 v[174:177], v196
	ds_read_b128 v[178:181], v196 offset:1024
	ds_read_b128 v[182:185], v196 offset:2048
	ds_read_b128 v[186:189], v196 offset:3072
	ds_read_b128 v[200:203], v196 offset:4096
	ds_read_b128 v[204:207], v196 offset:5120
	ds_read_b128 v[208:211], v196 offset:6144
	ds_read_b128 v[212:215], v196 offset:7168
	global_load_lds_dwordx4 v[190:191], off
	v_lshl_add_u64 v[190:191], s[20:21], 0, v[134:135]
	s_add_i32 m0, s27, 0xe000
	s_nop 0
	global_load_lds_dwordx4 v[190:191], off
	s_waitcnt vmcnt(8)
	s_waitcnt lgkmcnt(0)
	s_barrier
	s_setprio 0
	s_waitcnt lgkmcnt(0)
	v_mfma_f32_16x16x32_bf16 v[124:127], v[140:143], v[174:177], v[124:127]
	v_mfma_f32_16x16x32_bf16 v[120:123], v[150:153], v[174:177], v[120:123]
	v_mfma_f32_16x16x32_bf16 v[108:111], v[140:143], v[182:185], v[108:111]
	v_mfma_f32_16x16x32_bf16 v[104:107], v[150:153], v[182:185], v[104:107]
	v_mfma_f32_16x16x32_bf16 v[92:95], v[140:143], v[200:203], v[92:95]
	v_mfma_f32_16x16x32_bf16 v[88:91], v[150:153], v[200:203], v[88:91]
	v_mfma_f32_16x16x32_bf16 v[76:79], v[140:143], v[208:211], v[76:79]
	v_mfma_f32_16x16x32_bf16 v[72:75], v[150:153], v[208:211], v[72:75]
	v_mfma_f32_16x16x32_bf16 v[124:127], v[144:147], v[178:181], v[124:127]
	v_mfma_f32_16x16x32_bf16 v[120:123], v[154:157], v[178:181], v[120:123]
	v_mfma_f32_16x16x32_bf16 v[108:111], v[144:147], v[186:189], v[108:111]
	v_mfma_f32_16x16x32_bf16 v[104:107], v[154:157], v[186:189], v[104:107]
	v_mfma_f32_16x16x32_bf16 v[92:95], v[144:147], v[204:207], v[92:95]
	v_mfma_f32_16x16x32_bf16 v[88:91], v[154:157], v[204:207], v[88:91]
	v_mfma_f32_16x16x32_bf16 v[76:79], v[144:147], v[212:215], v[76:79]
	v_mfma_f32_16x16x32_bf16 v[72:75], v[154:157], v[212:215], v[72:75]
	s_setprio 1
	s_setprio 0
	v_mfma_f32_16x16x32_bf16 v[116:119], v[158:161], v[174:177], v[116:119]
	v_mfma_f32_16x16x32_bf16 v[112:115], v[166:169], v[174:177], v[112:115]
	v_mfma_f32_16x16x32_bf16 v[100:103], v[158:161], v[182:185], v[100:103]
	v_mfma_f32_16x16x32_bf16 v[96:99], v[166:169], v[182:185], v[96:99]
	v_mfma_f32_16x16x32_bf16 v[84:87], v[158:161], v[200:203], v[84:87]
	v_mfma_f32_16x16x32_bf16 v[80:83], v[166:169], v[200:203], v[80:83]
	v_mfma_f32_16x16x32_bf16 v[68:71], v[158:161], v[208:211], v[68:71]
	v_mfma_f32_16x16x32_bf16 v[64:67], v[166:169], v[208:211], v[64:67]
	v_mfma_f32_16x16x32_bf16 v[116:119], v[162:165], v[178:181], v[116:119]
	v_mfma_f32_16x16x32_bf16 v[112:115], v[170:173], v[178:181], v[112:115]
	v_mfma_f32_16x16x32_bf16 v[100:103], v[162:165], v[186:189], v[100:103]
	v_mfma_f32_16x16x32_bf16 v[96:99], v[170:173], v[186:189], v[96:99]
	v_mfma_f32_16x16x32_bf16 v[84:87], v[162:165], v[204:207], v[84:87]
	v_mfma_f32_16x16x32_bf16 v[80:83], v[170:173], v[204:207], v[80:83]
	v_mfma_f32_16x16x32_bf16 v[68:71], v[162:165], v[212:215], v[68:71]
	v_mfma_f32_16x16x32_bf16 v[64:67], v[170:173], v[212:215], v[64:67]
	s_setprio 1
	s_barrier
	s_add_i32 s50, s38, s26
	v_lshl_add_u64 v[190:191], s[22:23], 0, v[128:129]
	s_mov_b32 m0, s50
	ds_read_b128 v[174:177], v196 offset:16384
	ds_read_b128 v[178:181], v196 offset:17408
	ds_read_b128 v[182:185], v196 offset:18432
	ds_read_b128 v[186:189], v196 offset:19456
	ds_read_b128 v[200:203], v196 offset:20480
	ds_read_b128 v[204:207], v196 offset:21504
	ds_read_b128 v[208:211], v196 offset:22528
	ds_read_b128 v[212:215], v196 offset:23552
	global_load_lds_dwordx4 v[190:191], off
	s_add_i32 m0, s50, 0x2000
	s_add_u32 s50, s22, 0xb0000
	v_lshl_add_u64 v[216:217], s[22:23], 0, v[130:131]
	s_addc_u32 s51, s23, 0
	s_add_i32 s52, s39, s26
	global_load_lds_dwordx4 v[216:217], off
	v_lshl_add_u64 v[218:219], s[50:51], 0, v[128:129]
	s_mov_b32 m0, s52
	v_lshl_add_u64 v[220:221], s[24:25], 0, v[130:131]
	global_load_lds_dwordx4 v[218:219], off
	v_lshl_add_u64 v[218:219], s[50:51], 0, v[130:131]
	s_add_i32 m0, s52, 0x2000
	s_nop 0
	global_load_lds_dwordx4 v[218:219], off
	v_lshl_add_u64 v[218:219], s[24:25], 0, v[128:129]
	s_mov_b32 m0, s27
	s_nop 0
	global_load_lds_dwordx4 v[218:219], off
	s_mov_b32 m0, s28
	s_nop 0
	global_load_lds_dwordx4 v[220:221], off
	s_waitcnt vmcnt(8)
	s_waitcnt lgkmcnt(0)
	s_barrier
; #define PG8_STAGE(bufoff, gbase, voff) do { _Pragma("unroll") for (int _i = 0; _i < 2; ++_i) \
;         __builtin_amdgcn_global_load_lds((const unsigned*)((const char*)(gbase) + (voff)[_i]), (PG8_LAS unsigned*)(lds + (bufoff) + ldsw + _i * 8192), 16, 0, 0); } while (0)
; #define PG8_LDA(dst, b, h) do { _Pragma("unroll") for (int m = 0; m < 4; ++m) _Pragma("unroll") for (int k = 0; k < 2; ++k) dst[m][k] = *(const PG8_LAS bf16x8*)(lds + PG8_SA(b, h) + aoff + m * 2048 + k * 1024); } while (0)
; #define PG8_LDB(dst, b, h) do { _Pragma("unroll") for (int n = 0; n < 2; ++n) _Pragma("unroll") for (int k = 0; k < 2; ++k) dst[n][k] = *(const PG8_LAS bf16x8*)(lds + PG8_SB(b, h) + boff + n * 2048 + k * 1024); } while (0)
; #define PG8_MMA(ai, bj, At, Bt) do { __builtin_amdgcn_s_setprio(1); _Pragma("unroll") for (int m = 0; m < 4; ++m) _Pragma("unroll") for (int n = 0; n < 2; ++n) _Pragma("unroll") for (int k = 0; k < 2; ++k) \
;         acc[ai][bj][m][n] = __builtin_amdgcn_mfma_f32_16x16x32_bf16(Bt[n][k], At[m][k], acc[ai][bj][m][n], 0, 0, 0); __builtin_amdgcn_s_setprio(0); } while (0)
; #define PG8_WAIT_V(n) asm volatile("s_waitcnt vmcnt(" #n ")" ::: "memory")
; #define PG8_WAIT_L(n) asm volatile("s_waitcnt lgkmcnt(" #n ")" ::: "memory")
; #define PG8_BAR __builtin_amdgcn_s_barrier()
; #define PG8_SCHED __builtin_amdgcn_sched_barrier(0)
; template <class Epi, class Sched, bool ALIGN_EPI = false, bool SP2 = false>
; __device__ __forceinline__ void gemm_phase(PG8_LAS unsigned char* lds, const Gemm g, const Sched& S, const Epi& E) {
;     ...
;             PG8_WAIT_V(8); PG8_WAIT_L(0); PG8_BAR; PG8_MMA(1, 0, At, B0); PG8_MMA(1, 1, At, B1); PG8_BAR; PG8_SCHED;
;             PG8_LDB(B0, 1, 0); PG8_LDB(B1, 1, 1); PG8_SCHED; PG8_LDA(At, 1, 0); PG8_STAGE(PG8_SA(0, 1), a2 + hstep, voffA);
;             PG8_WAIT_V(8); PG8_WAIT_L(0); PG8_BAR; PG8_MMA(0, 0, At, B0); PG8_MMA(0, 1, At, B1); PG8_BAR; PG8_SCHED;
	s_setprio 0
	s_waitcnt lgkmcnt(0)
	v_mfma_f32_16x16x32_bf16 v[60:63], v[140:143], v[174:177], v[60:63]
	v_mfma_f32_16x16x32_bf16 v[56:59], v[150:153], v[174:177], v[56:59]
	v_mfma_f32_16x16x32_bf16 v[44:47], v[140:143], v[182:185], v[44:47]
	v_mfma_f32_16x16x32_bf16 v[40:43], v[150:153], v[182:185], v[40:43]
	v_mfma_f32_16x16x32_bf16 v[28:31], v[140:143], v[200:203], v[28:31]
	v_mfma_f32_16x16x32_bf16 v[24:27], v[150:153], v[200:203], v[24:27]
	v_mfma_f32_16x16x32_bf16 v[12:15], v[140:143], v[208:211], v[12:15]
	v_mfma_f32_16x16x32_bf16 v[8:11], v[150:153], v[208:211], v[8:11]
	v_mfma_f32_16x16x32_bf16 v[60:63], v[144:147], v[178:181], v[60:63]
	v_mfma_f32_16x16x32_bf16 v[56:59], v[154:157], v[178:181], v[56:59]
	v_mfma_f32_16x16x32_bf16 v[44:47], v[144:147], v[186:189], v[44:47]
	v_mfma_f32_16x16x32_bf16 v[40:43], v[154:157], v[186:189], v[40:43]
	v_mfma_f32_16x16x32_bf16 v[28:31], v[144:147], v[204:207], v[28:31]
	v_mfma_f32_16x16x32_bf16 v[24:27], v[154:157], v[204:207], v[24:27]
	v_mfma_f32_16x16x32_bf16 v[12:15], v[144:147], v[212:215], v[12:15]
	v_mfma_f32_16x16x32_bf16 v[8:11], v[154:157], v[212:215], v[8:11]
	s_setprio 1
	s_setprio 0
	v_mfma_f32_16x16x32_bf16 v[52:55], v[158:161], v[174:177], v[52:55]
	v_mfma_f32_16x16x32_bf16 v[48:51], v[166:169], v[174:177], v[48:51]
	v_mfma_f32_16x16x32_bf16 v[36:39], v[158:161], v[182:185], v[36:39]
	v_mfma_f32_16x16x32_bf16 v[32:35], v[166:169], v[182:185], v[32:35]
	v_mfma_f32_16x16x32_bf16 v[20:23], v[158:161], v[200:203], v[20:23]
	v_mfma_f32_16x16x32_bf16 v[16:19], v[166:169], v[200:203], v[16:19]
	v_mfma_f32_16x16x32_bf16 v[4:7], v[158:161], v[208:211], v[4:7]
	v_mfma_f32_16x16x32_bf16 v[0:3], v[166:169], v[208:211], v[0:3]
	v_mfma_f32_16x16x32_bf16 v[52:55], v[162:165], v[178:181], v[52:55]
	v_mfma_f32_16x16x32_bf16 v[48:51], v[170:173], v[178:181], v[48:51]
	v_mfma_f32_16x16x32_bf16 v[36:39], v[162:165], v[186:189], v[36:39]
	v_mfma_f32_16x16x32_bf16 v[32:35], v[170:173], v[186:189], v[32:35]
	v_mfma_f32_16x16x32_bf16 v[20:23], v[162:165], v[204:207], v[20:23]
	v_mfma_f32_16x16x32_bf16 v[16:19], v[170:173], v[204:207], v[16:19]
	v_mfma_f32_16x16x32_bf16 v[4:7], v[162:165], v[212:215], v[4:7]
	v_mfma_f32_16x16x32_bf16 v[0:3], v[170:173], v[212:215], v[0:3]
	s_setprio 1
	s_barrier
	s_add_i32 s50, 0, 0x18000
	s_add_i32 s51, 0, 0x1c000
	v_add_u32_e32 v154, s50, v192
	v_add_u32_e32 v170, s51, v192
	ds_read_b128 v[140:143], v154
	ds_read_b128 v[144:147], v154 offset:1024
	ds_read_b128 v[150:153], v154 offset:2048
	ds_read_b128 v[154:157], v154 offset:3072
	ds_read_b128 v[158:161], v170
	ds_read_b128 v[162:165], v170 offset:1024
	ds_read_b128 v[166:169], v170 offset:2048
	ds_read_b128 v[170:173], v170 offset:3072
	s_add_u32 s24, s24, 0xb0000
	s_addc_u32 s25, s25, 0
	s_mov_b32 m0, s29
	v_lshl_add_u64 v[222:223], s[24:25], 0, v[128:129]
	ds_read_b128 v[174:177], v196 offset:32768
	ds_read_b128 v[178:181], v196 offset:33792
	ds_read_b128 v[182:185], v196 offset:34816
	ds_read_b128 v[186:189], v196 offset:35840
	ds_read_b128 v[200:203], v196 offset:36864
	ds_read_b128 v[204:207], v196 offset:37888
	ds_read_b128 v[208:211], v196 offset:38912
	ds_read_b128 v[212:215], v196 offset:39936
	global_load_lds_dwordx4 v[222:223], off
	v_lshl_add_u64 v[222:223], s[24:25], 0, v[130:131]
	s_mov_b32 m0, s30
	s_nop 0
	global_load_lds_dwordx4 v[222:223], off
	s_waitcnt vmcnt(8)
	s_waitcnt lgkmcnt(0)
	s_barrier
	s_setprio 0
	s_waitcnt lgkmcnt(0)
	v_mfma_f32_16x16x32_bf16 v[124:127], v[140:143], v[174:177], v[124:127]
	v_mfma_f32_16x16x32_bf16 v[120:123], v[150:153], v[174:177], v[120:123]
	v_mfma_f32_16x16x32_bf16 v[108:111], v[140:143], v[182:185], v[108:111]
	v_mfma_f32_16x16x32_bf16 v[104:107], v[150:153], v[182:185], v[104:107]
	v_mfma_f32_16x16x32_bf16 v[92:95], v[140:143], v[200:203], v[92:95]
	v_mfma_f32_16x16x32_bf16 v[88:91], v[150:153], v[200:203], v[88:91]
	v_mfma_f32_16x16x32_bf16 v[76:79], v[140:143], v[208:211], v[76:79]
	v_mfma_f32_16x16x32_bf16 v[72:75], v[150:153], v[208:211], v[72:75]
	v_mfma_f32_16x16x32_bf16 v[124:127], v[144:147], v[178:181], v[124:127]
	v_mfma_f32_16x16x32_bf16 v[120:123], v[154:157], v[178:181], v[120:123]
	v_mfma_f32_16x16x32_bf16 v[108:111], v[144:147], v[186:189], v[108:111]
	v_mfma_f32_16x16x32_bf16 v[104:107], v[154:157], v[186:189], v[104:107]
	v_mfma_f32_16x16x32_bf16 v[92:95], v[144:147], v[204:207], v[92:95]
	v_mfma_f32_16x16x32_bf16 v[88:91], v[154:157], v[204:207], v[88:91]
	v_mfma_f32_16x16x32_bf16 v[76:79], v[144:147], v[212:215], v[76:79]
	v_mfma_f32_16x16x32_bf16 v[72:75], v[154:157], v[212:215], v[72:75]
	s_setprio 1
	s_setprio 0
	v_mfma_f32_16x16x32_bf16 v[116:119], v[158:161], v[174:177], v[116:119]
	v_mfma_f32_16x16x32_bf16 v[112:115], v[166:169], v[174:177], v[112:115]
	v_mfma_f32_16x16x32_bf16 v[100:103], v[158:161], v[182:185], v[100:103]
	v_mfma_f32_16x16x32_bf16 v[96:99], v[166:169], v[182:185], v[96:99]
	v_mfma_f32_16x16x32_bf16 v[84:87], v[158:161], v[200:203], v[84:87]
	v_mfma_f32_16x16x32_bf16 v[80:83], v[166:169], v[200:203], v[80:83]
	v_mfma_f32_16x16x32_bf16 v[68:71], v[158:161], v[208:211], v[68:71]
	v_mfma_f32_16x16x32_bf16 v[64:67], v[166:169], v[208:211], v[64:67]
	v_mfma_f32_16x16x32_bf16 v[116:119], v[162:165], v[178:181], v[116:119]
	v_mfma_f32_16x16x32_bf16 v[112:115], v[170:173], v[178:181], v[112:115]
	v_mfma_f32_16x16x32_bf16 v[100:103], v[162:165], v[186:189], v[100:103]
	v_mfma_f32_16x16x32_bf16 v[96:99], v[170:173], v[186:189], v[96:99]
	v_mfma_f32_16x16x32_bf16 v[84:87], v[162:165], v[204:207], v[84:87]
	v_mfma_f32_16x16x32_bf16 v[80:83], v[170:173], v[204:207], v[80:83]
	v_mfma_f32_16x16x32_bf16 v[68:71], v[162:165], v[212:215], v[68:71]
	v_mfma_f32_16x16x32_bf16 v[64:67], v[170:173], v[212:215], v[64:67]
	s_setprio 1
	s_barrier
; #define PG8_STAGE(bufoff, gbase, voff) do { _Pragma("unroll") for (int _i = 0; _i < 2; ++_i) \
;         __builtin_amdgcn_global_load_lds((const unsigned*)((const char*)(gbase) + (voff)[_i]), (PG8_LAS unsigned*)(lds + (bufoff) + ldsw + _i * 8192), 16, 0, 0); } while (0)
; #define PG8_LDA(dst, b, h) do { _Pragma("unroll") for (int m = 0; m < 4; ++m) _Pragma("unroll") for (int k = 0; k < 2; ++k) dst[m][k] = *(const PG8_LAS bf16x8*)(lds + PG8_SA(b, h) + aoff + m * 2048 + k * 1024); } while (0)
; #define PG8_MMA(ai, bj, At, Bt) do { __builtin_amdgcn_s_setprio(1); _Pragma("unroll") for (int m = 0; m < 4; ++m) _Pragma("unroll") for (int n = 0; n < 2; ++n) _Pragma("unroll") for (int k = 0; k < 2; ++k) \
;         acc[ai][bj][m][n] = __builtin_amdgcn_mfma_f32_16x16x32_bf16(Bt[n][k], At[m][k], acc[ai][bj][m][n], 0, 0, 0); __builtin_amdgcn_s_setprio(0); } while (0)
; #define PG8_WAIT_V(n) asm volatile("s_waitcnt vmcnt(" #n ")" ::: "memory")
; #define PG8_WAIT_L(n) asm volatile("s_waitcnt lgkmcnt(" #n ")" ::: "memory")
; #define PG8_BAR __builtin_amdgcn_s_barrier()
; #define PG8_SCHED __builtin_amdgcn_sched_barrier(0)
; template <class Epi, class Sched, bool ALIGN_EPI = false, bool SP2 = false>
; __device__ __forceinline__ void gemm_phase(PG8_LAS unsigned char* lds, const Gemm g, const Sched& S, const Epi& E) {
;     ...
;         for (int t = 0; t < nt; t += 2) {
;             const bool last = (t == nt - 2);
;     ...
;             PG8_LDA(At, 1, 1); PG8_STAGE(PG8_SB(1, 0), b3, voffB); PG8_STAGE(PG8_SB(1, 1), b3 + hstep, voffB); PG8_STAGE(PG8_SA(1, 0), a3, voffA);
;             PG8_WAIT_V(8); PG8_WAIT_L(0); PG8_BAR; PG8_MMA(1, 0, At, B0); PG8_MMA(1, 1, At, B1); PG8_BAR; PG8_SCHED;
	s_add_i32 s24, s50, s26
	v_lshl_add_u64 v[190:191], v[190:191], 0, s[14:15]
	s_mov_b32 m0, s24
	ds_read_b128 v[174:177], v196 offset:49152
	ds_read_b128 v[178:181], v196 offset:50176
	ds_read_b128 v[182:185], v196 offset:51200
	ds_read_b128 v[186:189], v196 offset:52224
	ds_read_b128 v[200:203], v196 offset:53248
	ds_read_b128 v[204:207], v196 offset:54272
	ds_read_b128 v[208:211], v196 offset:55296
	ds_read_b128 v[212:215], v196 offset:56320
	global_load_lds_dwordx4 v[190:191], off
	s_add_i32 m0, s24, 0x2000
	s_add_u32 s22, s22, 0xb0080
	v_lshl_add_u64 v[190:191], v[216:217], 0, s[14:15]
	s_addc_u32 s23, s23, 0
	s_add_i32 s24, s51, s26
	global_load_lds_dwordx4 v[190:191], off
	v_lshl_add_u64 v[190:191], s[22:23], 0, v[128:129]
	s_mov_b32 m0, s24
	s_nop 0
	global_load_lds_dwordx4 v[190:191], off
	v_lshl_add_u64 v[190:191], s[22:23], 0, v[130:131]
	s_add_i32 m0, s24, 0x2000
	s_nop 0
	global_load_lds_dwordx4 v[190:191], off
	v_lshl_add_u64 v[190:191], v[218:219], 0, s[14:15]
	s_mov_b32 m0, s34
	s_nop 0
	global_load_lds_dwordx4 v[190:191], off
	v_lshl_add_u64 v[190:191], v[220:221], 0, s[14:15]
	s_mov_b32 m0, s35
	s_nop 0
	global_load_lds_dwordx4 v[190:191], off
	s_waitcnt vmcnt(8)
	s_waitcnt lgkmcnt(0)
	s_barrier
	s_setprio 0
	s_waitcnt lgkmcnt(0)
	v_mfma_f32_16x16x32_bf16 v[60:63], v[140:143], v[174:177], v[60:63]
	v_mfma_f32_16x16x32_bf16 v[56:59], v[150:153], v[174:177], v[56:59]
	v_mfma_f32_16x16x32_bf16 v[44:47], v[140:143], v[182:185], v[44:47]
	v_mfma_f32_16x16x32_bf16 v[40:43], v[150:153], v[182:185], v[40:43]
	v_mfma_f32_16x16x32_bf16 v[28:31], v[140:143], v[200:203], v[28:31]
	v_mfma_f32_16x16x32_bf16 v[24:27], v[150:153], v[200:203], v[24:27]
	v_mfma_f32_16x16x32_bf16 v[12:15], v[140:143], v[208:211], v[12:15]
	v_mfma_f32_16x16x32_bf16 v[8:11], v[150:153], v[208:211], v[8:11]
	v_mfma_f32_16x16x32_bf16 v[60:63], v[144:147], v[178:181], v[60:63]
	v_mfma_f32_16x16x32_bf16 v[56:59], v[154:157], v[178:181], v[56:59]
	v_mfma_f32_16x16x32_bf16 v[44:47], v[144:147], v[186:189], v[44:47]
	v_mfma_f32_16x16x32_bf16 v[40:43], v[154:157], v[186:189], v[40:43]
	v_mfma_f32_16x16x32_bf16 v[28:31], v[144:147], v[204:207], v[28:31]
	v_mfma_f32_16x16x32_bf16 v[24:27], v[154:157], v[204:207], v[24:27]
	v_mfma_f32_16x16x32_bf16 v[12:15], v[144:147], v[212:215], v[12:15]
	v_mfma_f32_16x16x32_bf16 v[8:11], v[154:157], v[212:215], v[8:11]
	s_setprio 1
	s_setprio 0
	v_mfma_f32_16x16x32_bf16 v[52:55], v[158:161], v[174:177], v[52:55]
	v_mfma_f32_16x16x32_bf16 v[48:51], v[166:169], v[174:177], v[48:51]
	v_mfma_f32_16x16x32_bf16 v[36:39], v[158:161], v[182:185], v[36:39]
	v_mfma_f32_16x16x32_bf16 v[32:35], v[166:169], v[182:185], v[32:35]
	v_mfma_f32_16x16x32_bf16 v[20:23], v[158:161], v[200:203], v[20:23]
	v_mfma_f32_16x16x32_bf16 v[16:19], v[166:169], v[200:203], v[16:19]
	v_mfma_f32_16x16x32_bf16 v[4:7], v[158:161], v[208:211], v[4:7]
	v_mfma_f32_16x16x32_bf16 v[0:3], v[166:169], v[208:211], v[0:3]
	v_mfma_f32_16x16x32_bf16 v[52:55], v[162:165], v[178:181], v[52:55]
	v_mfma_f32_16x16x32_bf16 v[48:51], v[170:173], v[178:181], v[48:51]
	v_mfma_f32_16x16x32_bf16 v[36:39], v[162:165], v[186:189], v[36:39]
	v_mfma_f32_16x16x32_bf16 v[32:35], v[170:173], v[186:189], v[32:35]
	v_mfma_f32_16x16x32_bf16 v[20:23], v[162:165], v[204:207], v[20:23]
	v_mfma_f32_16x16x32_bf16 v[16:19], v[170:173], v[204:207], v[16:19]
	v_mfma_f32_16x16x32_bf16 v[4:7], v[162:165], v[212:215], v[4:7]
	v_mfma_f32_16x16x32_bf16 v[0:3], v[170:173], v[212:215], v[0:3]
	s_setprio 1
	s_barrier
	s_add_i32 s47, s47, 2
	s_add_u32 s20, s20, 0x100
	s_addc_u32 s21, s21, 0
	s_add_u32 s45, s45, 0x100
	s_addc_u32 s46, s46, 0
	s_cmp_gt_u32 s47, 41
	s_cbranch_scc0 .LBB0_1751
	s_and_b64 vcc, exec, s[16:17]
	s_cbranch_vccz .LBB0_1754
	s_barrier
